# GEMM load-segment tails: the two asm waits (vmcnt(N), lgkmcnt(0)) before each segment barrier merged into one s_waitcnt (52 sites)
# baseline (speedup 1.0000x reference)
;     __device__ bool next(int i, Unit& u) const { if (!b.next(i >> 1, u)) return false; u.half = i & 1; u.koff = (i & 1) * kbytes; return true; }
; #define PG8_STAGE(bufoff, gbase, voff) do { _Pragma("unroll") for (int _i = 0; _i < 2; ++_i) \
;         __builtin_amdgcn_global_load_lds((const unsigned*)((const char*)(gbase) + (voff)[_i]), (LAS unsigned*)(lds + (bufoff) + ldsw + _i * 8192), 16, 0, 0); } while (0)
; #define PG8_LDA(dst, b, h) do { _Pragma("unroll") for (int m = 0; m < 4; ++m) _Pragma("unroll") for (int k = 0; k < 2; ++k) dst[m][k] = *(const LAS bf16x8*)(lds + PG8_SA(b, h) + aoff + m * 2048 + k * 1024); } while (0)
; #define PG8_LDB(dst, b, h) do { _Pragma("unroll") for (int n = 0; n < 2; ++n) _Pragma("unroll") for (int k = 0; k < 2; ++k) dst[n][k] = *(const LAS bf16x8*)(lds + PG8_SB(b, h) + boff + n * 2048 + k * 1024); } while (0)
; #define PG8_WAIT_V(n) asm volatile("s_waitcnt vmcnt(" #n ")" ::: "memory")
; #define PG8_WAIT_L(n) asm volatile("s_waitcnt lgkmcnt(" #n ")" ::: "memory")
; #define PG8_BAR __builtin_amdgcn_s_barrier()
; #define PG8_SCHED __builtin_amdgcn_sched_barrier(0)
; template <class Epi, class Sched>
; __device__ __forceinline__ void gemm_phase(LAS unsigned char* lds, const Gemm g, const Sched& S, const Epi& E, int tid_in) {
;     ...
;         const bool has_next = S.next(ui + 1, nxt);
;         const char* nA = has_next ? (const char*)g.A + (size_t)nxt.pm * tstep + nxt.koff : cA; const char* nB = has_next ? (const char*)g.Bt + (size_t)nxt.pn * tstep + nxt.koff : cB;
;         for (int t = 0; t < nt; t += 2) {
;             const bool last = (t == nt - 2);
;             const char* a1 = cA + (size_t)(t + 1) * kstep;
;             const char* a2 = last ? nA : cA + (size_t)(t + 2) * kstep; const char* b2 = last ? nB : cB + (size_t)(t + 2) * kstep;
;             const char* a3 = a2 + kstep; const char* b3 = b2 + kstep;
;             PG8_LDB(B0, 0, 0); PG8_LDB(B1, 0, 1); PG8_SCHED; PG8_LDA(At, 0, 0); PG8_STAGE(PG8_SA(1, 0), a1, voffA); PG8_STAGE(PG8_SA(1, 1), a1 + hstep, voffA);
;             PG8_WAIT_V(8); PG8_WAIT_L(0); PG8_BAR; PG8_MMA(0, 0, At, B0); PG8_MMA(0, 1, At, B1); PG8_BAR; PG8_SCHED;
;             PG8_LDA(At, 0, 1); PG8_STAGE(PG8_SB(0, 0), b2, voffB); PG8_STAGE(PG8_SB(0, 1), b2 + hstep, voffB);
;             PG8_WAIT_V(6); PG8_WAIT_L(0); PG8_BAR; PG8_MMA(1, 0, At, B0); PG8_MMA(1, 1, At, B1); PG8_BAR; PG8_SCHED;
.LBB0_101:
	s_ashr_i32 s31, s30, 31
	s_lshl_b64 s[34:35], s[30:31], 20
	s_add_u32 s34, s58, s34
	s_addc_u32 s35, s59, s35
	s_and_b64 s[36:37], s[0:1], exec
	s_cselect_b32 s31, s35, s43
	s_cselect_b32 s39, s34, s42
	s_ashr_i32 s29, s28, 31
	s_lshl_b64 s[36:37], s[28:29], 20
	s_add_u32 s36, s56, s36
	s_addc_u32 s37, s57, s37
	s_and_b64 s[46:47], s[0:1], exec
	s_cselect_b32 s29, s37, s45
	s_cselect_b32 s41, s36, s44
	s_add_u32 s94, s44, 0x100
	s_addc_u32 s95, s45, 0
	s_mov_b32 s96, -2
	s_mov_b64 s[44:45], 0
	v_lshl_add_u64 v[128:129], s[42:43], 0, v[158:159]
	v_lshl_add_u64 v[130:131], s[42:43], 0, v[160:161]
	ds_read_b128 v[132:135], v179
	ds_read_b128 v[136:139], v179 offset:1024
	ds_read_b128 v[140:143], v179 offset:2048
	ds_read_b128 v[172:175], v179 offset:3072
	ds_read_b128 v[188:191], v180
	ds_read_b128 v[192:195], v180 offset:1024
	ds_read_b128 v[196:199], v180 offset:2048
	ds_read_b128 v[200:203], v180 offset:3072
	s_add_u32 s46, s42, s44
	s_addc_u32 s47, s43, s45
	s_add_u32 s48, s46, 0x100
	s_addc_u32 s49, s47, 0
	s_add_u32 s46, s94, s44
	s_addc_u32 s47, s95, s45
	s_cmpk_eq_i32 s44, 0xf00
	s_cselect_b32 s47, s29, s47
	s_cselect_b32 s46, s41, s46
	s_cselect_b32 s49, s31, s49
	s_cselect_b32 s48, s39, s48
	v_lshl_add_u64 v[168:169], v[130:131], 0, s[44:45]
	v_lshl_add_u64 v[176:177], v[168:169], 0, s[10:11]
	s_add_i32 m0, s60, 0x8000
	ds_read_b128 v[204:207], v181
	ds_read_b128 v[208:211], v181 offset:1024
	ds_read_b128 v[212:215], v181 offset:2048
	ds_read_b128 v[216:219], v181 offset:3072
	ds_read_b128 v[220:223], v181 offset:4096
	ds_read_b128 v[224:227], v181 offset:5120
	ds_read_b128 v[228:231], v181 offset:6144
	ds_read_b128 v[232:235], v181 offset:7168
	global_load_lds_dwordx4 v[176:177], off
	v_lshl_add_u64 v[176:177], v[128:129], 0, s[44:45]
	v_lshl_add_u64 v[184:185], v[176:177], 0, s[10:11]
	s_add_i32 m0, s60, 0xa000
	v_lshl_add_u64 v[168:169], v[168:169], 0, s[12:13]
	global_load_lds_dwordx4 v[184:185], off
	s_add_i32 m0, s60, 0xc000
	s_nop 0
	global_load_lds_dwordx4 v[168:169], off
	v_lshl_add_u64 v[168:169], v[176:177], 0, s[12:13]
	s_add_i32 m0, s60, 0xe000
	s_nop 0
	global_load_lds_dwordx4 v[168:169], off
	s_waitcnt vmcnt(8) lgkmcnt(0)
	s_barrier
	s_setprio 3
	v_mfma_f32_16x16x32_bf16 v[124:127], v[132:135], v[204:207], 0
	v_mfma_f32_16x16x32_bf16 v[120:123], v[140:143], v[204:207], 0
	v_mfma_f32_16x16x32_bf16 v[108:111], v[132:135], v[212:215], 0
	v_mfma_f32_16x16x32_bf16 v[104:107], v[140:143], v[212:215], 0
	v_mfma_f32_16x16x32_bf16 v[92:95], v[132:135], v[220:223], 0
	v_mfma_f32_16x16x32_bf16 v[88:91], v[140:143], v[220:223], 0
	v_mfma_f32_16x16x32_bf16 v[76:79], v[132:135], v[228:231], 0
	v_mfma_f32_16x16x32_bf16 v[72:75], v[140:143], v[228:231], 0
	v_mfma_f32_16x16x32_bf16 v[124:127], v[136:139], v[208:211], v[124:127]
	v_mfma_f32_16x16x32_bf16 v[120:123], v[172:175], v[208:211], v[120:123]
	v_mfma_f32_16x16x32_bf16 v[108:111], v[136:139], v[216:219], v[108:111]
	v_mfma_f32_16x16x32_bf16 v[104:107], v[172:175], v[216:219], v[104:107]
	v_mfma_f32_16x16x32_bf16 v[92:95], v[136:139], v[224:227], v[92:95]
	v_mfma_f32_16x16x32_bf16 v[88:91], v[172:175], v[224:227], v[88:91]
	v_mfma_f32_16x16x32_bf16 v[76:79], v[136:139], v[232:235], v[76:79]
	v_mfma_f32_16x16x32_bf16 v[72:75], v[172:175], v[232:235], v[72:75]
	s_setprio 0
	s_setprio 3
	v_mfma_f32_16x16x32_bf16 v[116:119], v[188:191], v[204:207], 0
	v_mfma_f32_16x16x32_bf16 v[112:115], v[196:199], v[204:207], 0
	v_mfma_f32_16x16x32_bf16 v[100:103], v[188:191], v[212:215], 0
	v_mfma_f32_16x16x32_bf16 v[96:99], v[196:199], v[212:215], 0
	v_mfma_f32_16x16x32_bf16 v[84:87], v[188:191], v[220:223], 0
	v_mfma_f32_16x16x32_bf16 v[80:83], v[196:199], v[220:223], 0
	v_mfma_f32_16x16x32_bf16 v[68:71], v[188:191], v[228:231], 0
	v_mfma_f32_16x16x32_bf16 v[64:67], v[196:199], v[228:231], 0
	v_mfma_f32_16x16x32_bf16 v[116:119], v[192:195], v[208:211], v[116:119]
	v_mfma_f32_16x16x32_bf16 v[112:115], v[200:203], v[208:211], v[112:115]
	v_mfma_f32_16x16x32_bf16 v[100:103], v[192:195], v[216:219], v[100:103]
	v_mfma_f32_16x16x32_bf16 v[96:99], v[200:203], v[216:219], v[96:99]
	v_mfma_f32_16x16x32_bf16 v[84:87], v[192:195], v[224:227], v[84:87]
	v_mfma_f32_16x16x32_bf16 v[80:83], v[200:203], v[224:227], v[80:83]
	v_mfma_f32_16x16x32_bf16 v[68:71], v[192:195], v[232:235], v[68:71]
	v_mfma_f32_16x16x32_bf16 v[64:67], v[200:203], v[232:235], v[64:67]
	s_setprio 0
	s_barrier
	s_add_i32 s97, s66, s2
	v_lshl_add_u64 v[168:169], s[46:47], 0, v[148:149]
	s_mov_b32 m0, s97
	ds_read_b128 v[204:207], v181 offset:16384
	ds_read_b128 v[208:211], v181 offset:17408
	ds_read_b128 v[212:215], v181 offset:18432
	ds_read_b128 v[216:219], v181 offset:19456
	ds_read_b128 v[220:223], v181 offset:20480
	ds_read_b128 v[224:227], v181 offset:21504
	ds_read_b128 v[228:231], v181 offset:22528
	ds_read_b128 v[232:235], v181 offset:23552
	global_load_lds_dwordx4 v[168:169], off
	s_add_i32 m0, s97, 0x2000
	s_add_u32 vcc_lo, s46, 0x80000
	v_lshl_add_u64 v[176:177], s[46:47], 0, v[144:145]
	s_addc_u32 vcc_hi, s47, 0
	s_add_i32 s97, s67, s2
	global_load_lds_dwordx4 v[176:177], off
	v_lshl_add_u64 v[184:185], vcc, 0, v[148:149]
	s_mov_b32 m0, s97
	s_nop 0
	global_load_lds_dwordx4 v[184:185], off
	v_lshl_add_u64 v[184:185], vcc, 0, v[144:145]
	s_add_i32 m0, s97, 0x2000
	s_nop 0
	global_load_lds_dwordx4 v[184:185], off
	s_waitcnt vmcnt(6) lgkmcnt(0)
	s_barrier
; #define PG8_STAGE(bufoff, gbase, voff) do { _Pragma("unroll") for (int _i = 0; _i < 2; ++_i) \
;         __builtin_amdgcn_global_load_lds((const unsigned*)((const char*)(gbase) + (voff)[_i]), (LAS unsigned*)(lds + (bufoff) + ldsw + _i * 8192), 16, 0, 0); } while (0)
; #define PG8_LDA(dst, b, h) do { _Pragma("unroll") for (int m = 0; m < 4; ++m) _Pragma("unroll") for (int k = 0; k < 2; ++k) dst[m][k] = *(const LAS bf16x8*)(lds + PG8_SA(b, h) + aoff + m * 2048 + k * 1024); } while (0)
; #define PG8_LDB(dst, b, h) do { _Pragma("unroll") for (int n = 0; n < 2; ++n) _Pragma("unroll") for (int k = 0; k < 2; ++k) dst[n][k] = *(const LAS bf16x8*)(lds + PG8_SB(b, h) + boff + n * 2048 + k * 1024); } while (0)
; #define PG8_MMA(ai, bj, At, Bt) do { __builtin_amdgcn_s_setprio(3); _Pragma("unroll") for (int m = 0; m < 4; ++m) _Pragma("unroll") for (int n = 0; n < 2; ++n) _Pragma("unroll") for (int k = 0; k < 2; ++k) \
;         acc[ai][bj][m][n] = __builtin_amdgcn_mfma_f32_16x16x32_bf16(Bt[n][k], At[m][k], acc[ai][bj][m][n], 0, 0, 0); __builtin_amdgcn_s_setprio(0); } while (0)
; #define PG8_WAIT_V(n) asm volatile("s_waitcnt vmcnt(" #n ")" ::: "memory")
; #define PG8_WAIT_L(n) asm volatile("s_waitcnt lgkmcnt(" #n ")" ::: "memory")
; #define PG8_BAR __builtin_amdgcn_s_barrier()
; #define PG8_SCHED __builtin_amdgcn_sched_barrier(0)
; template <class Epi, class Sched>
; __device__ __forceinline__ void gemm_phase(LAS unsigned char* lds, const Gemm g, const Sched& S, const Epi& E, int tid_in) {
;     ...
;             PG8_WAIT_V(6); PG8_WAIT_L(0); PG8_BAR; PG8_MMA(1, 0, At, B0); PG8_MMA(1, 1, At, B1); PG8_BAR; PG8_SCHED;
;             PG8_LDB(B0, 1, 0); PG8_LDB(B1, 1, 1); PG8_SCHED; PG8_LDA(At, 1, 0); PG8_STAGE(PG8_SA(0, 0), a2, voffA); PG8_STAGE(PG8_SA(0, 1), a2 + hstep, voffA);
;             PG8_WAIT_V(8); PG8_WAIT_L(0); PG8_BAR; PG8_MMA(0, 0, At, B0); PG8_MMA(0, 1, At, B1); PG8_BAR; PG8_SCHED;
	s_setprio 3
	v_mfma_f32_16x16x32_bf16 v[60:63], v[132:135], v[204:207], 0
	v_mfma_f32_16x16x32_bf16 v[56:59], v[140:143], v[204:207], 0
	v_mfma_f32_16x16x32_bf16 v[44:47], v[132:135], v[212:215], 0
	v_mfma_f32_16x16x32_bf16 v[40:43], v[140:143], v[212:215], 0
	v_mfma_f32_16x16x32_bf16 v[28:31], v[132:135], v[220:223], 0
	v_mfma_f32_16x16x32_bf16 v[24:27], v[140:143], v[220:223], 0
	v_mfma_f32_16x16x32_bf16 v[12:15], v[132:135], v[228:231], 0
	v_mfma_f32_16x16x32_bf16 v[8:11], v[140:143], v[228:231], 0
	v_mfma_f32_16x16x32_bf16 v[60:63], v[136:139], v[208:211], v[60:63]
	v_mfma_f32_16x16x32_bf16 v[56:59], v[172:175], v[208:211], v[56:59]
	v_mfma_f32_16x16x32_bf16 v[44:47], v[136:139], v[216:219], v[44:47]
	v_mfma_f32_16x16x32_bf16 v[40:43], v[172:175], v[216:219], v[40:43]
	v_mfma_f32_16x16x32_bf16 v[28:31], v[136:139], v[224:227], v[28:31]
	v_mfma_f32_16x16x32_bf16 v[24:27], v[172:175], v[224:227], v[24:27]
	v_mfma_f32_16x16x32_bf16 v[12:15], v[136:139], v[232:235], v[12:15]
	v_mfma_f32_16x16x32_bf16 v[8:11], v[172:175], v[232:235], v[8:11]
	s_setprio 0
	s_setprio 3
	v_mfma_f32_16x16x32_bf16 v[52:55], v[188:191], v[204:207], 0
	v_mfma_f32_16x16x32_bf16 v[48:51], v[196:199], v[204:207], 0
	v_mfma_f32_16x16x32_bf16 v[36:39], v[188:191], v[212:215], 0
	v_mfma_f32_16x16x32_bf16 v[32:35], v[196:199], v[212:215], 0
	v_mfma_f32_16x16x32_bf16 v[20:23], v[188:191], v[220:223], 0
	v_mfma_f32_16x16x32_bf16 v[16:19], v[196:199], v[220:223], 0
	v_mfma_f32_16x16x32_bf16 v[4:7], v[188:191], v[228:231], 0
	v_mfma_f32_16x16x32_bf16 v[0:3], v[196:199], v[228:231], 0
	v_mfma_f32_16x16x32_bf16 v[52:55], v[192:195], v[208:211], v[52:55]
	v_mfma_f32_16x16x32_bf16 v[48:51], v[200:203], v[208:211], v[48:51]
	v_mfma_f32_16x16x32_bf16 v[36:39], v[192:195], v[216:219], v[36:39]
	v_mfma_f32_16x16x32_bf16 v[32:35], v[200:203], v[216:219], v[32:35]
	v_mfma_f32_16x16x32_bf16 v[20:23], v[192:195], v[224:227], v[20:23]
	v_mfma_f32_16x16x32_bf16 v[16:19], v[200:203], v[224:227], v[16:19]
	v_mfma_f32_16x16x32_bf16 v[4:7], v[192:195], v[232:235], v[4:7]
	v_mfma_f32_16x16x32_bf16 v[0:3], v[200:203], v[232:235], v[0:3]
	s_setprio 0
	s_barrier
	s_add_i32 s97, 0, 0x18000
	v_add_u32_e32 v152, s97, v171
	s_add_i32 vcc_lo, 0, 0x1c000
	ds_read_b128 v[132:135], v152
	ds_read_b128 v[136:139], v152 offset:1024
	ds_read_b128 v[140:143], v152 offset:2048
	ds_read_b128 v[172:175], v152 offset:3072
	v_add_u32_e32 v152, vcc_lo, v171
	ds_read_b128 v[188:191], v152
	ds_read_b128 v[192:195], v152 offset:1024
	ds_read_b128 v[196:199], v152 offset:2048
	ds_read_b128 v[200:203], v152 offset:3072
	s_mov_b32 m0, s60
	v_lshl_add_u64 v[184:185], s[48:49], 0, v[150:151]
	ds_read_b128 v[204:207], v181 offset:32768
	ds_read_b128 v[208:211], v181 offset:33792
	ds_read_b128 v[212:215], v181 offset:34816
	ds_read_b128 v[216:219], v181 offset:35840
	ds_read_b128 v[220:223], v181 offset:36864
	ds_read_b128 v[224:227], v181 offset:37888
	ds_read_b128 v[228:231], v181 offset:38912
	ds_read_b128 v[232:235], v181 offset:39936
	global_load_lds_dwordx4 v[184:185], off
	v_lshl_add_u64 v[184:185], s[48:49], 0, v[146:147]
	s_add_u32 s48, s48, 0x80000
	s_mov_b32 m0, s61
	s_addc_u32 s49, s49, 0
	global_load_lds_dwordx4 v[184:185], off
	v_lshl_add_u64 v[184:185], s[48:49], 0, v[150:151]
	s_mov_b32 m0, s62
	s_nop 0
	global_load_lds_dwordx4 v[184:185], off
	v_lshl_add_u64 v[184:185], s[48:49], 0, v[146:147]
	s_mov_b32 m0, s63
	s_nop 0
	global_load_lds_dwordx4 v[184:185], off
	s_waitcnt vmcnt(8) lgkmcnt(0)
	s_barrier
	s_setprio 3
	v_mfma_f32_16x16x32_bf16 v[124:127], v[132:135], v[204:207], v[124:127]
	v_mfma_f32_16x16x32_bf16 v[120:123], v[140:143], v[204:207], v[120:123]
	v_mfma_f32_16x16x32_bf16 v[108:111], v[132:135], v[212:215], v[108:111]
	v_mfma_f32_16x16x32_bf16 v[104:107], v[140:143], v[212:215], v[104:107]
	v_mfma_f32_16x16x32_bf16 v[92:95], v[132:135], v[220:223], v[92:95]
	v_mfma_f32_16x16x32_bf16 v[88:91], v[140:143], v[220:223], v[88:91]
	v_mfma_f32_16x16x32_bf16 v[76:79], v[132:135], v[228:231], v[76:79]
	v_mfma_f32_16x16x32_bf16 v[72:75], v[140:143], v[228:231], v[72:75]
	v_mfma_f32_16x16x32_bf16 v[124:127], v[136:139], v[208:211], v[124:127]
	v_mfma_f32_16x16x32_bf16 v[120:123], v[172:175], v[208:211], v[120:123]
	v_mfma_f32_16x16x32_bf16 v[108:111], v[136:139], v[216:219], v[108:111]
	v_mfma_f32_16x16x32_bf16 v[104:107], v[172:175], v[216:219], v[104:107]
	v_mfma_f32_16x16x32_bf16 v[92:95], v[136:139], v[224:227], v[92:95]
	v_mfma_f32_16x16x32_bf16 v[88:91], v[172:175], v[224:227], v[88:91]
	v_mfma_f32_16x16x32_bf16 v[76:79], v[136:139], v[232:235], v[76:79]
	v_mfma_f32_16x16x32_bf16 v[72:75], v[172:175], v[232:235], v[72:75]
	s_setprio 0
	s_setprio 3
	v_mfma_f32_16x16x32_bf16 v[116:119], v[188:191], v[204:207], v[116:119]
	v_mfma_f32_16x16x32_bf16 v[112:115], v[196:199], v[204:207], v[112:115]
	v_mfma_f32_16x16x32_bf16 v[100:103], v[188:191], v[212:215], v[100:103]
	v_mfma_f32_16x16x32_bf16 v[96:99], v[196:199], v[212:215], v[96:99]
	v_mfma_f32_16x16x32_bf16 v[84:87], v[188:191], v[220:223], v[84:87]
	v_mfma_f32_16x16x32_bf16 v[80:83], v[196:199], v[220:223], v[80:83]
	v_mfma_f32_16x16x32_bf16 v[68:71], v[188:191], v[228:231], v[68:71]
	v_mfma_f32_16x16x32_bf16 v[64:67], v[196:199], v[228:231], v[64:67]
	v_mfma_f32_16x16x32_bf16 v[116:119], v[192:195], v[208:211], v[116:119]
	v_mfma_f32_16x16x32_bf16 v[112:115], v[200:203], v[208:211], v[112:115]
	v_mfma_f32_16x16x32_bf16 v[100:103], v[192:195], v[216:219], v[100:103]
	v_mfma_f32_16x16x32_bf16 v[96:99], v[200:203], v[216:219], v[96:99]
	v_mfma_f32_16x16x32_bf16 v[84:87], v[192:195], v[224:227], v[84:87]
	v_mfma_f32_16x16x32_bf16 v[80:83], v[200:203], v[224:227], v[80:83]
	v_mfma_f32_16x16x32_bf16 v[68:71], v[192:195], v[232:235], v[68:71]
	v_mfma_f32_16x16x32_bf16 v[64:67], v[200:203], v[232:235], v[64:67]
	s_setprio 0
	s_barrier
; #define PG8_STAGE(bufoff, gbase, voff) do { _Pragma("unroll") for (int _i = 0; _i < 2; ++_i) \
;         __builtin_amdgcn_global_load_lds((const unsigned*)((const char*)(gbase) + (voff)[_i]), (LAS unsigned*)(lds + (bufoff) + ldsw + _i * 8192), 16, 0, 0); } while (0)
; #define PG8_LDA(dst, b, h) do { _Pragma("unroll") for (int m = 0; m < 4; ++m) _Pragma("unroll") for (int k = 0; k < 2; ++k) dst[m][k] = *(const LAS bf16x8*)(lds + PG8_SA(b, h) + aoff + m * 2048 + k * 1024); } while (0)
; #define PG8_LDB(dst, b, h) do { _Pragma("unroll") for (int n = 0; n < 2; ++n) _Pragma("unroll") for (int k = 0; k < 2; ++k) dst[n][k] = *(const LAS bf16x8*)(lds + PG8_SB(b, h) + boff + n * 2048 + k * 1024); } while (0)
; #define PG8_MMA(ai, bj, At, Bt) do { __builtin_amdgcn_s_setprio(3); _Pragma("unroll") for (int m = 0; m < 4; ++m) _Pragma("unroll") for (int n = 0; n < 2; ++n) _Pragma("unroll") for (int k = 0; k < 2; ++k) \
;         acc[ai][bj][m][n] = __builtin_amdgcn_mfma_f32_16x16x32_bf16(Bt[n][k], At[m][k], acc[ai][bj][m][n], 0, 0, 0); __builtin_amdgcn_s_setprio(0); } while (0)
; #define PG8_WAIT_V(n) asm volatile("s_waitcnt vmcnt(" #n ")" ::: "memory")
; #define PG8_WAIT_L(n) asm volatile("s_waitcnt lgkmcnt(" #n ")" ::: "memory")
; #define PG8_BAR __builtin_amdgcn_s_barrier()
; #define PG8_SCHED __builtin_amdgcn_sched_barrier(0)
; template <class Epi, class Sched>
; __device__ __forceinline__ void gemm_phase(LAS unsigned char* lds, const Gemm g, const Sched& S, const Epi& E, int tid_in) {
;     ...
;         for (int t = 0; t < nt; t += 2) {
;             const bool last = (t == nt - 2);
;             const char* a1 = cA + (size_t)(t + 1) * kstep;
;             const char* a2 = last ? nA : cA + (size_t)(t + 2) * kstep; const char* b2 = last ? nB : cB + (size_t)(t + 2) * kstep;
;             const char* a3 = a2 + kstep; const char* b3 = b2 + kstep;
;             PG8_LDB(B0, 0, 0); PG8_LDB(B1, 0, 1); PG8_SCHED; PG8_LDA(At, 0, 0); PG8_STAGE(PG8_SA(1, 0), a1, voffA); PG8_STAGE(PG8_SA(1, 1), a1 + hstep, voffA);
;     ...
;             PG8_LDA(At, 1, 1); PG8_STAGE(PG8_SB(1, 0), b3, voffB); PG8_STAGE(PG8_SB(1, 1), b3 + hstep, voffB);
;             PG8_WAIT_V(6); PG8_WAIT_L(0); PG8_BAR; PG8_MMA(1, 0, At, B0); PG8_MMA(1, 1, At, B1); PG8_BAR; PG8_SCHED;
	s_add_i32 s48, s97, s2
	v_lshl_add_u64 v[168:169], v[168:169], 0, s[10:11]
	s_mov_b32 m0, s48
	ds_read_b128 v[204:207], v181 offset:49152
	ds_read_b128 v[208:211], v181 offset:50176
	ds_read_b128 v[212:215], v181 offset:51200
	ds_read_b128 v[216:219], v181 offset:52224
	ds_read_b128 v[220:223], v181 offset:53248
	ds_read_b128 v[224:227], v181 offset:54272
	ds_read_b128 v[228:231], v181 offset:55296
	ds_read_b128 v[232:235], v181 offset:56320
	global_load_lds_dwordx4 v[168:169], off
	s_add_i32 m0, s48, 0x2000
	s_add_u32 s46, s46, 0x80080
	v_lshl_add_u64 v[168:169], v[176:177], 0, s[10:11]
	s_addc_u32 s47, s47, 0
	s_add_i32 s48, vcc_lo, s2
	global_load_lds_dwordx4 v[168:169], off
	v_lshl_add_u64 v[168:169], s[46:47], 0, v[148:149]
	s_mov_b32 m0, s48
	s_nop 0
	global_load_lds_dwordx4 v[168:169], off
	v_lshl_add_u64 v[168:169], s[46:47], 0, v[144:145]
	s_add_i32 m0, s48, 0x2000
	s_nop 0
	global_load_lds_dwordx4 v[168:169], off
	s_waitcnt vmcnt(6) lgkmcnt(0)
	s_barrier
	s_setprio 3
	v_mfma_f32_16x16x32_bf16 v[60:63], v[132:135], v[204:207], v[60:63]
	v_mfma_f32_16x16x32_bf16 v[56:59], v[140:143], v[204:207], v[56:59]
	v_mfma_f32_16x16x32_bf16 v[44:47], v[132:135], v[212:215], v[44:47]
	v_mfma_f32_16x16x32_bf16 v[40:43], v[140:143], v[212:215], v[40:43]
	v_mfma_f32_16x16x32_bf16 v[28:31], v[132:135], v[220:223], v[28:31]
	v_mfma_f32_16x16x32_bf16 v[24:27], v[140:143], v[220:223], v[24:27]
	v_mfma_f32_16x16x32_bf16 v[12:15], v[132:135], v[228:231], v[12:15]
	v_mfma_f32_16x16x32_bf16 v[8:11], v[140:143], v[228:231], v[8:11]
	v_mfma_f32_16x16x32_bf16 v[60:63], v[136:139], v[208:211], v[60:63]
	v_mfma_f32_16x16x32_bf16 v[56:59], v[172:175], v[208:211], v[56:59]
	v_mfma_f32_16x16x32_bf16 v[44:47], v[136:139], v[216:219], v[44:47]
	v_mfma_f32_16x16x32_bf16 v[40:43], v[172:175], v[216:219], v[40:43]
	v_mfma_f32_16x16x32_bf16 v[28:31], v[136:139], v[224:227], v[28:31]
	v_mfma_f32_16x16x32_bf16 v[24:27], v[172:175], v[224:227], v[24:27]
	v_mfma_f32_16x16x32_bf16 v[12:15], v[136:139], v[232:235], v[12:15]
	v_mfma_f32_16x16x32_bf16 v[8:11], v[172:175], v[232:235], v[8:11]
	s_setprio 0
	s_setprio 3
	v_mfma_f32_16x16x32_bf16 v[52:55], v[188:191], v[204:207], v[52:55]
	v_mfma_f32_16x16x32_bf16 v[48:51], v[196:199], v[204:207], v[48:51]
	v_mfma_f32_16x16x32_bf16 v[36:39], v[188:191], v[212:215], v[36:39]
	v_mfma_f32_16x16x32_bf16 v[32:35], v[196:199], v[212:215], v[32:35]
	v_mfma_f32_16x16x32_bf16 v[20:23], v[188:191], v[220:223], v[20:23]
	v_mfma_f32_16x16x32_bf16 v[16:19], v[196:199], v[220:223], v[16:19]
	v_mfma_f32_16x16x32_bf16 v[4:7], v[188:191], v[228:231], v[4:7]
	v_mfma_f32_16x16x32_bf16 v[0:3], v[196:199], v[228:231], v[0:3]
	v_mfma_f32_16x16x32_bf16 v[52:55], v[192:195], v[208:211], v[52:55]
	v_mfma_f32_16x16x32_bf16 v[48:51], v[200:203], v[208:211], v[48:51]
	v_mfma_f32_16x16x32_bf16 v[36:39], v[192:195], v[216:219], v[36:39]
	v_mfma_f32_16x16x32_bf16 v[32:35], v[200:203], v[216:219], v[32:35]
	v_mfma_f32_16x16x32_bf16 v[20:23], v[192:195], v[224:227], v[20:23]
	v_mfma_f32_16x16x32_bf16 v[16:19], v[200:203], v[224:227], v[16:19]
	v_mfma_f32_16x16x32_bf16 v[4:7], v[192:195], v[232:235], v[4:7]
	v_mfma_f32_16x16x32_bf16 v[0:3], v[200:203], v[232:235], v[0:3]
	s_setprio 0
	s_barrier
	s_add_i32 s96, s96, 2
	s_add_u32 s44, s44, 0x100
	s_addc_u32 s45, s45, 0
	s_cmp_gt_u32 s96, 29
	s_cbranch_scc0 .LBB0_102
	s_branch .Lpeel_exit_0
.LBB0_102:
	ds_read_b128 v[132:135], v179
	ds_read_b128 v[136:139], v179 offset:1024
	ds_read_b128 v[140:143], v179 offset:2048
	ds_read_b128 v[172:175], v179 offset:3072
	ds_read_b128 v[188:191], v180
	ds_read_b128 v[192:195], v180 offset:1024
	ds_read_b128 v[196:199], v180 offset:2048
	ds_read_b128 v[200:203], v180 offset:3072
	s_add_u32 s46, s42, s44
	s_addc_u32 s47, s43, s45
	s_add_u32 s48, s46, 0x100
	s_addc_u32 s49, s47, 0
	s_add_u32 s46, s94, s44
	s_addc_u32 s47, s95, s45
	s_cmpk_eq_i32 s44, 0xf00
	s_cselect_b32 s47, s29, s47
	s_cselect_b32 s46, s41, s46
	s_cselect_b32 s49, s31, s49
	s_cselect_b32 s48, s39, s48
	v_lshl_add_u64 v[168:169], v[130:131], 0, s[44:45]
	v_lshl_add_u64 v[176:177], v[168:169], 0, s[10:11]
	s_add_i32 m0, s60, 0x8000
	ds_read_b128 v[204:207], v181
	ds_read_b128 v[208:211], v181 offset:1024
	ds_read_b128 v[212:215], v181 offset:2048
	ds_read_b128 v[216:219], v181 offset:3072
	ds_read_b128 v[220:223], v181 offset:4096
	ds_read_b128 v[224:227], v181 offset:5120
	ds_read_b128 v[228:231], v181 offset:6144
	ds_read_b128 v[232:235], v181 offset:7168
	global_load_lds_dwordx4 v[176:177], off
	v_lshl_add_u64 v[176:177], v[128:129], 0, s[44:45]
	v_lshl_add_u64 v[184:185], v[176:177], 0, s[10:11]
	s_add_i32 m0, s60, 0xa000
	v_lshl_add_u64 v[168:169], v[168:169], 0, s[12:13]
	global_load_lds_dwordx4 v[184:185], off
	s_add_i32 m0, s60, 0xc000
	s_nop 0
	global_load_lds_dwordx4 v[168:169], off
	v_lshl_add_u64 v[168:169], v[176:177], 0, s[12:13]
	s_add_i32 m0, s60, 0xe000
	s_nop 0
	global_load_lds_dwordx4 v[168:169], off
	s_waitcnt vmcnt(8) lgkmcnt(0)
	s_barrier
; #define PG8_STAGE(bufoff, gbase, voff) do { _Pragma("unroll") for (int _i = 0; _i < 2; ++_i) \
;         __builtin_amdgcn_global_load_lds((const unsigned*)((const char*)(gbase) + (voff)[_i]), (LAS unsigned*)(lds + (bufoff) + ldsw + _i * 8192), 16, 0, 0); } while (0)
; #define PG8_LDA(dst, b, h) do { _Pragma("unroll") for (int m = 0; m < 4; ++m) _Pragma("unroll") for (int k = 0; k < 2; ++k) dst[m][k] = *(const LAS bf16x8*)(lds + PG8_SA(b, h) + aoff + m * 2048 + k * 1024); } while (0)
; #define PG8_MMA(ai, bj, At, Bt) do { __builtin_amdgcn_s_setprio(3); _Pragma("unroll") for (int m = 0; m < 4; ++m) _Pragma("unroll") for (int n = 0; n < 2; ++n) _Pragma("unroll") for (int k = 0; k < 2; ++k) \
;         acc[ai][bj][m][n] = __builtin_amdgcn_mfma_f32_16x16x32_bf16(Bt[n][k], At[m][k], acc[ai][bj][m][n], 0, 0, 0); __builtin_amdgcn_s_setprio(0); } while (0)
; #define PG8_WAIT_V(n) asm volatile("s_waitcnt vmcnt(" #n ")" ::: "memory")
; #define PG8_WAIT_L(n) asm volatile("s_waitcnt lgkmcnt(" #n ")" ::: "memory")
; #define PG8_BAR __builtin_amdgcn_s_barrier()
; #define PG8_SCHED __builtin_amdgcn_sched_barrier(0)
; template <class Epi, class Sched>
; __device__ __forceinline__ void gemm_phase(LAS unsigned char* lds, const Gemm g, const Sched& S, const Epi& E, int tid_in) {
;     ...
;             PG8_WAIT_V(8); PG8_WAIT_L(0); PG8_BAR; PG8_MMA(0, 0, At, B0); PG8_MMA(0, 1, At, B1); PG8_BAR; PG8_SCHED;
;             PG8_LDA(At, 0, 1); PG8_STAGE(PG8_SB(0, 0), b2, voffB); PG8_STAGE(PG8_SB(0, 1), b2 + hstep, voffB);
;             PG8_WAIT_V(6); PG8_WAIT_L(0); PG8_BAR; PG8_MMA(1, 0, At, B0); PG8_MMA(1, 1, At, B1); PG8_BAR; PG8_SCHED;
	s_setprio 3
	v_mfma_f32_16x16x32_bf16 v[124:127], v[132:135], v[204:207], v[124:127]
	v_mfma_f32_16x16x32_bf16 v[120:123], v[140:143], v[204:207], v[120:123]
	v_mfma_f32_16x16x32_bf16 v[108:111], v[132:135], v[212:215], v[108:111]
	v_mfma_f32_16x16x32_bf16 v[104:107], v[140:143], v[212:215], v[104:107]
	v_mfma_f32_16x16x32_bf16 v[92:95], v[132:135], v[220:223], v[92:95]
	v_mfma_f32_16x16x32_bf16 v[88:91], v[140:143], v[220:223], v[88:91]
	v_mfma_f32_16x16x32_bf16 v[76:79], v[132:135], v[228:231], v[76:79]
	v_mfma_f32_16x16x32_bf16 v[72:75], v[140:143], v[228:231], v[72:75]
	v_mfma_f32_16x16x32_bf16 v[124:127], v[136:139], v[208:211], v[124:127]
	v_mfma_f32_16x16x32_bf16 v[120:123], v[172:175], v[208:211], v[120:123]
	v_mfma_f32_16x16x32_bf16 v[108:111], v[136:139], v[216:219], v[108:111]
	v_mfma_f32_16x16x32_bf16 v[104:107], v[172:175], v[216:219], v[104:107]
	v_mfma_f32_16x16x32_bf16 v[92:95], v[136:139], v[224:227], v[92:95]
	v_mfma_f32_16x16x32_bf16 v[88:91], v[172:175], v[224:227], v[88:91]
	v_mfma_f32_16x16x32_bf16 v[76:79], v[136:139], v[232:235], v[76:79]
	v_mfma_f32_16x16x32_bf16 v[72:75], v[172:175], v[232:235], v[72:75]
	s_setprio 0
	s_setprio 3
	v_mfma_f32_16x16x32_bf16 v[116:119], v[188:191], v[204:207], v[116:119]
	v_mfma_f32_16x16x32_bf16 v[112:115], v[196:199], v[204:207], v[112:115]
	v_mfma_f32_16x16x32_bf16 v[100:103], v[188:191], v[212:215], v[100:103]
	v_mfma_f32_16x16x32_bf16 v[96:99], v[196:199], v[212:215], v[96:99]
	v_mfma_f32_16x16x32_bf16 v[84:87], v[188:191], v[220:223], v[84:87]
	v_mfma_f32_16x16x32_bf16 v[80:83], v[196:199], v[220:223], v[80:83]
	v_mfma_f32_16x16x32_bf16 v[68:71], v[188:191], v[228:231], v[68:71]
	v_mfma_f32_16x16x32_bf16 v[64:67], v[196:199], v[228:231], v[64:67]
	v_mfma_f32_16x16x32_bf16 v[116:119], v[192:195], v[208:211], v[116:119]
	v_mfma_f32_16x16x32_bf16 v[112:115], v[200:203], v[208:211], v[112:115]
	v_mfma_f32_16x16x32_bf16 v[100:103], v[192:195], v[216:219], v[100:103]
	v_mfma_f32_16x16x32_bf16 v[96:99], v[200:203], v[216:219], v[96:99]
	v_mfma_f32_16x16x32_bf16 v[84:87], v[192:195], v[224:227], v[84:87]
	v_mfma_f32_16x16x32_bf16 v[80:83], v[200:203], v[224:227], v[80:83]
	v_mfma_f32_16x16x32_bf16 v[68:71], v[192:195], v[232:235], v[68:71]
	v_mfma_f32_16x16x32_bf16 v[64:67], v[200:203], v[232:235], v[64:67]
	s_setprio 0
	s_barrier
	s_add_i32 s97, s66, s2
	v_lshl_add_u64 v[168:169], s[46:47], 0, v[148:149]
	s_mov_b32 m0, s97
	ds_read_b128 v[204:207], v181 offset:16384
	ds_read_b128 v[208:211], v181 offset:17408
	ds_read_b128 v[212:215], v181 offset:18432
	ds_read_b128 v[216:219], v181 offset:19456
	ds_read_b128 v[220:223], v181 offset:20480
	ds_read_b128 v[224:227], v181 offset:21504
	ds_read_b128 v[228:231], v181 offset:22528
	ds_read_b128 v[232:235], v181 offset:23552
	global_load_lds_dwordx4 v[168:169], off
	s_add_i32 m0, s97, 0x2000
	s_add_u32 vcc_lo, s46, 0x80000
	v_lshl_add_u64 v[176:177], s[46:47], 0, v[144:145]
	s_addc_u32 vcc_hi, s47, 0
	s_add_i32 s97, s67, s2
	global_load_lds_dwordx4 v[176:177], off
	v_lshl_add_u64 v[184:185], vcc, 0, v[148:149]
	s_mov_b32 m0, s97
	s_nop 0
	global_load_lds_dwordx4 v[184:185], off
	v_lshl_add_u64 v[184:185], vcc, 0, v[144:145]
	s_add_i32 m0, s97, 0x2000
	s_nop 0
	global_load_lds_dwordx4 v[184:185], off
	s_waitcnt vmcnt(6) lgkmcnt(0)
	s_barrier
	s_setprio 3
	v_mfma_f32_16x16x32_bf16 v[60:63], v[132:135], v[204:207], v[60:63]
	v_mfma_f32_16x16x32_bf16 v[56:59], v[140:143], v[204:207], v[56:59]
	v_mfma_f32_16x16x32_bf16 v[44:47], v[132:135], v[212:215], v[44:47]
	v_mfma_f32_16x16x32_bf16 v[40:43], v[140:143], v[212:215], v[40:43]
	v_mfma_f32_16x16x32_bf16 v[28:31], v[132:135], v[220:223], v[28:31]
	v_mfma_f32_16x16x32_bf16 v[24:27], v[140:143], v[220:223], v[24:27]
	v_mfma_f32_16x16x32_bf16 v[12:15], v[132:135], v[228:231], v[12:15]
	v_mfma_f32_16x16x32_bf16 v[8:11], v[140:143], v[228:231], v[8:11]
	v_mfma_f32_16x16x32_bf16 v[60:63], v[136:139], v[208:211], v[60:63]
	v_mfma_f32_16x16x32_bf16 v[56:59], v[172:175], v[208:211], v[56:59]
	v_mfma_f32_16x16x32_bf16 v[44:47], v[136:139], v[216:219], v[44:47]
	v_mfma_f32_16x16x32_bf16 v[40:43], v[172:175], v[216:219], v[40:43]
	v_mfma_f32_16x16x32_bf16 v[28:31], v[136:139], v[224:227], v[28:31]
	v_mfma_f32_16x16x32_bf16 v[24:27], v[172:175], v[224:227], v[24:27]
	v_mfma_f32_16x16x32_bf16 v[12:15], v[136:139], v[232:235], v[12:15]
	v_mfma_f32_16x16x32_bf16 v[8:11], v[172:175], v[232:235], v[8:11]
	s_setprio 0
	s_setprio 3
	v_mfma_f32_16x16x32_bf16 v[52:55], v[188:191], v[204:207], v[52:55]
	v_mfma_f32_16x16x32_bf16 v[48:51], v[196:199], v[204:207], v[48:51]
	v_mfma_f32_16x16x32_bf16 v[36:39], v[188:191], v[212:215], v[36:39]
	v_mfma_f32_16x16x32_bf16 v[32:35], v[196:199], v[212:215], v[32:35]
	v_mfma_f32_16x16x32_bf16 v[20:23], v[188:191], v[220:223], v[20:23]
	v_mfma_f32_16x16x32_bf16 v[16:19], v[196:199], v[220:223], v[16:19]
	v_mfma_f32_16x16x32_bf16 v[4:7], v[188:191], v[228:231], v[4:7]
	v_mfma_f32_16x16x32_bf16 v[0:3], v[196:199], v[228:231], v[0:3]
	v_mfma_f32_16x16x32_bf16 v[52:55], v[192:195], v[208:211], v[52:55]
	v_mfma_f32_16x16x32_bf16 v[48:51], v[200:203], v[208:211], v[48:51]
	v_mfma_f32_16x16x32_bf16 v[36:39], v[192:195], v[216:219], v[36:39]
	v_mfma_f32_16x16x32_bf16 v[32:35], v[200:203], v[216:219], v[32:35]
	v_mfma_f32_16x16x32_bf16 v[20:23], v[192:195], v[224:227], v[20:23]
	v_mfma_f32_16x16x32_bf16 v[16:19], v[200:203], v[224:227], v[16:19]
	v_mfma_f32_16x16x32_bf16 v[4:7], v[192:195], v[232:235], v[4:7]
	v_mfma_f32_16x16x32_bf16 v[0:3], v[200:203], v[232:235], v[0:3]
	s_setprio 0
	s_barrier
; #define PG8_STAGE(bufoff, gbase, voff) do { _Pragma("unroll") for (int _i = 0; _i < 2; ++_i) \
;         __builtin_amdgcn_global_load_lds((const unsigned*)((const char*)(gbase) + (voff)[_i]), (LAS unsigned*)(lds + (bufoff) + ldsw + _i * 8192), 16, 0, 0); } while (0)
; #define PG8_LDA(dst, b, h) do { _Pragma("unroll") for (int m = 0; m < 4; ++m) _Pragma("unroll") for (int k = 0; k < 2; ++k) dst[m][k] = *(const LAS bf16x8*)(lds + PG8_SA(b, h) + aoff + m * 2048 + k * 1024); } while (0)
; #define PG8_LDB(dst, b, h) do { _Pragma("unroll") for (int n = 0; n < 2; ++n) _Pragma("unroll") for (int k = 0; k < 2; ++k) dst[n][k] = *(const LAS bf16x8*)(lds + PG8_SB(b, h) + boff + n * 2048 + k * 1024); } while (0)
; #define PG8_MMA(ai, bj, At, Bt) do { __builtin_amdgcn_s_setprio(3); _Pragma("unroll") for (int m = 0; m < 4; ++m) _Pragma("unroll") for (int n = 0; n < 2; ++n) _Pragma("unroll") for (int k = 0; k < 2; ++k) \
;         acc[ai][bj][m][n] = __builtin_amdgcn_mfma_f32_16x16x32_bf16(Bt[n][k], At[m][k], acc[ai][bj][m][n], 0, 0, 0); __builtin_amdgcn_s_setprio(0); } while (0)
; #define PG8_WAIT_V(n) asm volatile("s_waitcnt vmcnt(" #n ")" ::: "memory")
; #define PG8_WAIT_L(n) asm volatile("s_waitcnt lgkmcnt(" #n ")" ::: "memory")
; #define PG8_BAR __builtin_amdgcn_s_barrier()
; #define PG8_SCHED __builtin_amdgcn_sched_barrier(0)
; template <class Epi, class Sched>
; __device__ __forceinline__ void gemm_phase(LAS unsigned char* lds, const Gemm g, const Sched& S, const Epi& E, int tid_in) {
;     ...
;             PG8_LDB(B0, 1, 0); PG8_LDB(B1, 1, 1); PG8_SCHED; PG8_LDA(At, 1, 0); PG8_STAGE(PG8_SA(0, 0), a2, voffA); PG8_STAGE(PG8_SA(0, 1), a2 + hstep, voffA);
;             PG8_WAIT_V(8); PG8_WAIT_L(0); PG8_BAR; PG8_MMA(0, 0, At, B0); PG8_MMA(0, 1, At, B1); PG8_BAR; PG8_SCHED;
;             PG8_LDA(At, 1, 1); PG8_STAGE(PG8_SB(1, 0), b3, voffB); PG8_STAGE(PG8_SB(1, 1), b3 + hstep, voffB);
;             PG8_WAIT_V(6); PG8_WAIT_L(0); PG8_BAR; PG8_MMA(1, 0, At, B0); PG8_MMA(1, 1, At, B1); PG8_BAR; PG8_SCHED;
	s_add_i32 s97, 0, 0x18000
	v_add_u32_e32 v152, s97, v171
	s_add_i32 vcc_lo, 0, 0x1c000
	ds_read_b128 v[132:135], v152
	ds_read_b128 v[136:139], v152 offset:1024
	ds_read_b128 v[140:143], v152 offset:2048
	ds_read_b128 v[172:175], v152 offset:3072
	v_add_u32_e32 v152, vcc_lo, v171
	ds_read_b128 v[188:191], v152
	ds_read_b128 v[192:195], v152 offset:1024
	ds_read_b128 v[196:199], v152 offset:2048
	ds_read_b128 v[200:203], v152 offset:3072
	s_mov_b32 m0, s60
	v_lshl_add_u64 v[184:185], s[48:49], 0, v[150:151]
	ds_read_b128 v[204:207], v181 offset:32768
	ds_read_b128 v[208:211], v181 offset:33792
	ds_read_b128 v[212:215], v181 offset:34816
	ds_read_b128 v[216:219], v181 offset:35840
	ds_read_b128 v[220:223], v181 offset:36864
	ds_read_b128 v[224:227], v181 offset:37888
	ds_read_b128 v[228:231], v181 offset:38912
	ds_read_b128 v[232:235], v181 offset:39936
	global_load_lds_dwordx4 v[184:185], off
	v_lshl_add_u64 v[184:185], s[48:49], 0, v[146:147]
	s_add_u32 s48, s48, 0x80000
	s_mov_b32 m0, s61
	s_addc_u32 s49, s49, 0
	global_load_lds_dwordx4 v[184:185], off
	v_lshl_add_u64 v[184:185], s[48:49], 0, v[150:151]
	s_mov_b32 m0, s62
	s_nop 0
	global_load_lds_dwordx4 v[184:185], off
	v_lshl_add_u64 v[184:185], s[48:49], 0, v[146:147]
	s_mov_b32 m0, s63
	s_nop 0
	global_load_lds_dwordx4 v[184:185], off
	s_waitcnt vmcnt(8) lgkmcnt(0)
	s_barrier
	s_setprio 3
	v_mfma_f32_16x16x32_bf16 v[124:127], v[132:135], v[204:207], v[124:127]
	v_mfma_f32_16x16x32_bf16 v[120:123], v[140:143], v[204:207], v[120:123]
	v_mfma_f32_16x16x32_bf16 v[108:111], v[132:135], v[212:215], v[108:111]
	v_mfma_f32_16x16x32_bf16 v[104:107], v[140:143], v[212:215], v[104:107]
	v_mfma_f32_16x16x32_bf16 v[92:95], v[132:135], v[220:223], v[92:95]
	v_mfma_f32_16x16x32_bf16 v[88:91], v[140:143], v[220:223], v[88:91]
	v_mfma_f32_16x16x32_bf16 v[76:79], v[132:135], v[228:231], v[76:79]
	v_mfma_f32_16x16x32_bf16 v[72:75], v[140:143], v[228:231], v[72:75]
	v_mfma_f32_16x16x32_bf16 v[124:127], v[136:139], v[208:211], v[124:127]
	v_mfma_f32_16x16x32_bf16 v[120:123], v[172:175], v[208:211], v[120:123]
	v_mfma_f32_16x16x32_bf16 v[108:111], v[136:139], v[216:219], v[108:111]
	v_mfma_f32_16x16x32_bf16 v[104:107], v[172:175], v[216:219], v[104:107]
	v_mfma_f32_16x16x32_bf16 v[92:95], v[136:139], v[224:227], v[92:95]
	v_mfma_f32_16x16x32_bf16 v[88:91], v[172:175], v[224:227], v[88:91]
	v_mfma_f32_16x16x32_bf16 v[76:79], v[136:139], v[232:235], v[76:79]
	v_mfma_f32_16x16x32_bf16 v[72:75], v[172:175], v[232:235], v[72:75]
	s_setprio 0
	s_setprio 3
	v_mfma_f32_16x16x32_bf16 v[116:119], v[188:191], v[204:207], v[116:119]
	v_mfma_f32_16x16x32_bf16 v[112:115], v[196:199], v[204:207], v[112:115]
	v_mfma_f32_16x16x32_bf16 v[100:103], v[188:191], v[212:215], v[100:103]
	v_mfma_f32_16x16x32_bf16 v[96:99], v[196:199], v[212:215], v[96:99]
	v_mfma_f32_16x16x32_bf16 v[84:87], v[188:191], v[220:223], v[84:87]
	v_mfma_f32_16x16x32_bf16 v[80:83], v[196:199], v[220:223], v[80:83]
	v_mfma_f32_16x16x32_bf16 v[68:71], v[188:191], v[228:231], v[68:71]
	v_mfma_f32_16x16x32_bf16 v[64:67], v[196:199], v[228:231], v[64:67]
	v_mfma_f32_16x16x32_bf16 v[116:119], v[192:195], v[208:211], v[116:119]
	v_mfma_f32_16x16x32_bf16 v[112:115], v[200:203], v[208:211], v[112:115]
	v_mfma_f32_16x16x32_bf16 v[100:103], v[192:195], v[216:219], v[100:103]
	v_mfma_f32_16x16x32_bf16 v[96:99], v[200:203], v[216:219], v[96:99]
	v_mfma_f32_16x16x32_bf16 v[84:87], v[192:195], v[224:227], v[84:87]
	v_mfma_f32_16x16x32_bf16 v[80:83], v[200:203], v[224:227], v[80:83]
	v_mfma_f32_16x16x32_bf16 v[68:71], v[192:195], v[232:235], v[68:71]
	v_mfma_f32_16x16x32_bf16 v[64:67], v[200:203], v[232:235], v[64:67]
	s_setprio 0
	s_barrier
	s_add_i32 s48, s97, s2
	v_lshl_add_u64 v[168:169], v[168:169], 0, s[10:11]
	s_mov_b32 m0, s48
	ds_read_b128 v[204:207], v181 offset:49152
	ds_read_b128 v[208:211], v181 offset:50176
	ds_read_b128 v[212:215], v181 offset:51200
	ds_read_b128 v[216:219], v181 offset:52224
	ds_read_b128 v[220:223], v181 offset:53248
	ds_read_b128 v[224:227], v181 offset:54272
	ds_read_b128 v[228:231], v181 offset:55296
	ds_read_b128 v[232:235], v181 offset:56320
	global_load_lds_dwordx4 v[168:169], off
	s_add_i32 m0, s48, 0x2000
	s_add_u32 s46, s46, 0x80080
	v_lshl_add_u64 v[168:169], v[176:177], 0, s[10:11]
	s_addc_u32 s47, s47, 0
	s_add_i32 s48, vcc_lo, s2
	global_load_lds_dwordx4 v[168:169], off
	v_lshl_add_u64 v[168:169], s[46:47], 0, v[148:149]
	s_mov_b32 m0, s48
	s_nop 0
	global_load_lds_dwordx4 v[168:169], off
	v_lshl_add_u64 v[168:169], s[46:47], 0, v[144:145]
	s_add_i32 m0, s48, 0x2000
	s_nop 0
	global_load_lds_dwordx4 v[168:169], off
	s_waitcnt vmcnt(6) lgkmcnt(0)
	s_barrier
	s_setprio 3
	v_mfma_f32_16x16x32_bf16 v[60:63], v[132:135], v[204:207], v[60:63]
	v_mfma_f32_16x16x32_bf16 v[56:59], v[140:143], v[204:207], v[56:59]
	v_mfma_f32_16x16x32_bf16 v[44:47], v[132:135], v[212:215], v[44:47]
	v_mfma_f32_16x16x32_bf16 v[40:43], v[140:143], v[212:215], v[40:43]
	v_mfma_f32_16x16x32_bf16 v[28:31], v[132:135], v[220:223], v[28:31]
	v_mfma_f32_16x16x32_bf16 v[24:27], v[140:143], v[220:223], v[24:27]
	v_mfma_f32_16x16x32_bf16 v[12:15], v[132:135], v[228:231], v[12:15]
	v_mfma_f32_16x16x32_bf16 v[8:11], v[140:143], v[228:231], v[8:11]
	v_mfma_f32_16x16x32_bf16 v[60:63], v[136:139], v[208:211], v[60:63]
	v_mfma_f32_16x16x32_bf16 v[56:59], v[172:175], v[208:211], v[56:59]
	v_mfma_f32_16x16x32_bf16 v[44:47], v[136:139], v[216:219], v[44:47]
	v_mfma_f32_16x16x32_bf16 v[40:43], v[172:175], v[216:219], v[40:43]
	v_mfma_f32_16x16x32_bf16 v[28:31], v[136:139], v[224:227], v[28:31]
	v_mfma_f32_16x16x32_bf16 v[24:27], v[172:175], v[224:227], v[24:27]
	v_mfma_f32_16x16x32_bf16 v[12:15], v[136:139], v[232:235], v[12:15]
	v_mfma_f32_16x16x32_bf16 v[8:11], v[172:175], v[232:235], v[8:11]
	s_setprio 0
	s_setprio 3
	v_mfma_f32_16x16x32_bf16 v[52:55], v[188:191], v[204:207], v[52:55]
	v_mfma_f32_16x16x32_bf16 v[48:51], v[196:199], v[204:207], v[48:51]
	v_mfma_f32_16x16x32_bf16 v[36:39], v[188:191], v[212:215], v[36:39]
	v_mfma_f32_16x16x32_bf16 v[32:35], v[196:199], v[212:215], v[32:35]
	v_mfma_f32_16x16x32_bf16 v[20:23], v[188:191], v[220:223], v[20:23]
	v_mfma_f32_16x16x32_bf16 v[16:19], v[196:199], v[220:223], v[16:19]
	v_mfma_f32_16x16x32_bf16 v[4:7], v[188:191], v[228:231], v[4:7]
	v_mfma_f32_16x16x32_bf16 v[0:3], v[196:199], v[228:231], v[0:3]
	v_mfma_f32_16x16x32_bf16 v[52:55], v[192:195], v[208:211], v[52:55]
	v_mfma_f32_16x16x32_bf16 v[48:51], v[200:203], v[208:211], v[48:51]
	v_mfma_f32_16x16x32_bf16 v[36:39], v[192:195], v[216:219], v[36:39]
	v_mfma_f32_16x16x32_bf16 v[32:35], v[200:203], v[216:219], v[32:35]
	v_mfma_f32_16x16x32_bf16 v[20:23], v[192:195], v[224:227], v[20:23]
	v_mfma_f32_16x16x32_bf16 v[16:19], v[200:203], v[224:227], v[16:19]
	v_mfma_f32_16x16x32_bf16 v[4:7], v[192:195], v[232:235], v[4:7]
	v_mfma_f32_16x16x32_bf16 v[0:3], v[200:203], v[232:235], v[0:3]
	s_setprio 0
	s_barrier
	s_add_i32 s96, s96, 2
	s_add_u32 s44, s44, 0x100
	s_addc_u32 s45, s45, 0
	s_cmp_gt_u32 s96, 29
	s_cbranch_scc0 .LBB0_102

; #define PG8_STAGE(bufoff, gbase, voff) do { _Pragma("unroll") for (int _i = 0; _i < 2; ++_i) \
;         __builtin_amdgcn_global_load_lds((const unsigned*)((const char*)(gbase) + (voff)[_i]), (LAS unsigned*)(lds + (bufoff) + ldsw + _i * 8192), 16, 0, 0); } while (0)
; #define PG8_LDA(dst, b, h) do { _Pragma("unroll") for (int m = 0; m < 4; ++m) _Pragma("unroll") for (int k = 0; k < 2; ++k) dst[m][k] = *(const LAS bf16x8*)(lds + PG8_SA(b, h) + aoff + m * 2048 + k * 1024); } while (0)
; #define PG8_LDB(dst, b, h) do { _Pragma("unroll") for (int n = 0; n < 2; ++n) _Pragma("unroll") for (int k = 0; k < 2; ++k) dst[n][k] = *(const LAS bf16x8*)(lds + PG8_SB(b, h) + boff + n * 2048 + k * 1024); } while (0)
; #define PG8_MMA(ai, bj, At, Bt) do { __builtin_amdgcn_s_setprio(3); _Pragma("unroll") for (int m = 0; m < 4; ++m) _Pragma("unroll") for (int n = 0; n < 2; ++n) _Pragma("unroll") for (int k = 0; k < 2; ++k) \
;         acc[ai][bj][m][n] = __builtin_amdgcn_mfma_f32_16x16x32_bf16(Bt[n][k], At[m][k], acc[ai][bj][m][n], 0, 0, 0); __builtin_amdgcn_s_setprio(0); } while (0)
; #define PG8_WAIT_V(n) asm volatile("s_waitcnt vmcnt(" #n ")" ::: "memory")
; #define PG8_WAIT_L(n) asm volatile("s_waitcnt lgkmcnt(" #n ")" ::: "memory")
; #define PG8_BAR __builtin_amdgcn_s_barrier()
; #define PG8_SCHED __builtin_amdgcn_sched_barrier(0)
; template <class Epi, class Sched>
; __device__ __forceinline__ void gemm_phase(LAS unsigned char* lds, const Gemm g, const Sched& S, const Epi& E, int tid_in) {
;     ...
;             const char* a1 = cA + (size_t)(t + 1) * kstep;
;             const char* a2 = last ? nA : cA + (size_t)(t + 2) * kstep; const char* b2 = last ? nB : cB + (size_t)(t + 2) * kstep;
;             const char* a3 = a2 + kstep; const char* b3 = b2 + kstep;
;             PG8_LDB(B0, 0, 0); PG8_LDB(B1, 0, 1); PG8_SCHED; PG8_LDA(At, 0, 0); PG8_STAGE(PG8_SA(1, 0), a1, voffA); PG8_STAGE(PG8_SA(1, 1), a1 + hstep, voffA);
;             PG8_WAIT_V(8); PG8_WAIT_L(0); PG8_BAR; PG8_MMA(0, 0, At, B0); PG8_MMA(0, 1, At, B1); PG8_BAR; PG8_SCHED;
;             PG8_LDA(At, 0, 1); PG8_STAGE(PG8_SB(0, 0), b2, voffB); PG8_STAGE(PG8_SB(0, 1), b2 + hstep, voffB);
;             PG8_WAIT_V(6); PG8_WAIT_L(0); PG8_BAR; PG8_MMA(1, 0, At, B0); PG8_MMA(1, 1, At, B1); PG8_BAR; PG8_SCHED;
.LBB0_511:
	v_add_u32_e32 v144, s49, v188
	v_add_u32_e32 v176, s51, v188
	s_add_u32 s42, s38, s40
	ds_read_b128 v[132:135], v144
	ds_read_b128 v[136:139], v144 offset:1024
	ds_read_b128 v[140:143], v144 offset:2048
	ds_read_b128 v[144:147], v144 offset:3072
	ds_read_b128 v[148:151], v176
	ds_read_b128 v[152:155], v176 offset:1024
	ds_read_b128 v[172:175], v176 offset:2048
	ds_read_b128 v[176:179], v176 offset:3072
	s_addc_u32 s43, s39, s41
	s_add_u32 s44, s42, 0x100
	s_addc_u32 s45, s43, 0
	s_add_u32 s42, s77, s40
	s_addc_u32 s43, s78, s41
	s_cmpk_eq_i32 s40, 0x700
	s_cselect_b32 s43, s27, s43
	s_cselect_b32 s42, s76, s42
	s_cselect_b32 s45, s29, s45
	s_cselect_b32 s44, s37, s44
	v_lshl_add_u64 v[184:185], v[130:131], 0, s[40:41]
	v_lshl_add_u64 v[220:221], v[184:185], 0, s[14:15]
	s_add_i32 m0, s3, 0x8000
	ds_read_b128 v[180:183], v190
	ds_read_b128 v[192:195], v190 offset:1024
	ds_read_b128 v[196:199], v190 offset:2048
	ds_read_b128 v[200:203], v190 offset:3072
	ds_read_b128 v[204:207], v190 offset:4096
	ds_read_b128 v[208:211], v190 offset:5120
	ds_read_b128 v[212:215], v190 offset:6144
	ds_read_b128 v[216:219], v190 offset:7168
	global_load_lds_dwordx4 v[220:221], off
	v_lshl_add_u64 v[220:221], v[128:129], 0, s[40:41]
	v_lshl_add_u64 v[222:223], v[220:221], 0, s[14:15]
	s_add_i32 m0, s3, 0xa000
	v_lshl_add_u64 v[184:185], v[184:185], 0, s[16:17]
	global_load_lds_dwordx4 v[222:223], off
	s_add_i32 m0, s3, 0xc000
	s_nop 0
	global_load_lds_dwordx4 v[184:185], off
	v_lshl_add_u64 v[184:185], v[220:221], 0, s[16:17]
	s_add_i32 m0, s3, 0xe000
	s_nop 0
	global_load_lds_dwordx4 v[184:185], off
	s_waitcnt vmcnt(8) lgkmcnt(0)
	s_barrier
	s_setprio 3
	v_mfma_f32_16x16x32_bf16 v[124:127], v[132:135], v[180:183], v[124:127]
	v_mfma_f32_16x16x32_bf16 v[120:123], v[140:143], v[180:183], v[120:123]
	v_mfma_f32_16x16x32_bf16 v[116:119], v[132:135], v[196:199], v[116:119]
	v_mfma_f32_16x16x32_bf16 v[112:115], v[140:143], v[196:199], v[112:115]
	v_mfma_f32_16x16x32_bf16 v[108:111], v[132:135], v[204:207], v[108:111]
	v_mfma_f32_16x16x32_bf16 v[104:107], v[140:143], v[204:207], v[104:107]
	v_mfma_f32_16x16x32_bf16 v[100:103], v[132:135], v[212:215], v[100:103]
	v_mfma_f32_16x16x32_bf16 v[96:99], v[140:143], v[212:215], v[96:99]
	v_mfma_f32_16x16x32_bf16 v[124:127], v[136:139], v[192:195], v[124:127]
	v_mfma_f32_16x16x32_bf16 v[120:123], v[144:147], v[192:195], v[120:123]
	v_mfma_f32_16x16x32_bf16 v[116:119], v[136:139], v[200:203], v[116:119]
	v_mfma_f32_16x16x32_bf16 v[112:115], v[144:147], v[200:203], v[112:115]
	v_mfma_f32_16x16x32_bf16 v[108:111], v[136:139], v[208:211], v[108:111]
	v_mfma_f32_16x16x32_bf16 v[104:107], v[144:147], v[208:211], v[104:107]
	v_mfma_f32_16x16x32_bf16 v[100:103], v[136:139], v[216:219], v[100:103]
	v_mfma_f32_16x16x32_bf16 v[96:99], v[144:147], v[216:219], v[96:99]
	s_setprio 0
	s_setprio 3
	v_mfma_f32_16x16x32_bf16 v[92:95], v[148:151], v[180:183], v[92:95]
	v_mfma_f32_16x16x32_bf16 v[88:91], v[172:175], v[180:183], v[88:91]
	v_mfma_f32_16x16x32_bf16 v[84:87], v[148:151], v[196:199], v[84:87]
	v_mfma_f32_16x16x32_bf16 v[80:83], v[172:175], v[196:199], v[80:83]
	v_mfma_f32_16x16x32_bf16 v[76:79], v[148:151], v[204:207], v[76:79]
	v_mfma_f32_16x16x32_bf16 v[72:75], v[172:175], v[204:207], v[72:75]
	v_mfma_f32_16x16x32_bf16 v[68:71], v[148:151], v[212:215], v[68:71]
	v_mfma_f32_16x16x32_bf16 v[64:67], v[172:175], v[212:215], v[64:67]
	v_mfma_f32_16x16x32_bf16 v[92:95], v[152:155], v[192:195], v[92:95]
	v_mfma_f32_16x16x32_bf16 v[88:91], v[176:179], v[192:195], v[88:91]
	v_mfma_f32_16x16x32_bf16 v[84:87], v[152:155], v[200:203], v[84:87]
	v_mfma_f32_16x16x32_bf16 v[80:83], v[176:179], v[200:203], v[80:83]
	v_mfma_f32_16x16x32_bf16 v[76:79], v[152:155], v[208:211], v[76:79]
	v_mfma_f32_16x16x32_bf16 v[72:75], v[176:179], v[208:211], v[72:75]
	v_mfma_f32_16x16x32_bf16 v[68:71], v[152:155], v[216:219], v[68:71]
	v_mfma_f32_16x16x32_bf16 v[64:67], v[176:179], v[216:219], v[64:67]
	s_setprio 0
	s_barrier
	s_add_i32 s80, s49, s2
	v_lshl_add_u64 v[184:185], s[42:43], 0, v[158:159]
	s_mov_b32 m0, s80
	ds_read_b128 v[180:183], v190 offset:16384
	ds_read_b128 v[192:195], v190 offset:17408
	ds_read_b128 v[196:199], v190 offset:18432
	ds_read_b128 v[200:203], v190 offset:19456
	ds_read_b128 v[204:207], v190 offset:20480
	ds_read_b128 v[208:211], v190 offset:21504
	ds_read_b128 v[212:215], v190 offset:22528
	ds_read_b128 v[216:219], v190 offset:23552
	global_load_lds_dwordx4 v[184:185], off
	s_add_i32 m0, s80, 0x2000
	s_add_u32 s80, s42, 0x80000
	v_lshl_add_u64 v[220:221], s[42:43], 0, v[162:163]
	s_addc_u32 s81, s43, 0
	s_add_i32 s82, s51, s2
	global_load_lds_dwordx4 v[220:221], off
	v_lshl_add_u64 v[222:223], s[80:81], 0, v[158:159]
	s_mov_b32 m0, s82
	s_nop 0
	global_load_lds_dwordx4 v[222:223], off
	v_lshl_add_u64 v[222:223], s[80:81], 0, v[162:163]
	s_add_i32 m0, s82, 0x2000
	s_nop 0
	global_load_lds_dwordx4 v[222:223], off
	s_waitcnt vmcnt(6) lgkmcnt(0)
	s_barrier
; #define PG8_STAGE(bufoff, gbase, voff) do { _Pragma("unroll") for (int _i = 0; _i < 2; ++_i) \
;         __builtin_amdgcn_global_load_lds((const unsigned*)((const char*)(gbase) + (voff)[_i]), (LAS unsigned*)(lds + (bufoff) + ldsw + _i * 8192), 16, 0, 0); } while (0)
; #define PG8_LDA(dst, b, h) do { _Pragma("unroll") for (int m = 0; m < 4; ++m) _Pragma("unroll") for (int k = 0; k < 2; ++k) dst[m][k] = *(const LAS bf16x8*)(lds + PG8_SA(b, h) + aoff + m * 2048 + k * 1024); } while (0)
; #define PG8_LDB(dst, b, h) do { _Pragma("unroll") for (int n = 0; n < 2; ++n) _Pragma("unroll") for (int k = 0; k < 2; ++k) dst[n][k] = *(const LAS bf16x8*)(lds + PG8_SB(b, h) + boff + n * 2048 + k * 1024); } while (0)
; #define PG8_MMA(ai, bj, At, Bt) do { __builtin_amdgcn_s_setprio(3); _Pragma("unroll") for (int m = 0; m < 4; ++m) _Pragma("unroll") for (int n = 0; n < 2; ++n) _Pragma("unroll") for (int k = 0; k < 2; ++k) \
;         acc[ai][bj][m][n] = __builtin_amdgcn_mfma_f32_16x16x32_bf16(Bt[n][k], At[m][k], acc[ai][bj][m][n], 0, 0, 0); __builtin_amdgcn_s_setprio(0); } while (0)
; #define PG8_WAIT_V(n) asm volatile("s_waitcnt vmcnt(" #n ")" ::: "memory")
; #define PG8_WAIT_L(n) asm volatile("s_waitcnt lgkmcnt(" #n ")" ::: "memory")
; #define PG8_BAR __builtin_amdgcn_s_barrier()
; #define PG8_SCHED __builtin_amdgcn_sched_barrier(0)
; template <class Epi, class Sched>
; __device__ __forceinline__ void gemm_phase(LAS unsigned char* lds, const Gemm g, const Sched& S, const Epi& E, int tid_in) {
;     ...
;             PG8_WAIT_V(6); PG8_WAIT_L(0); PG8_BAR; PG8_MMA(1, 0, At, B0); PG8_MMA(1, 1, At, B1); PG8_BAR; PG8_SCHED;
;             PG8_LDB(B0, 1, 0); PG8_LDB(B1, 1, 1); PG8_SCHED; PG8_LDA(At, 1, 0); PG8_STAGE(PG8_SA(0, 0), a2, voffA); PG8_STAGE(PG8_SA(0, 1), a2 + hstep, voffA);
;             PG8_WAIT_V(8); PG8_WAIT_L(0); PG8_BAR; PG8_MMA(0, 0, At, B0); PG8_MMA(0, 1, At, B1); PG8_BAR; PG8_SCHED;
	s_setprio 3
	v_mfma_f32_16x16x32_bf16 v[60:63], v[132:135], v[180:183], v[60:63]
	v_mfma_f32_16x16x32_bf16 v[56:59], v[140:143], v[180:183], v[56:59]
	v_mfma_f32_16x16x32_bf16 v[52:55], v[132:135], v[196:199], v[52:55]
	v_mfma_f32_16x16x32_bf16 v[48:51], v[140:143], v[196:199], v[48:51]
	v_mfma_f32_16x16x32_bf16 v[44:47], v[132:135], v[204:207], v[44:47]
	v_mfma_f32_16x16x32_bf16 v[40:43], v[140:143], v[204:207], v[40:43]
	v_mfma_f32_16x16x32_bf16 v[36:39], v[132:135], v[212:215], v[36:39]
	v_mfma_f32_16x16x32_bf16 v[32:35], v[140:143], v[212:215], v[32:35]
	v_mfma_f32_16x16x32_bf16 v[60:63], v[136:139], v[192:195], v[60:63]
	v_mfma_f32_16x16x32_bf16 v[56:59], v[144:147], v[192:195], v[56:59]
	v_mfma_f32_16x16x32_bf16 v[52:55], v[136:139], v[200:203], v[52:55]
	v_mfma_f32_16x16x32_bf16 v[48:51], v[144:147], v[200:203], v[48:51]
	v_mfma_f32_16x16x32_bf16 v[44:47], v[136:139], v[208:211], v[44:47]
	v_mfma_f32_16x16x32_bf16 v[40:43], v[144:147], v[208:211], v[40:43]
	v_mfma_f32_16x16x32_bf16 v[36:39], v[136:139], v[216:219], v[36:39]
	v_mfma_f32_16x16x32_bf16 v[32:35], v[144:147], v[216:219], v[32:35]
	s_setprio 0
	s_setprio 3
	v_mfma_f32_16x16x32_bf16 v[28:31], v[148:151], v[180:183], v[28:31]
	v_mfma_f32_16x16x32_bf16 v[24:27], v[172:175], v[180:183], v[24:27]
	v_mfma_f32_16x16x32_bf16 v[20:23], v[148:151], v[196:199], v[20:23]
	v_mfma_f32_16x16x32_bf16 v[16:19], v[172:175], v[196:199], v[16:19]
	v_mfma_f32_16x16x32_bf16 v[12:15], v[148:151], v[204:207], v[12:15]
	v_mfma_f32_16x16x32_bf16 v[8:11], v[172:175], v[204:207], v[8:11]
	v_mfma_f32_16x16x32_bf16 v[4:7], v[148:151], v[212:215], v[4:7]
	v_mfma_f32_16x16x32_bf16 v[0:3], v[172:175], v[212:215], v[0:3]
	v_mfma_f32_16x16x32_bf16 v[28:31], v[152:155], v[192:195], v[28:31]
	v_mfma_f32_16x16x32_bf16 v[24:27], v[176:179], v[192:195], v[24:27]
	v_mfma_f32_16x16x32_bf16 v[20:23], v[152:155], v[200:203], v[20:23]
	v_mfma_f32_16x16x32_bf16 v[16:19], v[176:179], v[200:203], v[16:19]
	v_mfma_f32_16x16x32_bf16 v[12:15], v[152:155], v[208:211], v[12:15]
	v_mfma_f32_16x16x32_bf16 v[8:11], v[176:179], v[208:211], v[8:11]
	v_mfma_f32_16x16x32_bf16 v[4:7], v[152:155], v[216:219], v[4:7]
	v_mfma_f32_16x16x32_bf16 v[0:3], v[176:179], v[216:219], v[0:3]
	s_setprio 0
	s_barrier
	s_add_i32 s80, 0, 0x18000
	s_add_i32 s81, 0, 0x1c000
	v_add_u32_e32 v144, s80, v188
	v_add_u32_e32 v176, s81, v188
	ds_read_b128 v[132:135], v144
	ds_read_b128 v[136:139], v144 offset:1024
	ds_read_b128 v[140:143], v144 offset:2048
	ds_read_b128 v[144:147], v144 offset:3072
	ds_read_b128 v[148:151], v176
	ds_read_b128 v[152:155], v176 offset:1024
	ds_read_b128 v[172:175], v176 offset:2048
	ds_read_b128 v[176:179], v176 offset:3072
	s_mov_b32 m0, s3
	v_lshl_add_u64 v[222:223], s[44:45], 0, v[156:157]
	ds_read_b128 v[180:183], v190 offset:32768
	ds_read_b128 v[192:195], v190 offset:33792
	ds_read_b128 v[196:199], v190 offset:34816
	ds_read_b128 v[200:203], v190 offset:35840
	ds_read_b128 v[204:207], v190 offset:36864
	ds_read_b128 v[208:211], v190 offset:37888
	ds_read_b128 v[212:215], v190 offset:38912
	ds_read_b128 v[216:219], v190 offset:39936
	global_load_lds_dwordx4 v[222:223], off
	v_lshl_add_u64 v[222:223], s[44:45], 0, v[160:161]
	s_add_u32 s44, s44, 0x80000
	s_mov_b32 m0, s46
	s_addc_u32 s45, s45, 0
	global_load_lds_dwordx4 v[222:223], off
	v_lshl_add_u64 v[222:223], s[44:45], 0, v[156:157]
	s_mov_b32 m0, s47
	s_nop 0
	global_load_lds_dwordx4 v[222:223], off
	v_lshl_add_u64 v[222:223], s[44:45], 0, v[160:161]
	s_mov_b32 m0, s48
	s_nop 0
	global_load_lds_dwordx4 v[222:223], off
	s_waitcnt vmcnt(8) lgkmcnt(0)
	s_barrier
; #define PG8_STAGE(bufoff, gbase, voff) do { _Pragma("unroll") for (int _i = 0; _i < 2; ++_i) \
;         __builtin_amdgcn_global_load_lds((const unsigned*)((const char*)(gbase) + (voff)[_i]), (LAS unsigned*)(lds + (bufoff) + ldsw + _i * 8192), 16, 0, 0); } while (0)
; #define PG8_LDA(dst, b, h) do { _Pragma("unroll") for (int m = 0; m < 4; ++m) _Pragma("unroll") for (int k = 0; k < 2; ++k) dst[m][k] = *(const LAS bf16x8*)(lds + PG8_SA(b, h) + aoff + m * 2048 + k * 1024); } while (0)
; #define PG8_MMA(ai, bj, At, Bt) do { __builtin_amdgcn_s_setprio(3); _Pragma("unroll") for (int m = 0; m < 4; ++m) _Pragma("unroll") for (int n = 0; n < 2; ++n) _Pragma("unroll") for (int k = 0; k < 2; ++k) \
;         acc[ai][bj][m][n] = __builtin_amdgcn_mfma_f32_16x16x32_bf16(Bt[n][k], At[m][k], acc[ai][bj][m][n], 0, 0, 0); __builtin_amdgcn_s_setprio(0); } while (0)
; #define PG8_WAIT_V(n) asm volatile("s_waitcnt vmcnt(" #n ")" ::: "memory")
; #define PG8_WAIT_L(n) asm volatile("s_waitcnt lgkmcnt(" #n ")" ::: "memory")
; #define PG8_BAR __builtin_amdgcn_s_barrier()
; #define PG8_SCHED __builtin_amdgcn_sched_barrier(0)
; template <class Epi, class Sched>
; __device__ __forceinline__ void gemm_phase(LAS unsigned char* lds, const Gemm g, const Sched& S, const Epi& E, int tid_in) {
;     ...
;             PG8_LDA(At, 1, 1); PG8_STAGE(PG8_SB(1, 0), b3, voffB); PG8_STAGE(PG8_SB(1, 1), b3 + hstep, voffB);
;             PG8_WAIT_V(6); PG8_WAIT_L(0); PG8_BAR; PG8_MMA(1, 0, At, B0); PG8_MMA(1, 1, At, B1); PG8_BAR; PG8_SCHED;
;         }
;         if (wr == 0) PG8_BAR;
	s_setprio 3
	v_mfma_f32_16x16x32_bf16 v[124:127], v[132:135], v[180:183], v[124:127]
	v_mfma_f32_16x16x32_bf16 v[120:123], v[140:143], v[180:183], v[120:123]
	v_mfma_f32_16x16x32_bf16 v[116:119], v[132:135], v[196:199], v[116:119]
	v_mfma_f32_16x16x32_bf16 v[112:115], v[140:143], v[196:199], v[112:115]
	v_mfma_f32_16x16x32_bf16 v[108:111], v[132:135], v[204:207], v[108:111]
	v_mfma_f32_16x16x32_bf16 v[104:107], v[140:143], v[204:207], v[104:107]
	v_mfma_f32_16x16x32_bf16 v[100:103], v[132:135], v[212:215], v[100:103]
	v_mfma_f32_16x16x32_bf16 v[96:99], v[140:143], v[212:215], v[96:99]
	v_mfma_f32_16x16x32_bf16 v[124:127], v[136:139], v[192:195], v[124:127]
	v_mfma_f32_16x16x32_bf16 v[120:123], v[144:147], v[192:195], v[120:123]
	v_mfma_f32_16x16x32_bf16 v[116:119], v[136:139], v[200:203], v[116:119]
	v_mfma_f32_16x16x32_bf16 v[112:115], v[144:147], v[200:203], v[112:115]
	v_mfma_f32_16x16x32_bf16 v[108:111], v[136:139], v[208:211], v[108:111]
	v_mfma_f32_16x16x32_bf16 v[104:107], v[144:147], v[208:211], v[104:107]
	v_mfma_f32_16x16x32_bf16 v[100:103], v[136:139], v[216:219], v[100:103]
	v_mfma_f32_16x16x32_bf16 v[96:99], v[144:147], v[216:219], v[96:99]
	s_setprio 0
	s_setprio 3
	v_mfma_f32_16x16x32_bf16 v[92:95], v[148:151], v[180:183], v[92:95]
	v_mfma_f32_16x16x32_bf16 v[88:91], v[172:175], v[180:183], v[88:91]
	v_mfma_f32_16x16x32_bf16 v[84:87], v[148:151], v[196:199], v[84:87]
	v_mfma_f32_16x16x32_bf16 v[80:83], v[172:175], v[196:199], v[80:83]
	v_mfma_f32_16x16x32_bf16 v[76:79], v[148:151], v[204:207], v[76:79]
	v_mfma_f32_16x16x32_bf16 v[72:75], v[172:175], v[204:207], v[72:75]
	v_mfma_f32_16x16x32_bf16 v[68:71], v[148:151], v[212:215], v[68:71]
	v_mfma_f32_16x16x32_bf16 v[64:67], v[172:175], v[212:215], v[64:67]
	v_mfma_f32_16x16x32_bf16 v[92:95], v[152:155], v[192:195], v[92:95]
	v_mfma_f32_16x16x32_bf16 v[88:91], v[176:179], v[192:195], v[88:91]
	v_mfma_f32_16x16x32_bf16 v[84:87], v[152:155], v[200:203], v[84:87]
	v_mfma_f32_16x16x32_bf16 v[80:83], v[176:179], v[200:203], v[80:83]
	v_mfma_f32_16x16x32_bf16 v[76:79], v[152:155], v[208:211], v[76:79]
	v_mfma_f32_16x16x32_bf16 v[72:75], v[176:179], v[208:211], v[72:75]
	v_mfma_f32_16x16x32_bf16 v[68:71], v[152:155], v[216:219], v[68:71]
	v_mfma_f32_16x16x32_bf16 v[64:67], v[176:179], v[216:219], v[64:67]
	s_setprio 0
	s_barrier
	s_add_i32 s44, s80, s2
	v_lshl_add_u64 v[184:185], v[184:185], 0, s[14:15]
	s_mov_b32 m0, s44
	ds_read_b128 v[180:183], v190 offset:49152
	ds_read_b128 v[192:195], v190 offset:50176
	ds_read_b128 v[196:199], v190 offset:51200
	ds_read_b128 v[200:203], v190 offset:52224
	ds_read_b128 v[204:207], v190 offset:53248
	ds_read_b128 v[208:211], v190 offset:54272
	ds_read_b128 v[212:215], v190 offset:55296
	ds_read_b128 v[216:219], v190 offset:56320
	global_load_lds_dwordx4 v[184:185], off
	s_add_i32 m0, s44, 0x2000
	s_add_u32 s42, s42, 0x80080
	v_lshl_add_u64 v[184:185], v[220:221], 0, s[14:15]
	s_addc_u32 s43, s43, 0
	s_add_i32 s44, s81, s2
	global_load_lds_dwordx4 v[184:185], off
	v_lshl_add_u64 v[184:185], s[42:43], 0, v[158:159]
	s_mov_b32 m0, s44
	s_nop 0
	global_load_lds_dwordx4 v[184:185], off
	v_lshl_add_u64 v[184:185], s[42:43], 0, v[162:163]
	s_add_i32 m0, s44, 0x2000
	s_nop 0
	global_load_lds_dwordx4 v[184:185], off
	s_waitcnt vmcnt(6) lgkmcnt(0)
	s_barrier
	s_setprio 3
	v_mfma_f32_16x16x32_bf16 v[60:63], v[132:135], v[180:183], v[60:63]
	v_mfma_f32_16x16x32_bf16 v[56:59], v[140:143], v[180:183], v[56:59]
	v_mfma_f32_16x16x32_bf16 v[52:55], v[132:135], v[196:199], v[52:55]
	v_mfma_f32_16x16x32_bf16 v[48:51], v[140:143], v[196:199], v[48:51]
	v_mfma_f32_16x16x32_bf16 v[44:47], v[132:135], v[204:207], v[44:47]
	v_mfma_f32_16x16x32_bf16 v[40:43], v[140:143], v[204:207], v[40:43]
	v_mfma_f32_16x16x32_bf16 v[36:39], v[132:135], v[212:215], v[36:39]
	v_mfma_f32_16x16x32_bf16 v[32:35], v[140:143], v[212:215], v[32:35]
	v_mfma_f32_16x16x32_bf16 v[60:63], v[136:139], v[192:195], v[60:63]
	v_mfma_f32_16x16x32_bf16 v[56:59], v[144:147], v[192:195], v[56:59]
	v_mfma_f32_16x16x32_bf16 v[52:55], v[136:139], v[200:203], v[52:55]
	v_mfma_f32_16x16x32_bf16 v[48:51], v[144:147], v[200:203], v[48:51]
	v_mfma_f32_16x16x32_bf16 v[44:47], v[136:139], v[208:211], v[44:47]
	v_mfma_f32_16x16x32_bf16 v[40:43], v[144:147], v[208:211], v[40:43]
	v_mfma_f32_16x16x32_bf16 v[36:39], v[136:139], v[216:219], v[36:39]
	v_mfma_f32_16x16x32_bf16 v[32:35], v[144:147], v[216:219], v[32:35]
	s_setprio 0
	s_setprio 3
	v_mfma_f32_16x16x32_bf16 v[28:31], v[148:151], v[180:183], v[28:31]
	v_mfma_f32_16x16x32_bf16 v[24:27], v[172:175], v[180:183], v[24:27]
	v_mfma_f32_16x16x32_bf16 v[20:23], v[148:151], v[196:199], v[20:23]
	v_mfma_f32_16x16x32_bf16 v[16:19], v[172:175], v[196:199], v[16:19]
	v_mfma_f32_16x16x32_bf16 v[12:15], v[148:151], v[204:207], v[12:15]
	v_mfma_f32_16x16x32_bf16 v[8:11], v[172:175], v[204:207], v[8:11]
	v_mfma_f32_16x16x32_bf16 v[4:7], v[148:151], v[212:215], v[4:7]
	v_mfma_f32_16x16x32_bf16 v[0:3], v[172:175], v[212:215], v[0:3]
	v_mfma_f32_16x16x32_bf16 v[28:31], v[152:155], v[192:195], v[28:31]
	v_mfma_f32_16x16x32_bf16 v[24:27], v[176:179], v[192:195], v[24:27]
	v_mfma_f32_16x16x32_bf16 v[20:23], v[152:155], v[200:203], v[20:23]
	v_mfma_f32_16x16x32_bf16 v[16:19], v[176:179], v[200:203], v[16:19]
	v_mfma_f32_16x16x32_bf16 v[12:15], v[152:155], v[208:211], v[12:15]
	v_mfma_f32_16x16x32_bf16 v[8:11], v[176:179], v[208:211], v[8:11]
	v_mfma_f32_16x16x32_bf16 v[4:7], v[152:155], v[216:219], v[4:7]
	v_mfma_f32_16x16x32_bf16 v[0:3], v[176:179], v[216:219], v[0:3]
	s_setprio 0
	s_barrier
	s_add_i32 s79, s79, 2
	s_add_u32 s40, s40, 0x100
	s_addc_u32 s41, s41, 0
	s_cmp_gt_u32 s79, 13
	s_cbranch_scc0 .LBB0_511
	s_and_b64 vcc, exec, s[18:19]
	s_cbranch_vccz .LBB0_514
	s_barrier

;     __device__ bool next(int i, Unit& u) const { if (!b.next(i >> 1, u)) return false; u.half = i & 1; u.koff = (i & 1) * kbytes; return true; }
; #define PG8_STAGE(bufoff, gbase, voff) do { _Pragma("unroll") for (int _i = 0; _i < 2; ++_i) \
;         __builtin_amdgcn_global_load_lds((const unsigned*)((const char*)(gbase) + (voff)[_i]), (LAS unsigned*)(lds + (bufoff) + ldsw + _i * 8192), 16, 0, 0); } while (0)
; #define PG8_LDA(dst, b, h) do { _Pragma("unroll") for (int m = 0; m < 4; ++m) _Pragma("unroll") for (int k = 0; k < 2; ++k) dst[m][k] = *(const LAS bf16x8*)(lds + PG8_SA(b, h) + aoff + m * 2048 + k * 1024); } while (0)
; #define PG8_LDB(dst, b, h) do { _Pragma("unroll") for (int n = 0; n < 2; ++n) _Pragma("unroll") for (int k = 0; k < 2; ++k) dst[n][k] = *(const LAS bf16x8*)(lds + PG8_SB(b, h) + boff + n * 2048 + k * 1024); } while (0)
; #define PG8_WAIT_V(n) asm volatile("s_waitcnt vmcnt(" #n ")" ::: "memory")
; #define PG8_WAIT_L(n) asm volatile("s_waitcnt lgkmcnt(" #n ")" ::: "memory")
; #define PG8_BAR __builtin_amdgcn_s_barrier()
; #define PG8_SCHED __builtin_amdgcn_sched_barrier(0)
; template <class Epi, class Sched>
; __device__ __forceinline__ void gemm_phase(LAS unsigned char* lds, const Gemm g, const Sched& S, const Epi& E, int tid_in) {
;     ...
;         const bool has_next = S.next(ui + 1, nxt);
;         const char* nA = has_next ? (const char*)g.A + (size_t)nxt.pm * tstep + nxt.koff : cA; const char* nB = has_next ? (const char*)g.Bt + (size_t)nxt.pn * tstep + nxt.koff : cB;
;         for (int t = 0; t < nt; t += 2) {
;             const bool last = (t == nt - 2);
;             const char* a1 = cA + (size_t)(t + 1) * kstep;
;             const char* a2 = last ? nA : cA + (size_t)(t + 2) * kstep; const char* b2 = last ? nB : cB + (size_t)(t + 2) * kstep;
;             const char* a3 = a2 + kstep; const char* b3 = b2 + kstep;
;             PG8_LDB(B0, 0, 0); PG8_LDB(B1, 0, 1); PG8_SCHED; PG8_LDA(At, 0, 0); PG8_STAGE(PG8_SA(1, 0), a1, voffA); PG8_STAGE(PG8_SA(1, 1), a1 + hstep, voffA);
;             PG8_WAIT_V(8); PG8_WAIT_L(0); PG8_BAR; PG8_MMA(0, 0, At, B0); PG8_MMA(0, 1, At, B1); PG8_BAR; PG8_SCHED;
;             PG8_LDA(At, 0, 1); PG8_STAGE(PG8_SB(0, 0), b2, voffB); PG8_STAGE(PG8_SB(0, 1), b2 + hstep, voffB);
;             PG8_WAIT_V(6); PG8_WAIT_L(0); PG8_BAR; PG8_MMA(1, 0, At, B0); PG8_MMA(1, 1, At, B1); PG8_BAR; PG8_SCHED;
.LBB0_619:
	s_ashr_i32 s25, s24, 31
	s_lshl_b64 s[26:27], s[24:25], 20
	s_add_u32 s26, s8, s26
	s_addc_u32 s27, s9, s27
	s_and_b64 s[28:29], s[4:5], exec
	s_cselect_b32 s25, s27, s35
	s_cselect_b32 s31, s26, s34
	s_ashr_i32 s23, s22, 31
	s_lshl_b64 s[28:29], s[22:23], 20
	s_add_u32 s28, s68, s28
	s_addc_u32 s29, s69, s29
	s_and_b64 s[38:39], s[4:5], exec
	s_cselect_b32 s23, s29, s37
	s_cselect_b32 s49, s28, s36
	s_add_u32 s51, s36, 0x100
	s_addc_u32 s70, s37, 0
	v_lshl_add_u64 v[144:145], s[34:35], 0, v[136:137]
	v_lshl_add_u64 v[146:147], s[34:35], 0, v[138:139]
	s_mov_b32 s71, -2
	s_mov_b64 s[36:37], 0
	s_waitcnt lgkmcnt(0)
	ds_read_b128 v[156:159], v151
	ds_read_b128 v[160:163], v151 offset:1024
	ds_read_b128 v[164:167], v151 offset:2048
	ds_read_b128 v[168:171], v151 offset:3072
	ds_read_b128 v[172:175], v152
	ds_read_b128 v[176:179], v152 offset:1024
	ds_read_b128 v[180:183], v152 offset:2048
	ds_read_b128 v[188:191], v152 offset:3072
	s_add_u32 s38, s34, s36
	s_addc_u32 s39, s35, s37
	s_add_u32 s40, s38, 0x100
	s_addc_u32 s41, s39, 0
	s_add_u32 s38, s51, s36
	s_addc_u32 s39, s70, s37
	s_cmpk_eq_i32 s36, 0xf00
	s_cselect_b32 s39, s23, s39
	s_cselect_b32 s38, s49, s38
	s_cselect_b32 s41, s25, s41
	s_cselect_b32 s40, s31, s40
	v_lshl_add_u64 v[184:185], v[144:145], 0, s[36:37]
	v_lshl_add_u64 v[224:225], v[184:185], 0, s[16:17]
	s_add_i32 m0, s3, 0x8000
	ds_read_b128 v[192:195], v153
	ds_read_b128 v[196:199], v153 offset:1024
	ds_read_b128 v[200:203], v153 offset:2048
	ds_read_b128 v[204:207], v153 offset:3072
	ds_read_b128 v[208:211], v153 offset:4096
	ds_read_b128 v[212:215], v153 offset:5120
	ds_read_b128 v[216:219], v153 offset:6144
	ds_read_b128 v[220:223], v153 offset:7168
	global_load_lds_dwordx4 v[224:225], off
	v_lshl_add_u64 v[224:225], v[146:147], 0, s[36:37]
	v_lshl_add_u64 v[226:227], v[224:225], 0, s[16:17]
	s_add_i32 m0, s3, 0xa000
	v_lshl_add_u64 v[184:185], v[184:185], 0, s[18:19]
	global_load_lds_dwordx4 v[226:227], off
	s_add_i32 m0, s3, 0xc000
	s_nop 0
	global_load_lds_dwordx4 v[184:185], off
	v_lshl_add_u64 v[184:185], v[224:225], 0, s[18:19]
	s_add_i32 m0, s3, 0xe000
	s_nop 0
	global_load_lds_dwordx4 v[184:185], off
	s_waitcnt vmcnt(8) lgkmcnt(0)
	s_barrier
	s_setprio 3
	v_mfma_f32_16x16x32_bf16 v[124:127], v[156:159], v[192:195], 0
	v_mfma_f32_16x16x32_bf16 v[120:123], v[164:167], v[192:195], 0
	v_mfma_f32_16x16x32_bf16 v[108:111], v[156:159], v[200:203], 0
	v_mfma_f32_16x16x32_bf16 v[104:107], v[164:167], v[200:203], 0
	v_mfma_f32_16x16x32_bf16 v[92:95], v[156:159], v[208:211], 0
	v_mfma_f32_16x16x32_bf16 v[88:91], v[164:167], v[208:211], 0
	v_mfma_f32_16x16x32_bf16 v[76:79], v[156:159], v[216:219], 0
	v_mfma_f32_16x16x32_bf16 v[72:75], v[164:167], v[216:219], 0
	v_mfma_f32_16x16x32_bf16 v[124:127], v[160:163], v[196:199], v[124:127]
	v_mfma_f32_16x16x32_bf16 v[120:123], v[168:171], v[196:199], v[120:123]
	v_mfma_f32_16x16x32_bf16 v[108:111], v[160:163], v[204:207], v[108:111]
	v_mfma_f32_16x16x32_bf16 v[104:107], v[168:171], v[204:207], v[104:107]
	v_mfma_f32_16x16x32_bf16 v[92:95], v[160:163], v[212:215], v[92:95]
	v_mfma_f32_16x16x32_bf16 v[88:91], v[168:171], v[212:215], v[88:91]
	v_mfma_f32_16x16x32_bf16 v[76:79], v[160:163], v[220:223], v[76:79]
	v_mfma_f32_16x16x32_bf16 v[72:75], v[168:171], v[220:223], v[72:75]
	s_setprio 0
	s_setprio 3
	v_mfma_f32_16x16x32_bf16 v[116:119], v[172:175], v[192:195], 0
	v_mfma_f32_16x16x32_bf16 v[112:115], v[180:183], v[192:195], 0
	v_mfma_f32_16x16x32_bf16 v[100:103], v[172:175], v[200:203], 0
	v_mfma_f32_16x16x32_bf16 v[96:99], v[180:183], v[200:203], 0
	v_mfma_f32_16x16x32_bf16 v[84:87], v[172:175], v[208:211], 0
	v_mfma_f32_16x16x32_bf16 v[80:83], v[180:183], v[208:211], 0
	v_mfma_f32_16x16x32_bf16 v[68:71], v[172:175], v[216:219], 0
	v_mfma_f32_16x16x32_bf16 v[64:67], v[180:183], v[216:219], 0
	v_mfma_f32_16x16x32_bf16 v[116:119], v[176:179], v[196:199], v[116:119]
	v_mfma_f32_16x16x32_bf16 v[112:115], v[188:191], v[196:199], v[112:115]
	v_mfma_f32_16x16x32_bf16 v[100:103], v[176:179], v[204:207], v[100:103]
	v_mfma_f32_16x16x32_bf16 v[96:99], v[188:191], v[204:207], v[96:99]
	v_mfma_f32_16x16x32_bf16 v[84:87], v[176:179], v[212:215], v[84:87]
	v_mfma_f32_16x16x32_bf16 v[80:83], v[188:191], v[212:215], v[80:83]
	v_mfma_f32_16x16x32_bf16 v[68:71], v[176:179], v[220:223], v[68:71]
	v_mfma_f32_16x16x32_bf16 v[64:67], v[188:191], v[220:223], v[64:67]
	s_setprio 0
	s_barrier
	s_add_i32 s72, s46, s2
	v_lshl_add_u64 v[184:185], s[38:39], 0, v[130:131]
	s_mov_b32 m0, s72
	ds_read_b128 v[192:195], v153 offset:16384
	ds_read_b128 v[196:199], v153 offset:17408
	ds_read_b128 v[200:203], v153 offset:18432
	ds_read_b128 v[204:207], v153 offset:19456
	ds_read_b128 v[208:211], v153 offset:20480
	ds_read_b128 v[212:215], v153 offset:21504
	ds_read_b128 v[216:219], v153 offset:22528
	ds_read_b128 v[220:223], v153 offset:23552
	global_load_lds_dwordx4 v[184:185], off
	s_add_i32 m0, s72, 0x2000
	s_add_u32 s72, s38, 0x80000
	v_lshl_add_u64 v[224:225], s[38:39], 0, v[134:135]
	s_addc_u32 s73, s39, 0
	s_add_i32 s74, s47, s2
	global_load_lds_dwordx4 v[224:225], off
	v_lshl_add_u64 v[226:227], s[72:73], 0, v[130:131]
	s_mov_b32 m0, s74
	s_nop 0
	global_load_lds_dwordx4 v[226:227], off
	v_lshl_add_u64 v[226:227], s[72:73], 0, v[134:135]
	s_add_i32 m0, s74, 0x2000
	s_nop 0
	global_load_lds_dwordx4 v[226:227], off
	s_waitcnt vmcnt(6) lgkmcnt(0)
	s_barrier
; #define PG8_STAGE(bufoff, gbase, voff) do { _Pragma("unroll") for (int _i = 0; _i < 2; ++_i) \
;         __builtin_amdgcn_global_load_lds((const unsigned*)((const char*)(gbase) + (voff)[_i]), (LAS unsigned*)(lds + (bufoff) + ldsw + _i * 8192), 16, 0, 0); } while (0)
; #define PG8_LDA(dst, b, h) do { _Pragma("unroll") for (int m = 0; m < 4; ++m) _Pragma("unroll") for (int k = 0; k < 2; ++k) dst[m][k] = *(const LAS bf16x8*)(lds + PG8_SA(b, h) + aoff + m * 2048 + k * 1024); } while (0)
; #define PG8_LDB(dst, b, h) do { _Pragma("unroll") for (int n = 0; n < 2; ++n) _Pragma("unroll") for (int k = 0; k < 2; ++k) dst[n][k] = *(const LAS bf16x8*)(lds + PG8_SB(b, h) + boff + n * 2048 + k * 1024); } while (0)
; #define PG8_MMA(ai, bj, At, Bt) do { __builtin_amdgcn_s_setprio(3); _Pragma("unroll") for (int m = 0; m < 4; ++m) _Pragma("unroll") for (int n = 0; n < 2; ++n) _Pragma("unroll") for (int k = 0; k < 2; ++k) \
;         acc[ai][bj][m][n] = __builtin_amdgcn_mfma_f32_16x16x32_bf16(Bt[n][k], At[m][k], acc[ai][bj][m][n], 0, 0, 0); __builtin_amdgcn_s_setprio(0); } while (0)
; #define PG8_WAIT_V(n) asm volatile("s_waitcnt vmcnt(" #n ")" ::: "memory")
; #define PG8_WAIT_L(n) asm volatile("s_waitcnt lgkmcnt(" #n ")" ::: "memory")
; #define PG8_BAR __builtin_amdgcn_s_barrier()
; #define PG8_SCHED __builtin_amdgcn_sched_barrier(0)
; template <class Epi, class Sched>
; __device__ __forceinline__ void gemm_phase(LAS unsigned char* lds, const Gemm g, const Sched& S, const Epi& E, int tid_in) {
;     ...
;             PG8_WAIT_V(6); PG8_WAIT_L(0); PG8_BAR; PG8_MMA(1, 0, At, B0); PG8_MMA(1, 1, At, B1); PG8_BAR; PG8_SCHED;
;             PG8_LDB(B0, 1, 0); PG8_LDB(B1, 1, 1); PG8_SCHED; PG8_LDA(At, 1, 0); PG8_STAGE(PG8_SA(0, 0), a2, voffA); PG8_STAGE(PG8_SA(0, 1), a2 + hstep, voffA);
;             PG8_WAIT_V(8); PG8_WAIT_L(0); PG8_BAR; PG8_MMA(0, 0, At, B0); PG8_MMA(0, 1, At, B1); PG8_BAR; PG8_SCHED;
	s_setprio 3
	v_mfma_f32_16x16x32_bf16 v[60:63], v[156:159], v[192:195], 0
	v_mfma_f32_16x16x32_bf16 v[56:59], v[164:167], v[192:195], 0
	v_mfma_f32_16x16x32_bf16 v[44:47], v[156:159], v[200:203], 0
	v_mfma_f32_16x16x32_bf16 v[40:43], v[164:167], v[200:203], 0
	v_mfma_f32_16x16x32_bf16 v[28:31], v[156:159], v[208:211], 0
	v_mfma_f32_16x16x32_bf16 v[24:27], v[164:167], v[208:211], 0
	v_mfma_f32_16x16x32_bf16 v[12:15], v[156:159], v[216:219], 0
	v_mfma_f32_16x16x32_bf16 v[8:11], v[164:167], v[216:219], 0
	v_mfma_f32_16x16x32_bf16 v[60:63], v[160:163], v[196:199], v[60:63]
	v_mfma_f32_16x16x32_bf16 v[56:59], v[168:171], v[196:199], v[56:59]
	v_mfma_f32_16x16x32_bf16 v[44:47], v[160:163], v[204:207], v[44:47]
	v_mfma_f32_16x16x32_bf16 v[40:43], v[168:171], v[204:207], v[40:43]
	v_mfma_f32_16x16x32_bf16 v[28:31], v[160:163], v[212:215], v[28:31]
	v_mfma_f32_16x16x32_bf16 v[24:27], v[168:171], v[212:215], v[24:27]
	v_mfma_f32_16x16x32_bf16 v[12:15], v[160:163], v[220:223], v[12:15]
	v_mfma_f32_16x16x32_bf16 v[8:11], v[168:171], v[220:223], v[8:11]
	s_setprio 0
	s_setprio 3
	v_mfma_f32_16x16x32_bf16 v[52:55], v[172:175], v[192:195], 0
	v_mfma_f32_16x16x32_bf16 v[48:51], v[180:183], v[192:195], 0
	v_mfma_f32_16x16x32_bf16 v[36:39], v[172:175], v[200:203], 0
	v_mfma_f32_16x16x32_bf16 v[32:35], v[180:183], v[200:203], 0
	v_mfma_f32_16x16x32_bf16 v[20:23], v[172:175], v[208:211], 0
	v_mfma_f32_16x16x32_bf16 v[16:19], v[180:183], v[208:211], 0
	v_mfma_f32_16x16x32_bf16 v[4:7], v[172:175], v[216:219], 0
	v_mfma_f32_16x16x32_bf16 v[0:3], v[180:183], v[216:219], 0
	v_mfma_f32_16x16x32_bf16 v[52:55], v[176:179], v[196:199], v[52:55]
	v_mfma_f32_16x16x32_bf16 v[48:51], v[188:191], v[196:199], v[48:51]
	v_mfma_f32_16x16x32_bf16 v[36:39], v[176:179], v[204:207], v[36:39]
	v_mfma_f32_16x16x32_bf16 v[32:35], v[188:191], v[204:207], v[32:35]
	v_mfma_f32_16x16x32_bf16 v[20:23], v[176:179], v[212:215], v[20:23]
	v_mfma_f32_16x16x32_bf16 v[16:19], v[188:191], v[212:215], v[16:19]
	v_mfma_f32_16x16x32_bf16 v[4:7], v[176:179], v[220:223], v[4:7]
	v_mfma_f32_16x16x32_bf16 v[0:3], v[188:191], v[220:223], v[0:3]
	s_setprio 0
	s_barrier
	s_add_i32 s72, 0, 0x18000
	v_add_u32_e32 v155, s72, v149
	s_add_i32 s73, 0, 0x1c000
	ds_read_b128 v[156:159], v155
	ds_read_b128 v[160:163], v155 offset:1024
	ds_read_b128 v[164:167], v155 offset:2048
	ds_read_b128 v[168:171], v155 offset:3072
	v_add_u32_e32 v155, s73, v149
	ds_read_b128 v[172:175], v155
	ds_read_b128 v[176:179], v155 offset:1024
	ds_read_b128 v[180:183], v155 offset:2048
	ds_read_b128 v[188:191], v155 offset:3072
	s_mov_b32 m0, s3
	v_lshl_add_u64 v[226:227], s[40:41], 0, v[128:129]
	ds_read_b128 v[192:195], v153 offset:32768
	ds_read_b128 v[196:199], v153 offset:33792
	ds_read_b128 v[200:203], v153 offset:34816
	ds_read_b128 v[204:207], v153 offset:35840
	ds_read_b128 v[208:211], v153 offset:36864
	ds_read_b128 v[212:215], v153 offset:37888
	ds_read_b128 v[216:219], v153 offset:38912
	ds_read_b128 v[220:223], v153 offset:39936
	global_load_lds_dwordx4 v[226:227], off
	v_lshl_add_u64 v[226:227], s[40:41], 0, v[132:133]
	s_add_u32 s40, s40, 0x80000
	s_mov_b32 m0, s42
	s_addc_u32 s41, s41, 0
	global_load_lds_dwordx4 v[226:227], off
	v_lshl_add_u64 v[226:227], s[40:41], 0, v[128:129]
	s_mov_b32 m0, s43
	s_nop 0
	global_load_lds_dwordx4 v[226:227], off
	v_lshl_add_u64 v[226:227], s[40:41], 0, v[132:133]
	s_mov_b32 m0, s44
	s_nop 0
	global_load_lds_dwordx4 v[226:227], off
	s_waitcnt vmcnt(8) lgkmcnt(0)
	s_barrier
	s_setprio 3
	v_mfma_f32_16x16x32_bf16 v[124:127], v[156:159], v[192:195], v[124:127]
	v_mfma_f32_16x16x32_bf16 v[120:123], v[164:167], v[192:195], v[120:123]
	v_mfma_f32_16x16x32_bf16 v[108:111], v[156:159], v[200:203], v[108:111]
	v_mfma_f32_16x16x32_bf16 v[104:107], v[164:167], v[200:203], v[104:107]
	v_mfma_f32_16x16x32_bf16 v[92:95], v[156:159], v[208:211], v[92:95]
	v_mfma_f32_16x16x32_bf16 v[88:91], v[164:167], v[208:211], v[88:91]
	v_mfma_f32_16x16x32_bf16 v[76:79], v[156:159], v[216:219], v[76:79]
	v_mfma_f32_16x16x32_bf16 v[72:75], v[164:167], v[216:219], v[72:75]
	v_mfma_f32_16x16x32_bf16 v[124:127], v[160:163], v[196:199], v[124:127]
	v_mfma_f32_16x16x32_bf16 v[120:123], v[168:171], v[196:199], v[120:123]
	v_mfma_f32_16x16x32_bf16 v[108:111], v[160:163], v[204:207], v[108:111]
	v_mfma_f32_16x16x32_bf16 v[104:107], v[168:171], v[204:207], v[104:107]
	v_mfma_f32_16x16x32_bf16 v[92:95], v[160:163], v[212:215], v[92:95]
	v_mfma_f32_16x16x32_bf16 v[88:91], v[168:171], v[212:215], v[88:91]
	v_mfma_f32_16x16x32_bf16 v[76:79], v[160:163], v[220:223], v[76:79]
	v_mfma_f32_16x16x32_bf16 v[72:75], v[168:171], v[220:223], v[72:75]
	s_setprio 0
	s_setprio 3
	v_mfma_f32_16x16x32_bf16 v[116:119], v[172:175], v[192:195], v[116:119]
	v_mfma_f32_16x16x32_bf16 v[112:115], v[180:183], v[192:195], v[112:115]
	v_mfma_f32_16x16x32_bf16 v[100:103], v[172:175], v[200:203], v[100:103]
	v_mfma_f32_16x16x32_bf16 v[96:99], v[180:183], v[200:203], v[96:99]
	v_mfma_f32_16x16x32_bf16 v[84:87], v[172:175], v[208:211], v[84:87]
	v_mfma_f32_16x16x32_bf16 v[80:83], v[180:183], v[208:211], v[80:83]
	v_mfma_f32_16x16x32_bf16 v[68:71], v[172:175], v[216:219], v[68:71]
	v_mfma_f32_16x16x32_bf16 v[64:67], v[180:183], v[216:219], v[64:67]
	v_mfma_f32_16x16x32_bf16 v[116:119], v[176:179], v[196:199], v[116:119]
	v_mfma_f32_16x16x32_bf16 v[112:115], v[188:191], v[196:199], v[112:115]
	v_mfma_f32_16x16x32_bf16 v[100:103], v[176:179], v[204:207], v[100:103]
	v_mfma_f32_16x16x32_bf16 v[96:99], v[188:191], v[204:207], v[96:99]
	v_mfma_f32_16x16x32_bf16 v[84:87], v[176:179], v[212:215], v[84:87]
	v_mfma_f32_16x16x32_bf16 v[80:83], v[188:191], v[212:215], v[80:83]
	v_mfma_f32_16x16x32_bf16 v[68:71], v[176:179], v[220:223], v[68:71]
	v_mfma_f32_16x16x32_bf16 v[64:67], v[188:191], v[220:223], v[64:67]
	s_setprio 0
	s_barrier
; #define PG8_STAGE(bufoff, gbase, voff) do { _Pragma("unroll") for (int _i = 0; _i < 2; ++_i) \
;         __builtin_amdgcn_global_load_lds((const unsigned*)((const char*)(gbase) + (voff)[_i]), (LAS unsigned*)(lds + (bufoff) + ldsw + _i * 8192), 16, 0, 0); } while (0)
; #define PG8_LDA(dst, b, h) do { _Pragma("unroll") for (int m = 0; m < 4; ++m) _Pragma("unroll") for (int k = 0; k < 2; ++k) dst[m][k] = *(const LAS bf16x8*)(lds + PG8_SA(b, h) + aoff + m * 2048 + k * 1024); } while (0)
; #define PG8_LDB(dst, b, h) do { _Pragma("unroll") for (int n = 0; n < 2; ++n) _Pragma("unroll") for (int k = 0; k < 2; ++k) dst[n][k] = *(const LAS bf16x8*)(lds + PG8_SB(b, h) + boff + n * 2048 + k * 1024); } while (0)
; #define PG8_MMA(ai, bj, At, Bt) do { __builtin_amdgcn_s_setprio(3); _Pragma("unroll") for (int m = 0; m < 4; ++m) _Pragma("unroll") for (int n = 0; n < 2; ++n) _Pragma("unroll") for (int k = 0; k < 2; ++k) \
;         acc[ai][bj][m][n] = __builtin_amdgcn_mfma_f32_16x16x32_bf16(Bt[n][k], At[m][k], acc[ai][bj][m][n], 0, 0, 0); __builtin_amdgcn_s_setprio(0); } while (0)
; #define PG8_WAIT_V(n) asm volatile("s_waitcnt vmcnt(" #n ")" ::: "memory")
; #define PG8_WAIT_L(n) asm volatile("s_waitcnt lgkmcnt(" #n ")" ::: "memory")
; #define PG8_BAR __builtin_amdgcn_s_barrier()
; #define PG8_SCHED __builtin_amdgcn_sched_barrier(0)
; template <class Epi, class Sched>
; __device__ __forceinline__ void gemm_phase(LAS unsigned char* lds, const Gemm g, const Sched& S, const Epi& E, int tid_in) {
;     ...
;         for (int t = 0; t < nt; t += 2) {
;             const bool last = (t == nt - 2);
;             const char* a1 = cA + (size_t)(t + 1) * kstep;
;             const char* a2 = last ? nA : cA + (size_t)(t + 2) * kstep; const char* b2 = last ? nB : cB + (size_t)(t + 2) * kstep;
;             const char* a3 = a2 + kstep; const char* b3 = b2 + kstep;
;             PG8_LDB(B0, 0, 0); PG8_LDB(B1, 0, 1); PG8_SCHED; PG8_LDA(At, 0, 0); PG8_STAGE(PG8_SA(1, 0), a1, voffA); PG8_STAGE(PG8_SA(1, 1), a1 + hstep, voffA);
;     ...
;             PG8_LDA(At, 1, 1); PG8_STAGE(PG8_SB(1, 0), b3, voffB); PG8_STAGE(PG8_SB(1, 1), b3 + hstep, voffB);
;             PG8_WAIT_V(6); PG8_WAIT_L(0); PG8_BAR; PG8_MMA(1, 0, At, B0); PG8_MMA(1, 1, At, B1); PG8_BAR; PG8_SCHED;
	s_add_i32 s40, s72, s2
	v_lshl_add_u64 v[184:185], v[184:185], 0, s[16:17]
	s_mov_b32 m0, s40
	ds_read_b128 v[192:195], v153 offset:49152
	ds_read_b128 v[196:199], v153 offset:50176
	ds_read_b128 v[200:203], v153 offset:51200
	ds_read_b128 v[204:207], v153 offset:52224
	ds_read_b128 v[208:211], v153 offset:53248
	ds_read_b128 v[212:215], v153 offset:54272
	ds_read_b128 v[216:219], v153 offset:55296
	ds_read_b128 v[220:223], v153 offset:56320
	global_load_lds_dwordx4 v[184:185], off
	s_add_i32 m0, s40, 0x2000
	s_add_u32 s38, s38, 0x80080
	v_lshl_add_u64 v[184:185], v[224:225], 0, s[16:17]
	s_addc_u32 s39, s39, 0
	s_add_i32 s40, s73, s2
	global_load_lds_dwordx4 v[184:185], off
	v_lshl_add_u64 v[184:185], s[38:39], 0, v[130:131]
	s_mov_b32 m0, s40
	s_nop 0
	global_load_lds_dwordx4 v[184:185], off
	v_lshl_add_u64 v[184:185], s[38:39], 0, v[134:135]
	s_add_i32 m0, s40, 0x2000
	s_nop 0
	global_load_lds_dwordx4 v[184:185], off
	s_waitcnt vmcnt(6) lgkmcnt(0)
	s_barrier
	s_setprio 3
	v_mfma_f32_16x16x32_bf16 v[60:63], v[156:159], v[192:195], v[60:63]
	v_mfma_f32_16x16x32_bf16 v[56:59], v[164:167], v[192:195], v[56:59]
	v_mfma_f32_16x16x32_bf16 v[44:47], v[156:159], v[200:203], v[44:47]
	v_mfma_f32_16x16x32_bf16 v[40:43], v[164:167], v[200:203], v[40:43]
	v_mfma_f32_16x16x32_bf16 v[28:31], v[156:159], v[208:211], v[28:31]
	v_mfma_f32_16x16x32_bf16 v[24:27], v[164:167], v[208:211], v[24:27]
	v_mfma_f32_16x16x32_bf16 v[12:15], v[156:159], v[216:219], v[12:15]
	v_mfma_f32_16x16x32_bf16 v[8:11], v[164:167], v[216:219], v[8:11]
	v_mfma_f32_16x16x32_bf16 v[60:63], v[160:163], v[196:199], v[60:63]
	v_mfma_f32_16x16x32_bf16 v[56:59], v[168:171], v[196:199], v[56:59]
	v_mfma_f32_16x16x32_bf16 v[44:47], v[160:163], v[204:207], v[44:47]
	v_mfma_f32_16x16x32_bf16 v[40:43], v[168:171], v[204:207], v[40:43]
	v_mfma_f32_16x16x32_bf16 v[28:31], v[160:163], v[212:215], v[28:31]
	v_mfma_f32_16x16x32_bf16 v[24:27], v[168:171], v[212:215], v[24:27]
	v_mfma_f32_16x16x32_bf16 v[12:15], v[160:163], v[220:223], v[12:15]
	v_mfma_f32_16x16x32_bf16 v[8:11], v[168:171], v[220:223], v[8:11]
	s_setprio 0
	s_setprio 3
	v_mfma_f32_16x16x32_bf16 v[52:55], v[172:175], v[192:195], v[52:55]
	v_mfma_f32_16x16x32_bf16 v[48:51], v[180:183], v[192:195], v[48:51]
	v_mfma_f32_16x16x32_bf16 v[36:39], v[172:175], v[200:203], v[36:39]
	v_mfma_f32_16x16x32_bf16 v[32:35], v[180:183], v[200:203], v[32:35]
	v_mfma_f32_16x16x32_bf16 v[20:23], v[172:175], v[208:211], v[20:23]
	v_mfma_f32_16x16x32_bf16 v[16:19], v[180:183], v[208:211], v[16:19]
	v_mfma_f32_16x16x32_bf16 v[4:7], v[172:175], v[216:219], v[4:7]
	v_mfma_f32_16x16x32_bf16 v[0:3], v[180:183], v[216:219], v[0:3]
	v_mfma_f32_16x16x32_bf16 v[52:55], v[176:179], v[196:199], v[52:55]
	v_mfma_f32_16x16x32_bf16 v[48:51], v[188:191], v[196:199], v[48:51]
	v_mfma_f32_16x16x32_bf16 v[36:39], v[176:179], v[204:207], v[36:39]
	v_mfma_f32_16x16x32_bf16 v[32:35], v[188:191], v[204:207], v[32:35]
	v_mfma_f32_16x16x32_bf16 v[20:23], v[176:179], v[212:215], v[20:23]
	v_mfma_f32_16x16x32_bf16 v[16:19], v[188:191], v[212:215], v[16:19]
	v_mfma_f32_16x16x32_bf16 v[4:7], v[176:179], v[220:223], v[4:7]
	v_mfma_f32_16x16x32_bf16 v[0:3], v[188:191], v[220:223], v[0:3]
	s_setprio 0
	s_barrier
	s_add_i32 s71, s71, 2
	s_add_u32 s36, s36, 0x100
	s_addc_u32 s37, s37, 0
	s_cmp_gt_u32 s71, 29
	s_cbranch_scc0 .LBB0_620
	s_branch .Lpeel_exit_1
.LBB0_620:
	ds_read_b128 v[156:159], v151
	ds_read_b128 v[160:163], v151 offset:1024
	ds_read_b128 v[164:167], v151 offset:2048
	ds_read_b128 v[168:171], v151 offset:3072
	ds_read_b128 v[172:175], v152
	ds_read_b128 v[176:179], v152 offset:1024
	ds_read_b128 v[180:183], v152 offset:2048
	ds_read_b128 v[188:191], v152 offset:3072
	s_add_u32 s38, s34, s36
	s_addc_u32 s39, s35, s37
	s_add_u32 s40, s38, 0x100
	s_addc_u32 s41, s39, 0
	s_add_u32 s38, s51, s36
	s_addc_u32 s39, s70, s37
	s_cmpk_eq_i32 s36, 0xf00
	s_cselect_b32 s39, s23, s39
	s_cselect_b32 s38, s49, s38
	s_cselect_b32 s41, s25, s41
	s_cselect_b32 s40, s31, s40
	v_lshl_add_u64 v[184:185], v[144:145], 0, s[36:37]
	v_lshl_add_u64 v[224:225], v[184:185], 0, s[16:17]
	s_add_i32 m0, s3, 0x8000
	ds_read_b128 v[192:195], v153
	ds_read_b128 v[196:199], v153 offset:1024
	ds_read_b128 v[200:203], v153 offset:2048
	ds_read_b128 v[204:207], v153 offset:3072
	ds_read_b128 v[208:211], v153 offset:4096
	ds_read_b128 v[212:215], v153 offset:5120
	ds_read_b128 v[216:219], v153 offset:6144
	ds_read_b128 v[220:223], v153 offset:7168
	global_load_lds_dwordx4 v[224:225], off
	v_lshl_add_u64 v[224:225], v[146:147], 0, s[36:37]
	v_lshl_add_u64 v[226:227], v[224:225], 0, s[16:17]
	s_add_i32 m0, s3, 0xa000
	v_lshl_add_u64 v[184:185], v[184:185], 0, s[18:19]
	global_load_lds_dwordx4 v[226:227], off
	s_add_i32 m0, s3, 0xc000
	s_nop 0
	global_load_lds_dwordx4 v[184:185], off
	v_lshl_add_u64 v[184:185], v[224:225], 0, s[18:19]
	s_add_i32 m0, s3, 0xe000
	s_nop 0
	global_load_lds_dwordx4 v[184:185], off
	s_waitcnt vmcnt(8) lgkmcnt(0)
	s_barrier
; #define PG8_STAGE(bufoff, gbase, voff) do { _Pragma("unroll") for (int _i = 0; _i < 2; ++_i) \
;         __builtin_amdgcn_global_load_lds((const unsigned*)((const char*)(gbase) + (voff)[_i]), (LAS unsigned*)(lds + (bufoff) + ldsw + _i * 8192), 16, 0, 0); } while (0)
; #define PG8_LDA(dst, b, h) do { _Pragma("unroll") for (int m = 0; m < 4; ++m) _Pragma("unroll") for (int k = 0; k < 2; ++k) dst[m][k] = *(const LAS bf16x8*)(lds + PG8_SA(b, h) + aoff + m * 2048 + k * 1024); } while (0)
; #define PG8_MMA(ai, bj, At, Bt) do { __builtin_amdgcn_s_setprio(3); _Pragma("unroll") for (int m = 0; m < 4; ++m) _Pragma("unroll") for (int n = 0; n < 2; ++n) _Pragma("unroll") for (int k = 0; k < 2; ++k) \
;         acc[ai][bj][m][n] = __builtin_amdgcn_mfma_f32_16x16x32_bf16(Bt[n][k], At[m][k], acc[ai][bj][m][n], 0, 0, 0); __builtin_amdgcn_s_setprio(0); } while (0)
; #define PG8_WAIT_V(n) asm volatile("s_waitcnt vmcnt(" #n ")" ::: "memory")
; #define PG8_WAIT_L(n) asm volatile("s_waitcnt lgkmcnt(" #n ")" ::: "memory")
; #define PG8_BAR __builtin_amdgcn_s_barrier()
; #define PG8_SCHED __builtin_amdgcn_sched_barrier(0)
; template <class Epi, class Sched>
; __device__ __forceinline__ void gemm_phase(LAS unsigned char* lds, const Gemm g, const Sched& S, const Epi& E, int tid_in) {
;     ...
;             PG8_WAIT_V(8); PG8_WAIT_L(0); PG8_BAR; PG8_MMA(0, 0, At, B0); PG8_MMA(0, 1, At, B1); PG8_BAR; PG8_SCHED;
;             PG8_LDA(At, 0, 1); PG8_STAGE(PG8_SB(0, 0), b2, voffB); PG8_STAGE(PG8_SB(0, 1), b2 + hstep, voffB);
;             PG8_WAIT_V(6); PG8_WAIT_L(0); PG8_BAR; PG8_MMA(1, 0, At, B0); PG8_MMA(1, 1, At, B1); PG8_BAR; PG8_SCHED;
	s_setprio 3
	v_mfma_f32_16x16x32_bf16 v[124:127], v[156:159], v[192:195], v[124:127]
	v_mfma_f32_16x16x32_bf16 v[120:123], v[164:167], v[192:195], v[120:123]
	v_mfma_f32_16x16x32_bf16 v[108:111], v[156:159], v[200:203], v[108:111]
	v_mfma_f32_16x16x32_bf16 v[104:107], v[164:167], v[200:203], v[104:107]
	v_mfma_f32_16x16x32_bf16 v[92:95], v[156:159], v[208:211], v[92:95]
	v_mfma_f32_16x16x32_bf16 v[88:91], v[164:167], v[208:211], v[88:91]
	v_mfma_f32_16x16x32_bf16 v[76:79], v[156:159], v[216:219], v[76:79]
	v_mfma_f32_16x16x32_bf16 v[72:75], v[164:167], v[216:219], v[72:75]
	v_mfma_f32_16x16x32_bf16 v[124:127], v[160:163], v[196:199], v[124:127]
	v_mfma_f32_16x16x32_bf16 v[120:123], v[168:171], v[196:199], v[120:123]
	v_mfma_f32_16x16x32_bf16 v[108:111], v[160:163], v[204:207], v[108:111]
	v_mfma_f32_16x16x32_bf16 v[104:107], v[168:171], v[204:207], v[104:107]
	v_mfma_f32_16x16x32_bf16 v[92:95], v[160:163], v[212:215], v[92:95]
	v_mfma_f32_16x16x32_bf16 v[88:91], v[168:171], v[212:215], v[88:91]
	v_mfma_f32_16x16x32_bf16 v[76:79], v[160:163], v[220:223], v[76:79]
	v_mfma_f32_16x16x32_bf16 v[72:75], v[168:171], v[220:223], v[72:75]
	s_setprio 0
	s_setprio 3
	v_mfma_f32_16x16x32_bf16 v[116:119], v[172:175], v[192:195], v[116:119]
	v_mfma_f32_16x16x32_bf16 v[112:115], v[180:183], v[192:195], v[112:115]
	v_mfma_f32_16x16x32_bf16 v[100:103], v[172:175], v[200:203], v[100:103]
	v_mfma_f32_16x16x32_bf16 v[96:99], v[180:183], v[200:203], v[96:99]
	v_mfma_f32_16x16x32_bf16 v[84:87], v[172:175], v[208:211], v[84:87]
	v_mfma_f32_16x16x32_bf16 v[80:83], v[180:183], v[208:211], v[80:83]
	v_mfma_f32_16x16x32_bf16 v[68:71], v[172:175], v[216:219], v[68:71]
	v_mfma_f32_16x16x32_bf16 v[64:67], v[180:183], v[216:219], v[64:67]
	v_mfma_f32_16x16x32_bf16 v[116:119], v[176:179], v[196:199], v[116:119]
	v_mfma_f32_16x16x32_bf16 v[112:115], v[188:191], v[196:199], v[112:115]
	v_mfma_f32_16x16x32_bf16 v[100:103], v[176:179], v[204:207], v[100:103]
	v_mfma_f32_16x16x32_bf16 v[96:99], v[188:191], v[204:207], v[96:99]
	v_mfma_f32_16x16x32_bf16 v[84:87], v[176:179], v[212:215], v[84:87]
	v_mfma_f32_16x16x32_bf16 v[80:83], v[188:191], v[212:215], v[80:83]
	v_mfma_f32_16x16x32_bf16 v[68:71], v[176:179], v[220:223], v[68:71]
	v_mfma_f32_16x16x32_bf16 v[64:67], v[188:191], v[220:223], v[64:67]
	s_setprio 0
	s_barrier
	s_add_i32 s72, s46, s2
	v_lshl_add_u64 v[184:185], s[38:39], 0, v[130:131]
	s_mov_b32 m0, s72
	ds_read_b128 v[192:195], v153 offset:16384
	ds_read_b128 v[196:199], v153 offset:17408
	ds_read_b128 v[200:203], v153 offset:18432
	ds_read_b128 v[204:207], v153 offset:19456
	ds_read_b128 v[208:211], v153 offset:20480
	ds_read_b128 v[212:215], v153 offset:21504
	ds_read_b128 v[216:219], v153 offset:22528
	ds_read_b128 v[220:223], v153 offset:23552
	global_load_lds_dwordx4 v[184:185], off
	s_add_i32 m0, s72, 0x2000
	s_add_u32 s72, s38, 0x80000
	v_lshl_add_u64 v[224:225], s[38:39], 0, v[134:135]
	s_addc_u32 s73, s39, 0
	s_add_i32 s74, s47, s2
	global_load_lds_dwordx4 v[224:225], off
	v_lshl_add_u64 v[226:227], s[72:73], 0, v[130:131]
	s_mov_b32 m0, s74
	s_nop 0
	global_load_lds_dwordx4 v[226:227], off
	v_lshl_add_u64 v[226:227], s[72:73], 0, v[134:135]
	s_add_i32 m0, s74, 0x2000
	s_nop 0
	global_load_lds_dwordx4 v[226:227], off
	s_waitcnt vmcnt(6) lgkmcnt(0)
	s_barrier
	s_setprio 3
	v_mfma_f32_16x16x32_bf16 v[60:63], v[156:159], v[192:195], v[60:63]
	v_mfma_f32_16x16x32_bf16 v[56:59], v[164:167], v[192:195], v[56:59]
	v_mfma_f32_16x16x32_bf16 v[44:47], v[156:159], v[200:203], v[44:47]
	v_mfma_f32_16x16x32_bf16 v[40:43], v[164:167], v[200:203], v[40:43]
	v_mfma_f32_16x16x32_bf16 v[28:31], v[156:159], v[208:211], v[28:31]
	v_mfma_f32_16x16x32_bf16 v[24:27], v[164:167], v[208:211], v[24:27]
	v_mfma_f32_16x16x32_bf16 v[12:15], v[156:159], v[216:219], v[12:15]
	v_mfma_f32_16x16x32_bf16 v[8:11], v[164:167], v[216:219], v[8:11]
	v_mfma_f32_16x16x32_bf16 v[60:63], v[160:163], v[196:199], v[60:63]
	v_mfma_f32_16x16x32_bf16 v[56:59], v[168:171], v[196:199], v[56:59]
	v_mfma_f32_16x16x32_bf16 v[44:47], v[160:163], v[204:207], v[44:47]
	v_mfma_f32_16x16x32_bf16 v[40:43], v[168:171], v[204:207], v[40:43]
	v_mfma_f32_16x16x32_bf16 v[28:31], v[160:163], v[212:215], v[28:31]
	v_mfma_f32_16x16x32_bf16 v[24:27], v[168:171], v[212:215], v[24:27]
	v_mfma_f32_16x16x32_bf16 v[12:15], v[160:163], v[220:223], v[12:15]
	v_mfma_f32_16x16x32_bf16 v[8:11], v[168:171], v[220:223], v[8:11]
	s_setprio 0
	s_setprio 3
	v_mfma_f32_16x16x32_bf16 v[52:55], v[172:175], v[192:195], v[52:55]
	v_mfma_f32_16x16x32_bf16 v[48:51], v[180:183], v[192:195], v[48:51]
	v_mfma_f32_16x16x32_bf16 v[36:39], v[172:175], v[200:203], v[36:39]
	v_mfma_f32_16x16x32_bf16 v[32:35], v[180:183], v[200:203], v[32:35]
	v_mfma_f32_16x16x32_bf16 v[20:23], v[172:175], v[208:211], v[20:23]
	v_mfma_f32_16x16x32_bf16 v[16:19], v[180:183], v[208:211], v[16:19]
	v_mfma_f32_16x16x32_bf16 v[4:7], v[172:175], v[216:219], v[4:7]
	v_mfma_f32_16x16x32_bf16 v[0:3], v[180:183], v[216:219], v[0:3]
	v_mfma_f32_16x16x32_bf16 v[52:55], v[176:179], v[196:199], v[52:55]
	v_mfma_f32_16x16x32_bf16 v[48:51], v[188:191], v[196:199], v[48:51]
	v_mfma_f32_16x16x32_bf16 v[36:39], v[176:179], v[204:207], v[36:39]
	v_mfma_f32_16x16x32_bf16 v[32:35], v[188:191], v[204:207], v[32:35]
	v_mfma_f32_16x16x32_bf16 v[20:23], v[176:179], v[212:215], v[20:23]
	v_mfma_f32_16x16x32_bf16 v[16:19], v[188:191], v[212:215], v[16:19]
	v_mfma_f32_16x16x32_bf16 v[4:7], v[176:179], v[220:223], v[4:7]
	v_mfma_f32_16x16x32_bf16 v[0:3], v[188:191], v[220:223], v[0:3]
	s_setprio 0
	s_barrier
; #define PG8_STAGE(bufoff, gbase, voff) do { _Pragma("unroll") for (int _i = 0; _i < 2; ++_i) \
;         __builtin_amdgcn_global_load_lds((const unsigned*)((const char*)(gbase) + (voff)[_i]), (LAS unsigned*)(lds + (bufoff) + ldsw + _i * 8192), 16, 0, 0); } while (0)
; #define PG8_LDA(dst, b, h) do { _Pragma("unroll") for (int m = 0; m < 4; ++m) _Pragma("unroll") for (int k = 0; k < 2; ++k) dst[m][k] = *(const LAS bf16x8*)(lds + PG8_SA(b, h) + aoff + m * 2048 + k * 1024); } while (0)
; #define PG8_LDB(dst, b, h) do { _Pragma("unroll") for (int n = 0; n < 2; ++n) _Pragma("unroll") for (int k = 0; k < 2; ++k) dst[n][k] = *(const LAS bf16x8*)(lds + PG8_SB(b, h) + boff + n * 2048 + k * 1024); } while (0)
; #define PG8_MMA(ai, bj, At, Bt) do { __builtin_amdgcn_s_setprio(3); _Pragma("unroll") for (int m = 0; m < 4; ++m) _Pragma("unroll") for (int n = 0; n < 2; ++n) _Pragma("unroll") for (int k = 0; k < 2; ++k) \
;         acc[ai][bj][m][n] = __builtin_amdgcn_mfma_f32_16x16x32_bf16(Bt[n][k], At[m][k], acc[ai][bj][m][n], 0, 0, 0); __builtin_amdgcn_s_setprio(0); } while (0)
; #define PG8_WAIT_V(n) asm volatile("s_waitcnt vmcnt(" #n ")" ::: "memory")
; #define PG8_WAIT_L(n) asm volatile("s_waitcnt lgkmcnt(" #n ")" ::: "memory")
; #define PG8_BAR __builtin_amdgcn_s_barrier()
; #define PG8_SCHED __builtin_amdgcn_sched_barrier(0)
; template <class Epi, class Sched>
; __device__ __forceinline__ void gemm_phase(LAS unsigned char* lds, const Gemm g, const Sched& S, const Epi& E, int tid_in) {
;     ...
;             PG8_LDB(B0, 1, 0); PG8_LDB(B1, 1, 1); PG8_SCHED; PG8_LDA(At, 1, 0); PG8_STAGE(PG8_SA(0, 0), a2, voffA); PG8_STAGE(PG8_SA(0, 1), a2 + hstep, voffA);
;             PG8_WAIT_V(8); PG8_WAIT_L(0); PG8_BAR; PG8_MMA(0, 0, At, B0); PG8_MMA(0, 1, At, B1); PG8_BAR; PG8_SCHED;
;             PG8_LDA(At, 1, 1); PG8_STAGE(PG8_SB(1, 0), b3, voffB); PG8_STAGE(PG8_SB(1, 1), b3 + hstep, voffB);
;             PG8_WAIT_V(6); PG8_WAIT_L(0); PG8_BAR; PG8_MMA(1, 0, At, B0); PG8_MMA(1, 1, At, B1); PG8_BAR; PG8_SCHED;
	s_add_i32 s72, 0, 0x18000
	v_add_u32_e32 v155, s72, v149
	s_add_i32 s73, 0, 0x1c000
	ds_read_b128 v[156:159], v155
	ds_read_b128 v[160:163], v155 offset:1024
	ds_read_b128 v[164:167], v155 offset:2048
	ds_read_b128 v[168:171], v155 offset:3072
	v_add_u32_e32 v155, s73, v149
	ds_read_b128 v[172:175], v155
	ds_read_b128 v[176:179], v155 offset:1024
	ds_read_b128 v[180:183], v155 offset:2048
	ds_read_b128 v[188:191], v155 offset:3072
	s_mov_b32 m0, s3
	v_lshl_add_u64 v[226:227], s[40:41], 0, v[128:129]
	ds_read_b128 v[192:195], v153 offset:32768
	ds_read_b128 v[196:199], v153 offset:33792
	ds_read_b128 v[200:203], v153 offset:34816
	ds_read_b128 v[204:207], v153 offset:35840
	ds_read_b128 v[208:211], v153 offset:36864
	ds_read_b128 v[212:215], v153 offset:37888
	ds_read_b128 v[216:219], v153 offset:38912
	ds_read_b128 v[220:223], v153 offset:39936
	global_load_lds_dwordx4 v[226:227], off
	v_lshl_add_u64 v[226:227], s[40:41], 0, v[132:133]
	s_add_u32 s40, s40, 0x80000
	s_mov_b32 m0, s42
	s_addc_u32 s41, s41, 0
	global_load_lds_dwordx4 v[226:227], off
	v_lshl_add_u64 v[226:227], s[40:41], 0, v[128:129]
	s_mov_b32 m0, s43
	s_nop 0
	global_load_lds_dwordx4 v[226:227], off
	v_lshl_add_u64 v[226:227], s[40:41], 0, v[132:133]
	s_mov_b32 m0, s44
	s_nop 0
	global_load_lds_dwordx4 v[226:227], off
	s_waitcnt vmcnt(8) lgkmcnt(0)
	s_barrier
	s_setprio 3
	v_mfma_f32_16x16x32_bf16 v[124:127], v[156:159], v[192:195], v[124:127]
	v_mfma_f32_16x16x32_bf16 v[120:123], v[164:167], v[192:195], v[120:123]
	v_mfma_f32_16x16x32_bf16 v[108:111], v[156:159], v[200:203], v[108:111]
	v_mfma_f32_16x16x32_bf16 v[104:107], v[164:167], v[200:203], v[104:107]
	v_mfma_f32_16x16x32_bf16 v[92:95], v[156:159], v[208:211], v[92:95]
	v_mfma_f32_16x16x32_bf16 v[88:91], v[164:167], v[208:211], v[88:91]
	v_mfma_f32_16x16x32_bf16 v[76:79], v[156:159], v[216:219], v[76:79]
	v_mfma_f32_16x16x32_bf16 v[72:75], v[164:167], v[216:219], v[72:75]
	v_mfma_f32_16x16x32_bf16 v[124:127], v[160:163], v[196:199], v[124:127]
	v_mfma_f32_16x16x32_bf16 v[120:123], v[168:171], v[196:199], v[120:123]
	v_mfma_f32_16x16x32_bf16 v[108:111], v[160:163], v[204:207], v[108:111]
	v_mfma_f32_16x16x32_bf16 v[104:107], v[168:171], v[204:207], v[104:107]
	v_mfma_f32_16x16x32_bf16 v[92:95], v[160:163], v[212:215], v[92:95]
	v_mfma_f32_16x16x32_bf16 v[88:91], v[168:171], v[212:215], v[88:91]
	v_mfma_f32_16x16x32_bf16 v[76:79], v[160:163], v[220:223], v[76:79]
	v_mfma_f32_16x16x32_bf16 v[72:75], v[168:171], v[220:223], v[72:75]
	s_setprio 0
	s_setprio 3
	v_mfma_f32_16x16x32_bf16 v[116:119], v[172:175], v[192:195], v[116:119]
	v_mfma_f32_16x16x32_bf16 v[112:115], v[180:183], v[192:195], v[112:115]
	v_mfma_f32_16x16x32_bf16 v[100:103], v[172:175], v[200:203], v[100:103]
	v_mfma_f32_16x16x32_bf16 v[96:99], v[180:183], v[200:203], v[96:99]
	v_mfma_f32_16x16x32_bf16 v[84:87], v[172:175], v[208:211], v[84:87]
	v_mfma_f32_16x16x32_bf16 v[80:83], v[180:183], v[208:211], v[80:83]
	v_mfma_f32_16x16x32_bf16 v[68:71], v[172:175], v[216:219], v[68:71]
	v_mfma_f32_16x16x32_bf16 v[64:67], v[180:183], v[216:219], v[64:67]
	v_mfma_f32_16x16x32_bf16 v[116:119], v[176:179], v[196:199], v[116:119]
	v_mfma_f32_16x16x32_bf16 v[112:115], v[188:191], v[196:199], v[112:115]
	v_mfma_f32_16x16x32_bf16 v[100:103], v[176:179], v[204:207], v[100:103]
	v_mfma_f32_16x16x32_bf16 v[96:99], v[188:191], v[204:207], v[96:99]
	v_mfma_f32_16x16x32_bf16 v[84:87], v[176:179], v[212:215], v[84:87]
	v_mfma_f32_16x16x32_bf16 v[80:83], v[188:191], v[212:215], v[80:83]
	v_mfma_f32_16x16x32_bf16 v[68:71], v[176:179], v[220:223], v[68:71]
	v_mfma_f32_16x16x32_bf16 v[64:67], v[188:191], v[220:223], v[64:67]
	s_setprio 0
	s_barrier
	s_add_i32 s40, s72, s2
	v_lshl_add_u64 v[184:185], v[184:185], 0, s[16:17]
	s_mov_b32 m0, s40
	ds_read_b128 v[192:195], v153 offset:49152
	ds_read_b128 v[196:199], v153 offset:50176
	ds_read_b128 v[200:203], v153 offset:51200
	ds_read_b128 v[204:207], v153 offset:52224
	ds_read_b128 v[208:211], v153 offset:53248
	ds_read_b128 v[212:215], v153 offset:54272
	ds_read_b128 v[216:219], v153 offset:55296
	ds_read_b128 v[220:223], v153 offset:56320
	global_load_lds_dwordx4 v[184:185], off
	s_add_i32 m0, s40, 0x2000
	s_add_u32 s38, s38, 0x80080
	v_lshl_add_u64 v[184:185], v[224:225], 0, s[16:17]
	s_addc_u32 s39, s39, 0
	s_add_i32 s40, s73, s2
	global_load_lds_dwordx4 v[184:185], off
	v_lshl_add_u64 v[184:185], s[38:39], 0, v[130:131]
	s_mov_b32 m0, s40
	s_nop 0
	global_load_lds_dwordx4 v[184:185], off
	v_lshl_add_u64 v[184:185], s[38:39], 0, v[134:135]
	s_add_i32 m0, s40, 0x2000
	s_nop 0
	global_load_lds_dwordx4 v[184:185], off
	s_waitcnt vmcnt(6) lgkmcnt(0)
	s_barrier
	s_setprio 3
	v_mfma_f32_16x16x32_bf16 v[60:63], v[156:159], v[192:195], v[60:63]
	v_mfma_f32_16x16x32_bf16 v[56:59], v[164:167], v[192:195], v[56:59]
	v_mfma_f32_16x16x32_bf16 v[44:47], v[156:159], v[200:203], v[44:47]
	v_mfma_f32_16x16x32_bf16 v[40:43], v[164:167], v[200:203], v[40:43]
	v_mfma_f32_16x16x32_bf16 v[28:31], v[156:159], v[208:211], v[28:31]
	v_mfma_f32_16x16x32_bf16 v[24:27], v[164:167], v[208:211], v[24:27]
	v_mfma_f32_16x16x32_bf16 v[12:15], v[156:159], v[216:219], v[12:15]
	v_mfma_f32_16x16x32_bf16 v[8:11], v[164:167], v[216:219], v[8:11]
	v_mfma_f32_16x16x32_bf16 v[60:63], v[160:163], v[196:199], v[60:63]
	v_mfma_f32_16x16x32_bf16 v[56:59], v[168:171], v[196:199], v[56:59]
	v_mfma_f32_16x16x32_bf16 v[44:47], v[160:163], v[204:207], v[44:47]
	v_mfma_f32_16x16x32_bf16 v[40:43], v[168:171], v[204:207], v[40:43]
	v_mfma_f32_16x16x32_bf16 v[28:31], v[160:163], v[212:215], v[28:31]
	v_mfma_f32_16x16x32_bf16 v[24:27], v[168:171], v[212:215], v[24:27]
	v_mfma_f32_16x16x32_bf16 v[12:15], v[160:163], v[220:223], v[12:15]
	v_mfma_f32_16x16x32_bf16 v[8:11], v[168:171], v[220:223], v[8:11]
	s_setprio 0
	s_setprio 3
	v_mfma_f32_16x16x32_bf16 v[52:55], v[172:175], v[192:195], v[52:55]
	v_mfma_f32_16x16x32_bf16 v[48:51], v[180:183], v[192:195], v[48:51]
	v_mfma_f32_16x16x32_bf16 v[36:39], v[172:175], v[200:203], v[36:39]
	v_mfma_f32_16x16x32_bf16 v[32:35], v[180:183], v[200:203], v[32:35]
	v_mfma_f32_16x16x32_bf16 v[20:23], v[172:175], v[208:211], v[20:23]
	v_mfma_f32_16x16x32_bf16 v[16:19], v[180:183], v[208:211], v[16:19]
	v_mfma_f32_16x16x32_bf16 v[4:7], v[172:175], v[216:219], v[4:7]
	v_mfma_f32_16x16x32_bf16 v[0:3], v[180:183], v[216:219], v[0:3]
	v_mfma_f32_16x16x32_bf16 v[52:55], v[176:179], v[196:199], v[52:55]
	v_mfma_f32_16x16x32_bf16 v[48:51], v[188:191], v[196:199], v[48:51]
	v_mfma_f32_16x16x32_bf16 v[36:39], v[176:179], v[204:207], v[36:39]
	v_mfma_f32_16x16x32_bf16 v[32:35], v[188:191], v[204:207], v[32:35]
	v_mfma_f32_16x16x32_bf16 v[20:23], v[176:179], v[212:215], v[20:23]
	v_mfma_f32_16x16x32_bf16 v[16:19], v[188:191], v[212:215], v[16:19]
	v_mfma_f32_16x16x32_bf16 v[4:7], v[176:179], v[220:223], v[4:7]
	v_mfma_f32_16x16x32_bf16 v[0:3], v[188:191], v[220:223], v[0:3]
	s_setprio 0
	s_barrier
	s_add_i32 s71, s71, 2
	s_add_u32 s36, s36, 0x100
	s_addc_u32 s37, s37, 0
	s_cmp_gt_u32 s71, 29
	s_cbranch_scc0 .LBB0_620

;     __device__ bool next(int i, Unit& u) const { if (!b.next(i >> 1, u)) return false; u.half = i & 1; u.koff = (i & 1) * kbytes; return true; }
; #define PG8_STAGE(bufoff, gbase, voff) do { _Pragma("unroll") for (int _i = 0; _i < 2; ++_i) \
;         __builtin_amdgcn_global_load_lds((const unsigned*)((const char*)(gbase) + (voff)[_i]), (LAS unsigned*)(lds + (bufoff) + ldsw + _i * 8192), 16, 0, 0); } while (0)
; #define PG8_LDA(dst, b, h) do { _Pragma("unroll") for (int m = 0; m < 4; ++m) _Pragma("unroll") for (int k = 0; k < 2; ++k) dst[m][k] = *(const LAS bf16x8*)(lds + PG8_SA(b, h) + aoff + m * 2048 + k * 1024); } while (0)
; #define PG8_LDB(dst, b, h) do { _Pragma("unroll") for (int n = 0; n < 2; ++n) _Pragma("unroll") for (int k = 0; k < 2; ++k) dst[n][k] = *(const LAS bf16x8*)(lds + PG8_SB(b, h) + boff + n * 2048 + k * 1024); } while (0)
; #define PG8_WAIT_V(n) asm volatile("s_waitcnt vmcnt(" #n ")" ::: "memory")
; #define PG8_WAIT_L(n) asm volatile("s_waitcnt lgkmcnt(" #n ")" ::: "memory")
; #define PG8_BAR __builtin_amdgcn_s_barrier()
; #define PG8_SCHED __builtin_amdgcn_sched_barrier(0)
; template <class Epi, class Sched>
; __device__ __forceinline__ void gemm_phase(LAS unsigned char* lds, const Gemm g, const Sched& S, const Epi& E, int tid_in) {
;     ...
;         const bool has_next = S.next(ui + 1, nxt);
;         const char* nA = has_next ? (const char*)g.A + (size_t)nxt.pm * tstep + nxt.koff : cA; const char* nB = has_next ? (const char*)g.Bt + (size_t)nxt.pn * tstep + nxt.koff : cB;
;         for (int t = 0; t < nt; t += 2) {
;             const bool last = (t == nt - 2);
;             const char* a1 = cA + (size_t)(t + 1) * kstep;
;             const char* a2 = last ? nA : cA + (size_t)(t + 2) * kstep; const char* b2 = last ? nB : cB + (size_t)(t + 2) * kstep;
;             const char* a3 = a2 + kstep; const char* b3 = b2 + kstep;
;             PG8_LDB(B0, 0, 0); PG8_LDB(B1, 0, 1); PG8_SCHED; PG8_LDA(At, 0, 0); PG8_STAGE(PG8_SA(1, 0), a1, voffA); PG8_STAGE(PG8_SA(1, 1), a1 + hstep, voffA);
;             PG8_WAIT_V(8); PG8_WAIT_L(0); PG8_BAR; PG8_MMA(0, 0, At, B0); PG8_MMA(0, 1, At, B1); PG8_BAR; PG8_SCHED;
;             PG8_LDA(At, 0, 1); PG8_STAGE(PG8_SB(0, 0), b2, voffB); PG8_STAGE(PG8_SB(0, 1), b2 + hstep, voffB);
;             PG8_WAIT_V(6); PG8_WAIT_L(0); PG8_BAR; PG8_MMA(1, 0, At, B0); PG8_MMA(1, 1, At, B1); PG8_BAR; PG8_SCHED;
.LBB0_762:
	s_ashr_i32 s21, s20, 31
	s_lshl_b64 s[22:23], s[20:21], 20
	s_add_u32 s22, s58, s22
	s_addc_u32 s23, s59, s23
	s_and_b64 s[24:25], s[4:5], exec
	s_cselect_b32 s21, s23, s29
	s_cselect_b32 s48, s22, s28
	s_ashr_i32 s19, s18, 31
	s_lshl_b64 s[24:25], s[18:19], 20
	s_add_u32 s24, s2, s24
	s_addc_u32 s25, s3, s25
	s_and_b64 s[34:35], s[4:5], exec
	s_cselect_b32 s19, s25, s31
	s_cselect_b32 s49, s24, s30
	s_add_u32 s51, s30, 0x100
	v_lshl_add_u64 v[144:145], s[28:29], 0, v[136:137]
	v_lshl_add_u64 v[146:147], s[28:29], 0, v[138:139]
	s_addc_u32 s68, s31, 0
	s_mov_b32 s69, -2
	s_mov_b64 s[30:31], 0
	ds_read_b128 v[154:157], v151
	ds_read_b128 v[158:161], v151 offset:1024
	ds_read_b128 v[162:165], v151 offset:2048
	ds_read_b128 v[166:169], v151 offset:3072
	ds_read_b128 v[170:173], v152
	ds_read_b128 v[174:177], v152 offset:1024
	ds_read_b128 v[178:181], v152 offset:2048
	ds_read_b128 v[182:185], v152 offset:3072
	s_add_u32 s34, s28, s30
	s_addc_u32 s35, s29, s31
	s_add_u32 s36, s34, 0x100
	s_addc_u32 s37, s35, 0
	s_add_u32 s34, s51, s30
	s_addc_u32 s35, s68, s31
	s_cmpk_eq_i32 s30, 0xf00
	s_cselect_b32 s35, s19, s35
	s_cselect_b32 s34, s49, s34
	s_cselect_b32 s37, s21, s37
	s_cselect_b32 s36, s48, s36
	v_lshl_add_u64 v[220:221], v[146:147], 0, s[30:31]
	v_lshl_add_u64 v[222:223], v[220:221], 0, s[8:9]
	s_add_i32 m0, s27, 0x8000
	ds_read_b128 v[188:191], v153
	ds_read_b128 v[192:195], v153 offset:1024
	ds_read_b128 v[196:199], v153 offset:2048
	ds_read_b128 v[200:203], v153 offset:3072
	ds_read_b128 v[204:207], v153 offset:4096
	ds_read_b128 v[208:211], v153 offset:5120
	ds_read_b128 v[212:215], v153 offset:6144
	ds_read_b128 v[216:219], v153 offset:7168
	global_load_lds_dwordx4 v[222:223], off
	v_lshl_add_u64 v[222:223], v[144:145], 0, s[30:31]
	v_lshl_add_u64 v[224:225], v[222:223], 0, s[8:9]
	s_add_i32 m0, s27, 0xa000
	v_lshl_add_u64 v[220:221], v[220:221], 0, s[14:15]
	global_load_lds_dwordx4 v[224:225], off
	s_add_i32 m0, s27, 0xc000
	s_nop 0
	global_load_lds_dwordx4 v[220:221], off
	v_lshl_add_u64 v[220:221], v[222:223], 0, s[14:15]
	s_add_i32 m0, s27, 0xe000
	s_nop 0
	global_load_lds_dwordx4 v[220:221], off
	s_waitcnt vmcnt(8) lgkmcnt(0)
	s_barrier
	s_setprio 3
	v_mfma_f32_16x16x32_bf16 v[124:127], v[154:157], v[188:191], 0
	v_mfma_f32_16x16x32_bf16 v[120:123], v[162:165], v[188:191], 0
	v_mfma_f32_16x16x32_bf16 v[108:111], v[154:157], v[196:199], 0
	v_mfma_f32_16x16x32_bf16 v[104:107], v[162:165], v[196:199], 0
	v_mfma_f32_16x16x32_bf16 v[92:95], v[154:157], v[204:207], 0
	v_mfma_f32_16x16x32_bf16 v[88:91], v[162:165], v[204:207], 0
	v_mfma_f32_16x16x32_bf16 v[76:79], v[154:157], v[212:215], 0
	v_mfma_f32_16x16x32_bf16 v[72:75], v[162:165], v[212:215], 0
	v_mfma_f32_16x16x32_bf16 v[124:127], v[158:161], v[192:195], v[124:127]
	v_mfma_f32_16x16x32_bf16 v[120:123], v[166:169], v[192:195], v[120:123]
	v_mfma_f32_16x16x32_bf16 v[108:111], v[158:161], v[200:203], v[108:111]
	v_mfma_f32_16x16x32_bf16 v[104:107], v[166:169], v[200:203], v[104:107]
	v_mfma_f32_16x16x32_bf16 v[92:95], v[158:161], v[208:211], v[92:95]
	v_mfma_f32_16x16x32_bf16 v[88:91], v[166:169], v[208:211], v[88:91]
	v_mfma_f32_16x16x32_bf16 v[76:79], v[158:161], v[216:219], v[76:79]
	v_mfma_f32_16x16x32_bf16 v[72:75], v[166:169], v[216:219], v[72:75]
	s_setprio 0
	s_setprio 3
	v_mfma_f32_16x16x32_bf16 v[116:119], v[170:173], v[188:191], 0
	v_mfma_f32_16x16x32_bf16 v[112:115], v[178:181], v[188:191], 0
	v_mfma_f32_16x16x32_bf16 v[100:103], v[170:173], v[196:199], 0
	v_mfma_f32_16x16x32_bf16 v[96:99], v[178:181], v[196:199], 0
	v_mfma_f32_16x16x32_bf16 v[84:87], v[170:173], v[204:207], 0
	v_mfma_f32_16x16x32_bf16 v[80:83], v[178:181], v[204:207], 0
	v_mfma_f32_16x16x32_bf16 v[68:71], v[170:173], v[212:215], 0
	v_mfma_f32_16x16x32_bf16 v[64:67], v[178:181], v[212:215], 0
	v_mfma_f32_16x16x32_bf16 v[116:119], v[174:177], v[192:195], v[116:119]
	v_mfma_f32_16x16x32_bf16 v[112:115], v[182:185], v[192:195], v[112:115]
	v_mfma_f32_16x16x32_bf16 v[100:103], v[174:177], v[200:203], v[100:103]
	v_mfma_f32_16x16x32_bf16 v[96:99], v[182:185], v[200:203], v[96:99]
	v_mfma_f32_16x16x32_bf16 v[84:87], v[174:177], v[208:211], v[84:87]
	v_mfma_f32_16x16x32_bf16 v[80:83], v[182:185], v[208:211], v[80:83]
	v_mfma_f32_16x16x32_bf16 v[68:71], v[174:177], v[216:219], v[68:71]
	v_mfma_f32_16x16x32_bf16 v[64:67], v[182:185], v[216:219], v[64:67]
	s_setprio 0
	s_barrier
	s_add_i32 s70, s44, s38
	v_lshl_add_u64 v[220:221], s[34:35], 0, v[132:133]
	s_mov_b32 m0, s70
	ds_read_b128 v[188:191], v153 offset:16384
	ds_read_b128 v[192:195], v153 offset:17408
	ds_read_b128 v[196:199], v153 offset:18432
	ds_read_b128 v[200:203], v153 offset:19456
	ds_read_b128 v[204:207], v153 offset:20480
	ds_read_b128 v[208:211], v153 offset:21504
	ds_read_b128 v[212:215], v153 offset:22528
	ds_read_b128 v[216:219], v153 offset:23552
	global_load_lds_dwordx4 v[220:221], off
	s_add_i32 m0, s70, 0x2000
	s_add_u32 s70, s34, 0x80000
	v_lshl_add_u64 v[222:223], s[34:35], 0, v[128:129]
	s_addc_u32 s71, s35, 0
	s_add_i32 s72, s45, s38
	global_load_lds_dwordx4 v[222:223], off
	v_lshl_add_u64 v[224:225], s[70:71], 0, v[132:133]
	s_mov_b32 m0, s72
	s_nop 0
	global_load_lds_dwordx4 v[224:225], off
	v_lshl_add_u64 v[224:225], s[70:71], 0, v[128:129]
	s_add_i32 m0, s72, 0x2000
	s_nop 0
	global_load_lds_dwordx4 v[224:225], off
	s_waitcnt vmcnt(6) lgkmcnt(0)
	s_barrier
; #define PG8_STAGE(bufoff, gbase, voff) do { _Pragma("unroll") for (int _i = 0; _i < 2; ++_i) \
;         __builtin_amdgcn_global_load_lds((const unsigned*)((const char*)(gbase) + (voff)[_i]), (LAS unsigned*)(lds + (bufoff) + ldsw + _i * 8192), 16, 0, 0); } while (0)
; #define PG8_LDA(dst, b, h) do { _Pragma("unroll") for (int m = 0; m < 4; ++m) _Pragma("unroll") for (int k = 0; k < 2; ++k) dst[m][k] = *(const LAS bf16x8*)(lds + PG8_SA(b, h) + aoff + m * 2048 + k * 1024); } while (0)
; #define PG8_LDB(dst, b, h) do { _Pragma("unroll") for (int n = 0; n < 2; ++n) _Pragma("unroll") for (int k = 0; k < 2; ++k) dst[n][k] = *(const LAS bf16x8*)(lds + PG8_SB(b, h) + boff + n * 2048 + k * 1024); } while (0)
; #define PG8_MMA(ai, bj, At, Bt) do { __builtin_amdgcn_s_setprio(3); _Pragma("unroll") for (int m = 0; m < 4; ++m) _Pragma("unroll") for (int n = 0; n < 2; ++n) _Pragma("unroll") for (int k = 0; k < 2; ++k) \
;         acc[ai][bj][m][n] = __builtin_amdgcn_mfma_f32_16x16x32_bf16(Bt[n][k], At[m][k], acc[ai][bj][m][n], 0, 0, 0); __builtin_amdgcn_s_setprio(0); } while (0)
; #define PG8_WAIT_V(n) asm volatile("s_waitcnt vmcnt(" #n ")" ::: "memory")
; #define PG8_WAIT_L(n) asm volatile("s_waitcnt lgkmcnt(" #n ")" ::: "memory")
; #define PG8_BAR __builtin_amdgcn_s_barrier()
; #define PG8_SCHED __builtin_amdgcn_sched_barrier(0)
; template <class Epi, class Sched>
; __device__ __forceinline__ void gemm_phase(LAS unsigned char* lds, const Gemm g, const Sched& S, const Epi& E, int tid_in) {
;     ...
;             PG8_WAIT_V(6); PG8_WAIT_L(0); PG8_BAR; PG8_MMA(1, 0, At, B0); PG8_MMA(1, 1, At, B1); PG8_BAR; PG8_SCHED;
;             PG8_LDB(B0, 1, 0); PG8_LDB(B1, 1, 1); PG8_SCHED; PG8_LDA(At, 1, 0); PG8_STAGE(PG8_SA(0, 0), a2, voffA); PG8_STAGE(PG8_SA(0, 1), a2 + hstep, voffA);
;             PG8_WAIT_V(8); PG8_WAIT_L(0); PG8_BAR; PG8_MMA(0, 0, At, B0); PG8_MMA(0, 1, At, B1); PG8_BAR; PG8_SCHED;
	s_setprio 3
	v_mfma_f32_16x16x32_bf16 v[60:63], v[154:157], v[188:191], 0
	v_mfma_f32_16x16x32_bf16 v[56:59], v[162:165], v[188:191], 0
	v_mfma_f32_16x16x32_bf16 v[44:47], v[154:157], v[196:199], 0
	v_mfma_f32_16x16x32_bf16 v[40:43], v[162:165], v[196:199], 0
	v_mfma_f32_16x16x32_bf16 v[28:31], v[154:157], v[204:207], 0
	v_mfma_f32_16x16x32_bf16 v[24:27], v[162:165], v[204:207], 0
	v_mfma_f32_16x16x32_bf16 v[12:15], v[154:157], v[212:215], 0
	v_mfma_f32_16x16x32_bf16 v[8:11], v[162:165], v[212:215], 0
	v_mfma_f32_16x16x32_bf16 v[60:63], v[158:161], v[192:195], v[60:63]
	v_mfma_f32_16x16x32_bf16 v[56:59], v[166:169], v[192:195], v[56:59]
	v_mfma_f32_16x16x32_bf16 v[44:47], v[158:161], v[200:203], v[44:47]
	v_mfma_f32_16x16x32_bf16 v[40:43], v[166:169], v[200:203], v[40:43]
	v_mfma_f32_16x16x32_bf16 v[28:31], v[158:161], v[208:211], v[28:31]
	v_mfma_f32_16x16x32_bf16 v[24:27], v[166:169], v[208:211], v[24:27]
	v_mfma_f32_16x16x32_bf16 v[12:15], v[158:161], v[216:219], v[12:15]
	v_mfma_f32_16x16x32_bf16 v[8:11], v[166:169], v[216:219], v[8:11]
	s_setprio 0
	s_setprio 3
	v_mfma_f32_16x16x32_bf16 v[52:55], v[170:173], v[188:191], 0
	v_mfma_f32_16x16x32_bf16 v[48:51], v[178:181], v[188:191], 0
	v_mfma_f32_16x16x32_bf16 v[36:39], v[170:173], v[196:199], 0
	v_mfma_f32_16x16x32_bf16 v[32:35], v[178:181], v[196:199], 0
	v_mfma_f32_16x16x32_bf16 v[20:23], v[170:173], v[204:207], 0
	v_mfma_f32_16x16x32_bf16 v[16:19], v[178:181], v[204:207], 0
	v_mfma_f32_16x16x32_bf16 v[4:7], v[170:173], v[212:215], 0
	v_mfma_f32_16x16x32_bf16 v[0:3], v[178:181], v[212:215], 0
	v_mfma_f32_16x16x32_bf16 v[52:55], v[174:177], v[192:195], v[52:55]
	v_mfma_f32_16x16x32_bf16 v[48:51], v[182:185], v[192:195], v[48:51]
	v_mfma_f32_16x16x32_bf16 v[36:39], v[174:177], v[200:203], v[36:39]
	v_mfma_f32_16x16x32_bf16 v[32:35], v[182:185], v[200:203], v[32:35]
	v_mfma_f32_16x16x32_bf16 v[20:23], v[174:177], v[208:211], v[20:23]
	v_mfma_f32_16x16x32_bf16 v[16:19], v[182:185], v[208:211], v[16:19]
	v_mfma_f32_16x16x32_bf16 v[4:7], v[174:177], v[216:219], v[4:7]
	v_mfma_f32_16x16x32_bf16 v[0:3], v[182:185], v[216:219], v[0:3]
	s_setprio 0
	s_barrier
	s_add_i32 s70, 0, 0x18000
	s_add_i32 s71, 0, 0x1c000
	v_add_u32_e32 v166, s70, v149
	v_add_u32_e32 v182, s71, v149
	ds_read_b128 v[154:157], v166
	ds_read_b128 v[158:161], v166 offset:1024
	ds_read_b128 v[162:165], v166 offset:2048
	ds_read_b128 v[166:169], v166 offset:3072
	ds_read_b128 v[170:173], v182
	ds_read_b128 v[174:177], v182 offset:1024
	ds_read_b128 v[178:181], v182 offset:2048
	ds_read_b128 v[182:185], v182 offset:3072
	s_mov_b32 m0, s27
	v_lshl_add_u64 v[224:225], s[36:37], 0, v[134:135]
	ds_read_b128 v[188:191], v153 offset:32768
	ds_read_b128 v[192:195], v153 offset:33792
	ds_read_b128 v[196:199], v153 offset:34816
	ds_read_b128 v[200:203], v153 offset:35840
	ds_read_b128 v[204:207], v153 offset:36864
	ds_read_b128 v[208:211], v153 offset:37888
	ds_read_b128 v[212:215], v153 offset:38912
	ds_read_b128 v[216:219], v153 offset:39936
	global_load_lds_dwordx4 v[224:225], off
	v_lshl_add_u64 v[224:225], s[36:37], 0, v[130:131]
	s_add_u32 s36, s36, 0x80000
	s_mov_b32 m0, s40
	s_addc_u32 s37, s37, 0
	global_load_lds_dwordx4 v[224:225], off
	v_lshl_add_u64 v[224:225], s[36:37], 0, v[134:135]
	s_mov_b32 m0, s41
	s_nop 0
	global_load_lds_dwordx4 v[224:225], off
	v_lshl_add_u64 v[224:225], s[36:37], 0, v[130:131]
	s_mov_b32 m0, s42
	s_nop 0
	global_load_lds_dwordx4 v[224:225], off
	s_waitcnt vmcnt(8) lgkmcnt(0)
	s_barrier
	s_setprio 3
	v_mfma_f32_16x16x32_bf16 v[124:127], v[154:157], v[188:191], v[124:127]
	v_mfma_f32_16x16x32_bf16 v[120:123], v[162:165], v[188:191], v[120:123]
	v_mfma_f32_16x16x32_bf16 v[108:111], v[154:157], v[196:199], v[108:111]
	v_mfma_f32_16x16x32_bf16 v[104:107], v[162:165], v[196:199], v[104:107]
	v_mfma_f32_16x16x32_bf16 v[92:95], v[154:157], v[204:207], v[92:95]
	v_mfma_f32_16x16x32_bf16 v[88:91], v[162:165], v[204:207], v[88:91]
	v_mfma_f32_16x16x32_bf16 v[76:79], v[154:157], v[212:215], v[76:79]
	v_mfma_f32_16x16x32_bf16 v[72:75], v[162:165], v[212:215], v[72:75]
	v_mfma_f32_16x16x32_bf16 v[124:127], v[158:161], v[192:195], v[124:127]
	v_mfma_f32_16x16x32_bf16 v[120:123], v[166:169], v[192:195], v[120:123]
	v_mfma_f32_16x16x32_bf16 v[108:111], v[158:161], v[200:203], v[108:111]
	v_mfma_f32_16x16x32_bf16 v[104:107], v[166:169], v[200:203], v[104:107]
	v_mfma_f32_16x16x32_bf16 v[92:95], v[158:161], v[208:211], v[92:95]
	v_mfma_f32_16x16x32_bf16 v[88:91], v[166:169], v[208:211], v[88:91]
	v_mfma_f32_16x16x32_bf16 v[76:79], v[158:161], v[216:219], v[76:79]
	v_mfma_f32_16x16x32_bf16 v[72:75], v[166:169], v[216:219], v[72:75]
	s_setprio 0
	s_setprio 3
	v_mfma_f32_16x16x32_bf16 v[116:119], v[170:173], v[188:191], v[116:119]
	v_mfma_f32_16x16x32_bf16 v[112:115], v[178:181], v[188:191], v[112:115]
	v_mfma_f32_16x16x32_bf16 v[100:103], v[170:173], v[196:199], v[100:103]
	v_mfma_f32_16x16x32_bf16 v[96:99], v[178:181], v[196:199], v[96:99]
	v_mfma_f32_16x16x32_bf16 v[84:87], v[170:173], v[204:207], v[84:87]
	v_mfma_f32_16x16x32_bf16 v[80:83], v[178:181], v[204:207], v[80:83]
	v_mfma_f32_16x16x32_bf16 v[68:71], v[170:173], v[212:215], v[68:71]
	v_mfma_f32_16x16x32_bf16 v[64:67], v[178:181], v[212:215], v[64:67]
	v_mfma_f32_16x16x32_bf16 v[116:119], v[174:177], v[192:195], v[116:119]
	v_mfma_f32_16x16x32_bf16 v[112:115], v[182:185], v[192:195], v[112:115]
	v_mfma_f32_16x16x32_bf16 v[100:103], v[174:177], v[200:203], v[100:103]
	v_mfma_f32_16x16x32_bf16 v[96:99], v[182:185], v[200:203], v[96:99]
	v_mfma_f32_16x16x32_bf16 v[84:87], v[174:177], v[208:211], v[84:87]
	v_mfma_f32_16x16x32_bf16 v[80:83], v[182:185], v[208:211], v[80:83]
	v_mfma_f32_16x16x32_bf16 v[68:71], v[174:177], v[216:219], v[68:71]
	v_mfma_f32_16x16x32_bf16 v[64:67], v[182:185], v[216:219], v[64:67]
	s_setprio 0
	s_barrier
; #define PG8_STAGE(bufoff, gbase, voff) do { _Pragma("unroll") for (int _i = 0; _i < 2; ++_i) \
;         __builtin_amdgcn_global_load_lds((const unsigned*)((const char*)(gbase) + (voff)[_i]), (LAS unsigned*)(lds + (bufoff) + ldsw + _i * 8192), 16, 0, 0); } while (0)
; #define PG8_LDA(dst, b, h) do { _Pragma("unroll") for (int m = 0; m < 4; ++m) _Pragma("unroll") for (int k = 0; k < 2; ++k) dst[m][k] = *(const LAS bf16x8*)(lds + PG8_SA(b, h) + aoff + m * 2048 + k * 1024); } while (0)
; #define PG8_LDB(dst, b, h) do { _Pragma("unroll") for (int n = 0; n < 2; ++n) _Pragma("unroll") for (int k = 0; k < 2; ++k) dst[n][k] = *(const LAS bf16x8*)(lds + PG8_SB(b, h) + boff + n * 2048 + k * 1024); } while (0)
; #define PG8_WAIT_V(n) asm volatile("s_waitcnt vmcnt(" #n ")" ::: "memory")
; #define PG8_BAR __builtin_amdgcn_s_barrier()
; template <class Epi, class Sched>
; __device__ __forceinline__ void gemm_phase(LAS unsigned char* lds, const Gemm g, const Sched& S, const Epi& E, int tid_in) {
;     ...
;         for (int t = 0; t < nt; t += 2) {
;             const bool last = (t == nt - 2);
;             const char* a1 = cA + (size_t)(t + 1) * kstep;
;             const char* a2 = last ? nA : cA + (size_t)(t + 2) * kstep; const char* b2 = last ? nB : cB + (size_t)(t + 2) * kstep;
;             const char* a3 = a2 + kstep; const char* b3 = b2 + kstep;
;             PG8_LDB(B0, 0, 0); PG8_LDB(B1, 0, 1); PG8_SCHED; PG8_LDA(At, 0, 0); PG8_STAGE(PG8_SA(1, 0), a1, voffA); PG8_STAGE(PG8_SA(1, 1), a1 + hstep, voffA);
;             PG8_WAIT_V(8); PG8_WAIT_L(0); PG8_BAR; PG8_MMA(0, 0, At, B0); PG8_MMA(0, 1, At, B1); PG8_BAR; PG8_SCHED;
;             PG8_LDA(At, 0, 1); PG8_STAGE(PG8_SB(0, 0), b2, voffB); PG8_STAGE(PG8_SB(0, 1), b2 + hstep, voffB);
;             PG8_WAIT_V(6); PG8_WAIT_L(0); PG8_BAR; PG8_MMA(1, 0, At, B0); PG8_MMA(1, 1, At, B1); PG8_BAR; PG8_SCHED;
;             PG8_LDB(B0, 1, 0); PG8_LDB(B1, 1, 1); PG8_SCHED; PG8_LDA(At, 1, 0); PG8_STAGE(PG8_SA(0, 0), a2, voffA); PG8_STAGE(PG8_SA(0, 1), a2 + hstep, voffA);
;             PG8_WAIT_V(8); PG8_WAIT_L(0); PG8_BAR; PG8_MMA(0, 0, At, B0); PG8_MMA(0, 1, At, B1); PG8_BAR; PG8_SCHED;
;             PG8_LDA(At, 1, 1); PG8_STAGE(PG8_SB(1, 0), b3, voffB); PG8_STAGE(PG8_SB(1, 1), b3 + hstep, voffB);
;             PG8_WAIT_V(6); PG8_WAIT_L(0); PG8_BAR; PG8_MMA(1, 0, At, B0); PG8_MMA(1, 1, At, B1); PG8_BAR; PG8_SCHED;
	s_add_i32 s36, s70, s38
	v_lshl_add_u64 v[220:221], v[220:221], 0, s[8:9]
	s_mov_b32 m0, s36
	ds_read_b128 v[188:191], v153 offset:49152
	ds_read_b128 v[192:195], v153 offset:50176
	ds_read_b128 v[196:199], v153 offset:51200
	ds_read_b128 v[200:203], v153 offset:52224
	ds_read_b128 v[204:207], v153 offset:53248
	ds_read_b128 v[208:211], v153 offset:54272
	ds_read_b128 v[212:215], v153 offset:55296
	ds_read_b128 v[216:219], v153 offset:56320
	global_load_lds_dwordx4 v[220:221], off
	s_add_i32 m0, s36, 0x2000
	s_add_u32 s34, s34, 0x80080
	v_lshl_add_u64 v[220:221], v[222:223], 0, s[8:9]
	s_addc_u32 s35, s35, 0
	s_add_i32 s36, s71, s38
	global_load_lds_dwordx4 v[220:221], off
	v_lshl_add_u64 v[220:221], s[34:35], 0, v[132:133]
	s_mov_b32 m0, s36
	s_nop 0
	global_load_lds_dwordx4 v[220:221], off
	v_lshl_add_u64 v[220:221], s[34:35], 0, v[128:129]
	s_add_i32 m0, s36, 0x2000
	s_nop 0
	global_load_lds_dwordx4 v[220:221], off
	s_waitcnt vmcnt(6) lgkmcnt(0)
	s_barrier
	s_setprio 3
	v_mfma_f32_16x16x32_bf16 v[60:63], v[154:157], v[188:191], v[60:63]
	v_mfma_f32_16x16x32_bf16 v[56:59], v[162:165], v[188:191], v[56:59]
	v_mfma_f32_16x16x32_bf16 v[44:47], v[154:157], v[196:199], v[44:47]
	v_mfma_f32_16x16x32_bf16 v[40:43], v[162:165], v[196:199], v[40:43]
	v_mfma_f32_16x16x32_bf16 v[28:31], v[154:157], v[204:207], v[28:31]
	v_mfma_f32_16x16x32_bf16 v[24:27], v[162:165], v[204:207], v[24:27]
	v_mfma_f32_16x16x32_bf16 v[12:15], v[154:157], v[212:215], v[12:15]
	v_mfma_f32_16x16x32_bf16 v[8:11], v[162:165], v[212:215], v[8:11]
	v_mfma_f32_16x16x32_bf16 v[60:63], v[158:161], v[192:195], v[60:63]
	v_mfma_f32_16x16x32_bf16 v[56:59], v[166:169], v[192:195], v[56:59]
	v_mfma_f32_16x16x32_bf16 v[44:47], v[158:161], v[200:203], v[44:47]
	v_mfma_f32_16x16x32_bf16 v[40:43], v[166:169], v[200:203], v[40:43]
	v_mfma_f32_16x16x32_bf16 v[28:31], v[158:161], v[208:211], v[28:31]
	v_mfma_f32_16x16x32_bf16 v[24:27], v[166:169], v[208:211], v[24:27]
	v_mfma_f32_16x16x32_bf16 v[12:15], v[158:161], v[216:219], v[12:15]
	v_mfma_f32_16x16x32_bf16 v[8:11], v[166:169], v[216:219], v[8:11]
	s_setprio 0
	s_setprio 3
	v_mfma_f32_16x16x32_bf16 v[52:55], v[170:173], v[188:191], v[52:55]
	v_mfma_f32_16x16x32_bf16 v[48:51], v[178:181], v[188:191], v[48:51]
	v_mfma_f32_16x16x32_bf16 v[36:39], v[170:173], v[196:199], v[36:39]
	v_mfma_f32_16x16x32_bf16 v[32:35], v[178:181], v[196:199], v[32:35]
	v_mfma_f32_16x16x32_bf16 v[20:23], v[170:173], v[204:207], v[20:23]
	v_mfma_f32_16x16x32_bf16 v[16:19], v[178:181], v[204:207], v[16:19]
	v_mfma_f32_16x16x32_bf16 v[4:7], v[170:173], v[212:215], v[4:7]
	v_mfma_f32_16x16x32_bf16 v[0:3], v[178:181], v[212:215], v[0:3]
	v_mfma_f32_16x16x32_bf16 v[52:55], v[174:177], v[192:195], v[52:55]
	v_mfma_f32_16x16x32_bf16 v[48:51], v[182:185], v[192:195], v[48:51]
	v_mfma_f32_16x16x32_bf16 v[36:39], v[174:177], v[200:203], v[36:39]
	v_mfma_f32_16x16x32_bf16 v[32:35], v[182:185], v[200:203], v[32:35]
	v_mfma_f32_16x16x32_bf16 v[20:23], v[174:177], v[208:211], v[20:23]
	v_mfma_f32_16x16x32_bf16 v[16:19], v[182:185], v[208:211], v[16:19]
	v_mfma_f32_16x16x32_bf16 v[4:7], v[174:177], v[216:219], v[4:7]
	v_mfma_f32_16x16x32_bf16 v[0:3], v[182:185], v[216:219], v[0:3]
	s_setprio 0
	s_barrier
	s_add_i32 s69, s69, 2
	s_add_u32 s30, s30, 0x100
	s_addc_u32 s31, s31, 0
	s_cmp_gt_u32 s69, 29
	s_cbranch_scc0 .LBB0_763
	s_branch .Lpeel_exit_2
.LBB0_763:
	ds_read_b128 v[154:157], v151
	ds_read_b128 v[158:161], v151 offset:1024
	ds_read_b128 v[162:165], v151 offset:2048
	ds_read_b128 v[166:169], v151 offset:3072
	ds_read_b128 v[170:173], v152
	ds_read_b128 v[174:177], v152 offset:1024
	ds_read_b128 v[178:181], v152 offset:2048
	ds_read_b128 v[182:185], v152 offset:3072
	s_add_u32 s34, s28, s30
	s_addc_u32 s35, s29, s31
	s_add_u32 s36, s34, 0x100
	s_addc_u32 s37, s35, 0
	s_add_u32 s34, s51, s30
	s_addc_u32 s35, s68, s31
	s_cmpk_eq_i32 s30, 0xf00
	s_cselect_b32 s35, s19, s35
	s_cselect_b32 s34, s49, s34
	s_cselect_b32 s37, s21, s37
	s_cselect_b32 s36, s48, s36
	v_lshl_add_u64 v[220:221], v[146:147], 0, s[30:31]
	v_lshl_add_u64 v[222:223], v[220:221], 0, s[8:9]
	s_add_i32 m0, s27, 0x8000
	ds_read_b128 v[188:191], v153
	ds_read_b128 v[192:195], v153 offset:1024
	ds_read_b128 v[196:199], v153 offset:2048
	ds_read_b128 v[200:203], v153 offset:3072
	ds_read_b128 v[204:207], v153 offset:4096
	ds_read_b128 v[208:211], v153 offset:5120
	ds_read_b128 v[212:215], v153 offset:6144
	ds_read_b128 v[216:219], v153 offset:7168
	global_load_lds_dwordx4 v[222:223], off
	v_lshl_add_u64 v[222:223], v[144:145], 0, s[30:31]
	v_lshl_add_u64 v[224:225], v[222:223], 0, s[8:9]
	s_add_i32 m0, s27, 0xa000
	v_lshl_add_u64 v[220:221], v[220:221], 0, s[14:15]
	global_load_lds_dwordx4 v[224:225], off
	s_add_i32 m0, s27, 0xc000
	s_nop 0
	global_load_lds_dwordx4 v[220:221], off
	v_lshl_add_u64 v[220:221], v[222:223], 0, s[14:15]
	s_add_i32 m0, s27, 0xe000
	s_nop 0
	global_load_lds_dwordx4 v[220:221], off
	s_waitcnt vmcnt(8) lgkmcnt(0)
	s_barrier
; #define PG8_STAGE(bufoff, gbase, voff) do { _Pragma("unroll") for (int _i = 0; _i < 2; ++_i) \
;         __builtin_amdgcn_global_load_lds((const unsigned*)((const char*)(gbase) + (voff)[_i]), (LAS unsigned*)(lds + (bufoff) + ldsw + _i * 8192), 16, 0, 0); } while (0)
; #define PG8_LDA(dst, b, h) do { _Pragma("unroll") for (int m = 0; m < 4; ++m) _Pragma("unroll") for (int k = 0; k < 2; ++k) dst[m][k] = *(const LAS bf16x8*)(lds + PG8_SA(b, h) + aoff + m * 2048 + k * 1024); } while (0)
; #define PG8_MMA(ai, bj, At, Bt) do { __builtin_amdgcn_s_setprio(3); _Pragma("unroll") for (int m = 0; m < 4; ++m) _Pragma("unroll") for (int n = 0; n < 2; ++n) _Pragma("unroll") for (int k = 0; k < 2; ++k) \
;         acc[ai][bj][m][n] = __builtin_amdgcn_mfma_f32_16x16x32_bf16(Bt[n][k], At[m][k], acc[ai][bj][m][n], 0, 0, 0); __builtin_amdgcn_s_setprio(0); } while (0)
; #define PG8_WAIT_V(n) asm volatile("s_waitcnt vmcnt(" #n ")" ::: "memory")
; #define PG8_WAIT_L(n) asm volatile("s_waitcnt lgkmcnt(" #n ")" ::: "memory")
; #define PG8_BAR __builtin_amdgcn_s_barrier()
; #define PG8_SCHED __builtin_amdgcn_sched_barrier(0)
; template <class Epi, class Sched>
; __device__ __forceinline__ void gemm_phase(LAS unsigned char* lds, const Gemm g, const Sched& S, const Epi& E, int tid_in) {
;     ...
;             PG8_WAIT_V(8); PG8_WAIT_L(0); PG8_BAR; PG8_MMA(0, 0, At, B0); PG8_MMA(0, 1, At, B1); PG8_BAR; PG8_SCHED;
;             PG8_LDA(At, 0, 1); PG8_STAGE(PG8_SB(0, 0), b2, voffB); PG8_STAGE(PG8_SB(0, 1), b2 + hstep, voffB);
;             PG8_WAIT_V(6); PG8_WAIT_L(0); PG8_BAR; PG8_MMA(1, 0, At, B0); PG8_MMA(1, 1, At, B1); PG8_BAR; PG8_SCHED;
	s_setprio 3
	v_mfma_f32_16x16x32_bf16 v[124:127], v[154:157], v[188:191], v[124:127]
	v_mfma_f32_16x16x32_bf16 v[120:123], v[162:165], v[188:191], v[120:123]
	v_mfma_f32_16x16x32_bf16 v[108:111], v[154:157], v[196:199], v[108:111]
	v_mfma_f32_16x16x32_bf16 v[104:107], v[162:165], v[196:199], v[104:107]
	v_mfma_f32_16x16x32_bf16 v[92:95], v[154:157], v[204:207], v[92:95]
	v_mfma_f32_16x16x32_bf16 v[88:91], v[162:165], v[204:207], v[88:91]
	v_mfma_f32_16x16x32_bf16 v[76:79], v[154:157], v[212:215], v[76:79]
	v_mfma_f32_16x16x32_bf16 v[72:75], v[162:165], v[212:215], v[72:75]
	v_mfma_f32_16x16x32_bf16 v[124:127], v[158:161], v[192:195], v[124:127]
	v_mfma_f32_16x16x32_bf16 v[120:123], v[166:169], v[192:195], v[120:123]
	v_mfma_f32_16x16x32_bf16 v[108:111], v[158:161], v[200:203], v[108:111]
	v_mfma_f32_16x16x32_bf16 v[104:107], v[166:169], v[200:203], v[104:107]
	v_mfma_f32_16x16x32_bf16 v[92:95], v[158:161], v[208:211], v[92:95]
	v_mfma_f32_16x16x32_bf16 v[88:91], v[166:169], v[208:211], v[88:91]
	v_mfma_f32_16x16x32_bf16 v[76:79], v[158:161], v[216:219], v[76:79]
	v_mfma_f32_16x16x32_bf16 v[72:75], v[166:169], v[216:219], v[72:75]
	s_setprio 0
	s_setprio 3
	v_mfma_f32_16x16x32_bf16 v[116:119], v[170:173], v[188:191], v[116:119]
	v_mfma_f32_16x16x32_bf16 v[112:115], v[178:181], v[188:191], v[112:115]
	v_mfma_f32_16x16x32_bf16 v[100:103], v[170:173], v[196:199], v[100:103]
	v_mfma_f32_16x16x32_bf16 v[96:99], v[178:181], v[196:199], v[96:99]
	v_mfma_f32_16x16x32_bf16 v[84:87], v[170:173], v[204:207], v[84:87]
	v_mfma_f32_16x16x32_bf16 v[80:83], v[178:181], v[204:207], v[80:83]
	v_mfma_f32_16x16x32_bf16 v[68:71], v[170:173], v[212:215], v[68:71]
	v_mfma_f32_16x16x32_bf16 v[64:67], v[178:181], v[212:215], v[64:67]
	v_mfma_f32_16x16x32_bf16 v[116:119], v[174:177], v[192:195], v[116:119]
	v_mfma_f32_16x16x32_bf16 v[112:115], v[182:185], v[192:195], v[112:115]
	v_mfma_f32_16x16x32_bf16 v[100:103], v[174:177], v[200:203], v[100:103]
	v_mfma_f32_16x16x32_bf16 v[96:99], v[182:185], v[200:203], v[96:99]
	v_mfma_f32_16x16x32_bf16 v[84:87], v[174:177], v[208:211], v[84:87]
	v_mfma_f32_16x16x32_bf16 v[80:83], v[182:185], v[208:211], v[80:83]
	v_mfma_f32_16x16x32_bf16 v[68:71], v[174:177], v[216:219], v[68:71]
	v_mfma_f32_16x16x32_bf16 v[64:67], v[182:185], v[216:219], v[64:67]
	s_setprio 0
	s_barrier
	s_add_i32 s70, s44, s38
	v_lshl_add_u64 v[220:221], s[34:35], 0, v[132:133]
	s_mov_b32 m0, s70
	ds_read_b128 v[188:191], v153 offset:16384
	ds_read_b128 v[192:195], v153 offset:17408
	ds_read_b128 v[196:199], v153 offset:18432
	ds_read_b128 v[200:203], v153 offset:19456
	ds_read_b128 v[204:207], v153 offset:20480
	ds_read_b128 v[208:211], v153 offset:21504
	ds_read_b128 v[212:215], v153 offset:22528
	ds_read_b128 v[216:219], v153 offset:23552
	global_load_lds_dwordx4 v[220:221], off
	s_add_i32 m0, s70, 0x2000
	s_add_u32 s70, s34, 0x80000
	v_lshl_add_u64 v[222:223], s[34:35], 0, v[128:129]
	s_addc_u32 s71, s35, 0
	s_add_i32 s72, s45, s38
	global_load_lds_dwordx4 v[222:223], off
	v_lshl_add_u64 v[224:225], s[70:71], 0, v[132:133]
	s_mov_b32 m0, s72
	s_nop 0
	global_load_lds_dwordx4 v[224:225], off
	v_lshl_add_u64 v[224:225], s[70:71], 0, v[128:129]
	s_add_i32 m0, s72, 0x2000
	s_nop 0
	global_load_lds_dwordx4 v[224:225], off
	s_waitcnt vmcnt(6) lgkmcnt(0)
	s_barrier
	s_setprio 3
	v_mfma_f32_16x16x32_bf16 v[60:63], v[154:157], v[188:191], v[60:63]
	v_mfma_f32_16x16x32_bf16 v[56:59], v[162:165], v[188:191], v[56:59]
	v_mfma_f32_16x16x32_bf16 v[44:47], v[154:157], v[196:199], v[44:47]
	v_mfma_f32_16x16x32_bf16 v[40:43], v[162:165], v[196:199], v[40:43]
	v_mfma_f32_16x16x32_bf16 v[28:31], v[154:157], v[204:207], v[28:31]
	v_mfma_f32_16x16x32_bf16 v[24:27], v[162:165], v[204:207], v[24:27]
	v_mfma_f32_16x16x32_bf16 v[12:15], v[154:157], v[212:215], v[12:15]
	v_mfma_f32_16x16x32_bf16 v[8:11], v[162:165], v[212:215], v[8:11]
	v_mfma_f32_16x16x32_bf16 v[60:63], v[158:161], v[192:195], v[60:63]
	v_mfma_f32_16x16x32_bf16 v[56:59], v[166:169], v[192:195], v[56:59]
	v_mfma_f32_16x16x32_bf16 v[44:47], v[158:161], v[200:203], v[44:47]
	v_mfma_f32_16x16x32_bf16 v[40:43], v[166:169], v[200:203], v[40:43]
	v_mfma_f32_16x16x32_bf16 v[28:31], v[158:161], v[208:211], v[28:31]
	v_mfma_f32_16x16x32_bf16 v[24:27], v[166:169], v[208:211], v[24:27]
	v_mfma_f32_16x16x32_bf16 v[12:15], v[158:161], v[216:219], v[12:15]
	v_mfma_f32_16x16x32_bf16 v[8:11], v[166:169], v[216:219], v[8:11]
	s_setprio 0
	s_setprio 3
	v_mfma_f32_16x16x32_bf16 v[52:55], v[170:173], v[188:191], v[52:55]
	v_mfma_f32_16x16x32_bf16 v[48:51], v[178:181], v[188:191], v[48:51]
	v_mfma_f32_16x16x32_bf16 v[36:39], v[170:173], v[196:199], v[36:39]
	v_mfma_f32_16x16x32_bf16 v[32:35], v[178:181], v[196:199], v[32:35]
	v_mfma_f32_16x16x32_bf16 v[20:23], v[170:173], v[204:207], v[20:23]
	v_mfma_f32_16x16x32_bf16 v[16:19], v[178:181], v[204:207], v[16:19]
	v_mfma_f32_16x16x32_bf16 v[4:7], v[170:173], v[212:215], v[4:7]
	v_mfma_f32_16x16x32_bf16 v[0:3], v[178:181], v[212:215], v[0:3]
	v_mfma_f32_16x16x32_bf16 v[52:55], v[174:177], v[192:195], v[52:55]
	v_mfma_f32_16x16x32_bf16 v[48:51], v[182:185], v[192:195], v[48:51]
	v_mfma_f32_16x16x32_bf16 v[36:39], v[174:177], v[200:203], v[36:39]
	v_mfma_f32_16x16x32_bf16 v[32:35], v[182:185], v[200:203], v[32:35]
	v_mfma_f32_16x16x32_bf16 v[20:23], v[174:177], v[208:211], v[20:23]
	v_mfma_f32_16x16x32_bf16 v[16:19], v[182:185], v[208:211], v[16:19]
	v_mfma_f32_16x16x32_bf16 v[4:7], v[174:177], v[216:219], v[4:7]
	v_mfma_f32_16x16x32_bf16 v[0:3], v[182:185], v[216:219], v[0:3]
	s_setprio 0
	s_barrier
; #define PG8_STAGE(bufoff, gbase, voff) do { _Pragma("unroll") for (int _i = 0; _i < 2; ++_i) \
;         __builtin_amdgcn_global_load_lds((const unsigned*)((const char*)(gbase) + (voff)[_i]), (LAS unsigned*)(lds + (bufoff) + ldsw + _i * 8192), 16, 0, 0); } while (0)
; #define PG8_LDA(dst, b, h) do { _Pragma("unroll") for (int m = 0; m < 4; ++m) _Pragma("unroll") for (int k = 0; k < 2; ++k) dst[m][k] = *(const LAS bf16x8*)(lds + PG8_SA(b, h) + aoff + m * 2048 + k * 1024); } while (0)
; #define PG8_LDB(dst, b, h) do { _Pragma("unroll") for (int n = 0; n < 2; ++n) _Pragma("unroll") for (int k = 0; k < 2; ++k) dst[n][k] = *(const LAS bf16x8*)(lds + PG8_SB(b, h) + boff + n * 2048 + k * 1024); } while (0)
; #define PG8_MMA(ai, bj, At, Bt) do { __builtin_amdgcn_s_setprio(3); _Pragma("unroll") for (int m = 0; m < 4; ++m) _Pragma("unroll") for (int n = 0; n < 2; ++n) _Pragma("unroll") for (int k = 0; k < 2; ++k) \
;         acc[ai][bj][m][n] = __builtin_amdgcn_mfma_f32_16x16x32_bf16(Bt[n][k], At[m][k], acc[ai][bj][m][n], 0, 0, 0); __builtin_amdgcn_s_setprio(0); } while (0)
; #define PG8_WAIT_V(n) asm volatile("s_waitcnt vmcnt(" #n ")" ::: "memory")
; #define PG8_WAIT_L(n) asm volatile("s_waitcnt lgkmcnt(" #n ")" ::: "memory")
; #define PG8_BAR __builtin_amdgcn_s_barrier()
; #define PG8_SCHED __builtin_amdgcn_sched_barrier(0)
; template <class Epi, class Sched>
; __device__ __forceinline__ void gemm_phase(LAS unsigned char* lds, const Gemm g, const Sched& S, const Epi& E, int tid_in) {
;     ...
;             PG8_LDB(B0, 1, 0); PG8_LDB(B1, 1, 1); PG8_SCHED; PG8_LDA(At, 1, 0); PG8_STAGE(PG8_SA(0, 0), a2, voffA); PG8_STAGE(PG8_SA(0, 1), a2 + hstep, voffA);
;             PG8_WAIT_V(8); PG8_WAIT_L(0); PG8_BAR; PG8_MMA(0, 0, At, B0); PG8_MMA(0, 1, At, B1); PG8_BAR; PG8_SCHED;
;             PG8_LDA(At, 1, 1); PG8_STAGE(PG8_SB(1, 0), b3, voffB); PG8_STAGE(PG8_SB(1, 1), b3 + hstep, voffB);
;             PG8_WAIT_V(6); PG8_WAIT_L(0); PG8_BAR; PG8_MMA(1, 0, At, B0); PG8_MMA(1, 1, At, B1); PG8_BAR; PG8_SCHED;
	s_add_i32 s70, 0, 0x18000
	s_add_i32 s71, 0, 0x1c000
	v_add_u32_e32 v166, s70, v149
	v_add_u32_e32 v182, s71, v149
	ds_read_b128 v[154:157], v166
	ds_read_b128 v[158:161], v166 offset:1024
	ds_read_b128 v[162:165], v166 offset:2048
	ds_read_b128 v[166:169], v166 offset:3072
	ds_read_b128 v[170:173], v182
	ds_read_b128 v[174:177], v182 offset:1024
	ds_read_b128 v[178:181], v182 offset:2048
	ds_read_b128 v[182:185], v182 offset:3072
	s_mov_b32 m0, s27
	v_lshl_add_u64 v[224:225], s[36:37], 0, v[134:135]
	ds_read_b128 v[188:191], v153 offset:32768
	ds_read_b128 v[192:195], v153 offset:33792
	ds_read_b128 v[196:199], v153 offset:34816
	ds_read_b128 v[200:203], v153 offset:35840
	ds_read_b128 v[204:207], v153 offset:36864
	ds_read_b128 v[208:211], v153 offset:37888
	ds_read_b128 v[212:215], v153 offset:38912
	ds_read_b128 v[216:219], v153 offset:39936
	global_load_lds_dwordx4 v[224:225], off
	v_lshl_add_u64 v[224:225], s[36:37], 0, v[130:131]
	s_add_u32 s36, s36, 0x80000
	s_mov_b32 m0, s40
	s_addc_u32 s37, s37, 0
	global_load_lds_dwordx4 v[224:225], off
	v_lshl_add_u64 v[224:225], s[36:37], 0, v[134:135]
	s_mov_b32 m0, s41
	s_nop 0
	global_load_lds_dwordx4 v[224:225], off
	v_lshl_add_u64 v[224:225], s[36:37], 0, v[130:131]
	s_mov_b32 m0, s42
	s_nop 0
	global_load_lds_dwordx4 v[224:225], off
	s_waitcnt vmcnt(8) lgkmcnt(0)
	s_barrier
	s_setprio 3
	v_mfma_f32_16x16x32_bf16 v[124:127], v[154:157], v[188:191], v[124:127]
	v_mfma_f32_16x16x32_bf16 v[120:123], v[162:165], v[188:191], v[120:123]
	v_mfma_f32_16x16x32_bf16 v[108:111], v[154:157], v[196:199], v[108:111]
	v_mfma_f32_16x16x32_bf16 v[104:107], v[162:165], v[196:199], v[104:107]
	v_mfma_f32_16x16x32_bf16 v[92:95], v[154:157], v[204:207], v[92:95]
	v_mfma_f32_16x16x32_bf16 v[88:91], v[162:165], v[204:207], v[88:91]
	v_mfma_f32_16x16x32_bf16 v[76:79], v[154:157], v[212:215], v[76:79]
	v_mfma_f32_16x16x32_bf16 v[72:75], v[162:165], v[212:215], v[72:75]
	v_mfma_f32_16x16x32_bf16 v[124:127], v[158:161], v[192:195], v[124:127]
	v_mfma_f32_16x16x32_bf16 v[120:123], v[166:169], v[192:195], v[120:123]
	v_mfma_f32_16x16x32_bf16 v[108:111], v[158:161], v[200:203], v[108:111]
	v_mfma_f32_16x16x32_bf16 v[104:107], v[166:169], v[200:203], v[104:107]
	v_mfma_f32_16x16x32_bf16 v[92:95], v[158:161], v[208:211], v[92:95]
	v_mfma_f32_16x16x32_bf16 v[88:91], v[166:169], v[208:211], v[88:91]
	v_mfma_f32_16x16x32_bf16 v[76:79], v[158:161], v[216:219], v[76:79]
	v_mfma_f32_16x16x32_bf16 v[72:75], v[166:169], v[216:219], v[72:75]
	s_setprio 0
	s_setprio 3
	v_mfma_f32_16x16x32_bf16 v[116:119], v[170:173], v[188:191], v[116:119]
	v_mfma_f32_16x16x32_bf16 v[112:115], v[178:181], v[188:191], v[112:115]
	v_mfma_f32_16x16x32_bf16 v[100:103], v[170:173], v[196:199], v[100:103]
	v_mfma_f32_16x16x32_bf16 v[96:99], v[178:181], v[196:199], v[96:99]
	v_mfma_f32_16x16x32_bf16 v[84:87], v[170:173], v[204:207], v[84:87]
	v_mfma_f32_16x16x32_bf16 v[80:83], v[178:181], v[204:207], v[80:83]
	v_mfma_f32_16x16x32_bf16 v[68:71], v[170:173], v[212:215], v[68:71]
	v_mfma_f32_16x16x32_bf16 v[64:67], v[178:181], v[212:215], v[64:67]
	v_mfma_f32_16x16x32_bf16 v[116:119], v[174:177], v[192:195], v[116:119]
	v_mfma_f32_16x16x32_bf16 v[112:115], v[182:185], v[192:195], v[112:115]
	v_mfma_f32_16x16x32_bf16 v[100:103], v[174:177], v[200:203], v[100:103]
	v_mfma_f32_16x16x32_bf16 v[96:99], v[182:185], v[200:203], v[96:99]
	v_mfma_f32_16x16x32_bf16 v[84:87], v[174:177], v[208:211], v[84:87]
	v_mfma_f32_16x16x32_bf16 v[80:83], v[182:185], v[208:211], v[80:83]
	v_mfma_f32_16x16x32_bf16 v[68:71], v[174:177], v[216:219], v[68:71]
	v_mfma_f32_16x16x32_bf16 v[64:67], v[182:185], v[216:219], v[64:67]
	s_setprio 0
	s_barrier
	s_add_i32 s36, s70, s38
	v_lshl_add_u64 v[220:221], v[220:221], 0, s[8:9]
	s_mov_b32 m0, s36
	ds_read_b128 v[188:191], v153 offset:49152
	ds_read_b128 v[192:195], v153 offset:50176
	ds_read_b128 v[196:199], v153 offset:51200
	ds_read_b128 v[200:203], v153 offset:52224
	ds_read_b128 v[204:207], v153 offset:53248
	ds_read_b128 v[208:211], v153 offset:54272
	ds_read_b128 v[212:215], v153 offset:55296
	ds_read_b128 v[216:219], v153 offset:56320
	global_load_lds_dwordx4 v[220:221], off
	s_add_i32 m0, s36, 0x2000
	s_add_u32 s34, s34, 0x80080
	v_lshl_add_u64 v[220:221], v[222:223], 0, s[8:9]
	s_addc_u32 s35, s35, 0
	s_add_i32 s36, s71, s38
	global_load_lds_dwordx4 v[220:221], off
	v_lshl_add_u64 v[220:221], s[34:35], 0, v[132:133]
	s_mov_b32 m0, s36
	s_nop 0
	global_load_lds_dwordx4 v[220:221], off
	v_lshl_add_u64 v[220:221], s[34:35], 0, v[128:129]
	s_add_i32 m0, s36, 0x2000
	s_nop 0
	global_load_lds_dwordx4 v[220:221], off
	s_waitcnt vmcnt(6) lgkmcnt(0)
	s_barrier
	s_setprio 3
	v_mfma_f32_16x16x32_bf16 v[60:63], v[154:157], v[188:191], v[60:63]
	v_mfma_f32_16x16x32_bf16 v[56:59], v[162:165], v[188:191], v[56:59]
	v_mfma_f32_16x16x32_bf16 v[44:47], v[154:157], v[196:199], v[44:47]
	v_mfma_f32_16x16x32_bf16 v[40:43], v[162:165], v[196:199], v[40:43]
	v_mfma_f32_16x16x32_bf16 v[28:31], v[154:157], v[204:207], v[28:31]
	v_mfma_f32_16x16x32_bf16 v[24:27], v[162:165], v[204:207], v[24:27]
	v_mfma_f32_16x16x32_bf16 v[12:15], v[154:157], v[212:215], v[12:15]
	v_mfma_f32_16x16x32_bf16 v[8:11], v[162:165], v[212:215], v[8:11]
	v_mfma_f32_16x16x32_bf16 v[60:63], v[158:161], v[192:195], v[60:63]
	v_mfma_f32_16x16x32_bf16 v[56:59], v[166:169], v[192:195], v[56:59]
	v_mfma_f32_16x16x32_bf16 v[44:47], v[158:161], v[200:203], v[44:47]
	v_mfma_f32_16x16x32_bf16 v[40:43], v[166:169], v[200:203], v[40:43]
	v_mfma_f32_16x16x32_bf16 v[28:31], v[158:161], v[208:211], v[28:31]
	v_mfma_f32_16x16x32_bf16 v[24:27], v[166:169], v[208:211], v[24:27]
	v_mfma_f32_16x16x32_bf16 v[12:15], v[158:161], v[216:219], v[12:15]
	v_mfma_f32_16x16x32_bf16 v[8:11], v[166:169], v[216:219], v[8:11]
	s_setprio 0
	s_setprio 3
	v_mfma_f32_16x16x32_bf16 v[52:55], v[170:173], v[188:191], v[52:55]
	v_mfma_f32_16x16x32_bf16 v[48:51], v[178:181], v[188:191], v[48:51]
	v_mfma_f32_16x16x32_bf16 v[36:39], v[170:173], v[196:199], v[36:39]
	v_mfma_f32_16x16x32_bf16 v[32:35], v[178:181], v[196:199], v[32:35]
	v_mfma_f32_16x16x32_bf16 v[20:23], v[170:173], v[204:207], v[20:23]
	v_mfma_f32_16x16x32_bf16 v[16:19], v[178:181], v[204:207], v[16:19]
	v_mfma_f32_16x16x32_bf16 v[4:7], v[170:173], v[212:215], v[4:7]
	v_mfma_f32_16x16x32_bf16 v[0:3], v[178:181], v[212:215], v[0:3]
	v_mfma_f32_16x16x32_bf16 v[52:55], v[174:177], v[192:195], v[52:55]
	v_mfma_f32_16x16x32_bf16 v[48:51], v[182:185], v[192:195], v[48:51]
	v_mfma_f32_16x16x32_bf16 v[36:39], v[174:177], v[200:203], v[36:39]
	v_mfma_f32_16x16x32_bf16 v[32:35], v[182:185], v[200:203], v[32:35]
	v_mfma_f32_16x16x32_bf16 v[20:23], v[174:177], v[208:211], v[20:23]
	v_mfma_f32_16x16x32_bf16 v[16:19], v[182:185], v[208:211], v[16:19]
	v_mfma_f32_16x16x32_bf16 v[4:7], v[174:177], v[216:219], v[4:7]
	v_mfma_f32_16x16x32_bf16 v[0:3], v[182:185], v[216:219], v[0:3]
	s_setprio 0
	s_barrier
	s_add_i32 s69, s69, 2
	s_add_u32 s30, s30, 0x100
	s_addc_u32 s31, s31, 0
	s_cmp_gt_u32 s69, 29
	s_cbranch_scc0 .LBB0_763

;     __device__ bool next(int i, Unit& u) const { if (!b.next(i >> 1, u)) return false; u.half = i & 1; u.koff = (i & 1) * kbytes; return true; }
; #define PG8_STAGE(bufoff, gbase, voff) do { _Pragma("unroll") for (int _i = 0; _i < 2; ++_i) \
;         __builtin_amdgcn_global_load_lds((const unsigned*)((const char*)(gbase) + (voff)[_i]), (LAS unsigned*)(lds + (bufoff) + ldsw + _i * 8192), 16, 0, 0); } while (0)
; #define PG8_LDA(dst, b, h) do { _Pragma("unroll") for (int m = 0; m < 4; ++m) _Pragma("unroll") for (int k = 0; k < 2; ++k) dst[m][k] = *(const LAS bf16x8*)(lds + PG8_SA(b, h) + aoff + m * 2048 + k * 1024); } while (0)
; #define PG8_LDB(dst, b, h) do { _Pragma("unroll") for (int n = 0; n < 2; ++n) _Pragma("unroll") for (int k = 0; k < 2; ++k) dst[n][k] = *(const LAS bf16x8*)(lds + PG8_SB(b, h) + boff + n * 2048 + k * 1024); } while (0)
; #define PG8_MMA(ai, bj, At, Bt) do { __builtin_amdgcn_s_setprio(3); _Pragma("unroll") for (int m = 0; m < 4; ++m) _Pragma("unroll") for (int n = 0; n < 2; ++n) _Pragma("unroll") for (int k = 0; k < 2; ++k) \
;         acc[ai][bj][m][n] = __builtin_amdgcn_mfma_f32_16x16x32_bf16(Bt[n][k], At[m][k], acc[ai][bj][m][n], 0, 0, 0); __builtin_amdgcn_s_setprio(0); } while (0)
; template <class Epi, class Sched>
; __device__ __forceinline__ void gemm_phase(LAS unsigned char* lds, const Gemm g, const Sched& S, const Epi& E, int tid_in) {
;     ...
;     for (;;) {
;         const bool has_next = S.next(ui + 1, nxt);
;         const char* nA = has_next ? (const char*)g.A + (size_t)nxt.pm * tstep + nxt.koff : cA; const char* nB = has_next ? (const char*)g.Bt + (size_t)nxt.pn * tstep + nxt.koff : cB;
;         for (int t = 0; t < nt; t += 2) {
;             const bool last = (t == nt - 2);
;             const char* a1 = cA + (size_t)(t + 1) * kstep;
;             const char* a2 = last ? nA : cA + (size_t)(t + 2) * kstep; const char* b2 = last ? nB : cB + (size_t)(t + 2) * kstep;
;             const char* a3 = a2 + kstep; const char* b3 = b2 + kstep;
;             PG8_LDB(B0, 0, 0); PG8_LDB(B1, 0, 1); PG8_SCHED; PG8_LDA(At, 0, 0); PG8_STAGE(PG8_SA(1, 0), a1, voffA); PG8_STAGE(PG8_SA(1, 1), a1 + hstep, voffA);
;             PG8_WAIT_V(8); PG8_WAIT_L(0); PG8_BAR; PG8_MMA(0, 0, At, B0); PG8_MMA(0, 1, At, B1); PG8_BAR; PG8_SCHED;
;             PG8_LDA(At, 0, 1); PG8_STAGE(PG8_SB(0, 0), b2, voffB); PG8_STAGE(PG8_SB(0, 1), b2 + hstep, voffB);
.LBB0_841:
	s_add_u32 s46, s28, 0x100
	s_addc_u32 s47, s29, 0
	v_lshl_add_u64 v[144:145], s[26:27], 0, v[136:137]
	v_lshl_add_u64 v[146:147], s[26:27], 0, v[138:139]
	s_mov_b32 s48, -2
	s_mov_b64 s[28:29], 0
	s_waitcnt lgkmcnt(0)
	ds_read_b128 v[156:159], v151
	ds_read_b128 v[160:163], v151 offset:1024
	ds_read_b128 v[164:167], v151 offset:2048
	ds_read_b128 v[168:171], v151 offset:3072
	ds_read_b128 v[172:175], v152
	ds_read_b128 v[176:179], v152 offset:1024
	ds_read_b128 v[180:183], v152 offset:2048
	ds_read_b128 v[188:191], v152 offset:3072
	s_add_u32 s30, s26, s28
	s_addc_u32 s31, s27, s29
	s_add_u32 s34, s30, 0x100
	s_addc_u32 s35, s31, 0
	s_add_u32 s30, s46, s28
	s_addc_u32 s31, s47, s29
	s_cmpk_eq_i32 s28, 0x2b00
	s_cselect_b32 s31, s25, s31
	s_cselect_b32 s30, s24, s30
	s_cselect_b32 s35, s7, s35
	s_cselect_b32 s34, s6, s34
	v_lshl_add_u64 v[184:185], v[144:145], 0, s[28:29]
	v_lshl_add_u64 v[224:225], v[184:185], 0, s[18:19]
	s_add_i32 m0, s3, 0x8000
	ds_read_b128 v[192:195], v153
	ds_read_b128 v[196:199], v153 offset:1024
	ds_read_b128 v[200:203], v153 offset:2048
	ds_read_b128 v[204:207], v153 offset:3072
	ds_read_b128 v[208:211], v153 offset:4096
	ds_read_b128 v[212:215], v153 offset:5120
	ds_read_b128 v[216:219], v153 offset:6144
	ds_read_b128 v[220:223], v153 offset:7168
	global_load_lds_dwordx4 v[224:225], off
	v_lshl_add_u64 v[224:225], v[146:147], 0, s[28:29]
	v_lshl_add_u64 v[226:227], v[224:225], 0, s[18:19]
	s_add_i32 m0, s3, 0xa000
	v_lshl_add_u64 v[184:185], v[184:185], 0, s[20:21]
	global_load_lds_dwordx4 v[226:227], off
	s_add_i32 m0, s3, 0xc000
	s_nop 0
	global_load_lds_dwordx4 v[184:185], off
	v_lshl_add_u64 v[184:185], v[224:225], 0, s[20:21]
	s_add_i32 m0, s3, 0xe000
	s_nop 0
	global_load_lds_dwordx4 v[184:185], off
	s_waitcnt vmcnt(8) lgkmcnt(0)
	s_barrier
	s_setprio 3
	v_mfma_f32_16x16x32_bf16 v[124:127], v[156:159], v[192:195], 0
	v_mfma_f32_16x16x32_bf16 v[120:123], v[164:167], v[192:195], 0
	v_mfma_f32_16x16x32_bf16 v[108:111], v[156:159], v[200:203], 0
	v_mfma_f32_16x16x32_bf16 v[104:107], v[164:167], v[200:203], 0
	v_mfma_f32_16x16x32_bf16 v[92:95], v[156:159], v[208:211], 0
	v_mfma_f32_16x16x32_bf16 v[88:91], v[164:167], v[208:211], 0
	v_mfma_f32_16x16x32_bf16 v[76:79], v[156:159], v[216:219], 0
	v_mfma_f32_16x16x32_bf16 v[72:75], v[164:167], v[216:219], 0
	v_mfma_f32_16x16x32_bf16 v[124:127], v[160:163], v[196:199], v[124:127]
	v_mfma_f32_16x16x32_bf16 v[120:123], v[168:171], v[196:199], v[120:123]
	v_mfma_f32_16x16x32_bf16 v[108:111], v[160:163], v[204:207], v[108:111]
	v_mfma_f32_16x16x32_bf16 v[104:107], v[168:171], v[204:207], v[104:107]
	v_mfma_f32_16x16x32_bf16 v[92:95], v[160:163], v[212:215], v[92:95]
	v_mfma_f32_16x16x32_bf16 v[88:91], v[168:171], v[212:215], v[88:91]
	v_mfma_f32_16x16x32_bf16 v[76:79], v[160:163], v[220:223], v[76:79]
	v_mfma_f32_16x16x32_bf16 v[72:75], v[168:171], v[220:223], v[72:75]
	s_setprio 0
	s_setprio 3
	v_mfma_f32_16x16x32_bf16 v[116:119], v[172:175], v[192:195], 0
	v_mfma_f32_16x16x32_bf16 v[112:115], v[180:183], v[192:195], 0
	v_mfma_f32_16x16x32_bf16 v[100:103], v[172:175], v[200:203], 0
	v_mfma_f32_16x16x32_bf16 v[96:99], v[180:183], v[200:203], 0
	v_mfma_f32_16x16x32_bf16 v[84:87], v[172:175], v[208:211], 0
	v_mfma_f32_16x16x32_bf16 v[80:83], v[180:183], v[208:211], 0
	v_mfma_f32_16x16x32_bf16 v[68:71], v[172:175], v[216:219], 0
	v_mfma_f32_16x16x32_bf16 v[64:67], v[180:183], v[216:219], 0
	v_mfma_f32_16x16x32_bf16 v[116:119], v[176:179], v[196:199], v[116:119]
	v_mfma_f32_16x16x32_bf16 v[112:115], v[188:191], v[196:199], v[112:115]
	v_mfma_f32_16x16x32_bf16 v[100:103], v[176:179], v[204:207], v[100:103]
	v_mfma_f32_16x16x32_bf16 v[96:99], v[188:191], v[204:207], v[96:99]
	v_mfma_f32_16x16x32_bf16 v[84:87], v[176:179], v[212:215], v[84:87]
	v_mfma_f32_16x16x32_bf16 v[80:83], v[188:191], v[212:215], v[80:83]
	v_mfma_f32_16x16x32_bf16 v[68:71], v[176:179], v[220:223], v[68:71]
	v_mfma_f32_16x16x32_bf16 v[64:67], v[188:191], v[220:223], v[64:67]
	s_setprio 0
	s_barrier
	s_add_i32 s49, s40, s2
	v_lshl_add_u64 v[184:185], s[30:31], 0, v[130:131]
	s_mov_b32 m0, s49
	ds_read_b128 v[192:195], v153 offset:16384
	ds_read_b128 v[196:199], v153 offset:17408
	ds_read_b128 v[200:203], v153 offset:18432
	ds_read_b128 v[204:207], v153 offset:19456
	ds_read_b128 v[208:211], v153 offset:20480
	ds_read_b128 v[212:215], v153 offset:21504
	ds_read_b128 v[216:219], v153 offset:22528
	ds_read_b128 v[220:223], v153 offset:23552
	global_load_lds_dwordx4 v[184:185], off
	s_add_i32 m0, s49, 0x2000
	s_add_u32 s68, s30, 0x160000
	v_lshl_add_u64 v[224:225], s[30:31], 0, v[134:135]
	s_addc_u32 s69, s31, 0
	s_add_i32 s49, s41, s2
	global_load_lds_dwordx4 v[224:225], off
	v_lshl_add_u64 v[226:227], s[68:69], 0, v[130:131]
	s_mov_b32 m0, s49
	s_nop 0
	global_load_lds_dwordx4 v[226:227], off
	v_lshl_add_u64 v[226:227], s[68:69], 0, v[134:135]
	s_add_i32 m0, s49, 0x2000
	s_nop 0
	global_load_lds_dwordx4 v[226:227], off
	s_waitcnt vmcnt(6) lgkmcnt(0)
	s_barrier
; #define PG8_STAGE(bufoff, gbase, voff) do { _Pragma("unroll") for (int _i = 0; _i < 2; ++_i) \
;         __builtin_amdgcn_global_load_lds((const unsigned*)((const char*)(gbase) + (voff)[_i]), (LAS unsigned*)(lds + (bufoff) + ldsw + _i * 8192), 16, 0, 0); } while (0)
; #define PG8_LDA(dst, b, h) do { _Pragma("unroll") for (int m = 0; m < 4; ++m) _Pragma("unroll") for (int k = 0; k < 2; ++k) dst[m][k] = *(const LAS bf16x8*)(lds + PG8_SA(b, h) + aoff + m * 2048 + k * 1024); } while (0)
; #define PG8_LDB(dst, b, h) do { _Pragma("unroll") for (int n = 0; n < 2; ++n) _Pragma("unroll") for (int k = 0; k < 2; ++k) dst[n][k] = *(const LAS bf16x8*)(lds + PG8_SB(b, h) + boff + n * 2048 + k * 1024); } while (0)
; #define PG8_MMA(ai, bj, At, Bt) do { __builtin_amdgcn_s_setprio(3); _Pragma("unroll") for (int m = 0; m < 4; ++m) _Pragma("unroll") for (int n = 0; n < 2; ++n) _Pragma("unroll") for (int k = 0; k < 2; ++k) \
;         acc[ai][bj][m][n] = __builtin_amdgcn_mfma_f32_16x16x32_bf16(Bt[n][k], At[m][k], acc[ai][bj][m][n], 0, 0, 0); __builtin_amdgcn_s_setprio(0); } while (0)
; #define PG8_WAIT_V(n) asm volatile("s_waitcnt vmcnt(" #n ")" ::: "memory")
; #define PG8_WAIT_L(n) asm volatile("s_waitcnt lgkmcnt(" #n ")" ::: "memory")
; #define PG8_BAR __builtin_amdgcn_s_barrier()
; #define PG8_SCHED __builtin_amdgcn_sched_barrier(0)
; template <class Epi, class Sched>
; __device__ __forceinline__ void gemm_phase(LAS unsigned char* lds, const Gemm g, const Sched& S, const Epi& E, int tid_in) {
;     ...
;             PG8_WAIT_V(6); PG8_WAIT_L(0); PG8_BAR; PG8_MMA(1, 0, At, B0); PG8_MMA(1, 1, At, B1); PG8_BAR; PG8_SCHED;
;             PG8_LDB(B0, 1, 0); PG8_LDB(B1, 1, 1); PG8_SCHED; PG8_LDA(At, 1, 0); PG8_STAGE(PG8_SA(0, 0), a2, voffA); PG8_STAGE(PG8_SA(0, 1), a2 + hstep, voffA);
;             PG8_WAIT_V(8); PG8_WAIT_L(0); PG8_BAR; PG8_MMA(0, 0, At, B0); PG8_MMA(0, 1, At, B1); PG8_BAR; PG8_SCHED;
	s_setprio 3
	v_mfma_f32_16x16x32_bf16 v[60:63], v[156:159], v[192:195], 0
	v_mfma_f32_16x16x32_bf16 v[56:59], v[164:167], v[192:195], 0
	v_mfma_f32_16x16x32_bf16 v[44:47], v[156:159], v[200:203], 0
	v_mfma_f32_16x16x32_bf16 v[40:43], v[164:167], v[200:203], 0
	v_mfma_f32_16x16x32_bf16 v[28:31], v[156:159], v[208:211], 0
	v_mfma_f32_16x16x32_bf16 v[24:27], v[164:167], v[208:211], 0
	v_mfma_f32_16x16x32_bf16 v[12:15], v[156:159], v[216:219], 0
	v_mfma_f32_16x16x32_bf16 v[8:11], v[164:167], v[216:219], 0
	v_mfma_f32_16x16x32_bf16 v[60:63], v[160:163], v[196:199], v[60:63]
	v_mfma_f32_16x16x32_bf16 v[56:59], v[168:171], v[196:199], v[56:59]
	v_mfma_f32_16x16x32_bf16 v[44:47], v[160:163], v[204:207], v[44:47]
	v_mfma_f32_16x16x32_bf16 v[40:43], v[168:171], v[204:207], v[40:43]
	v_mfma_f32_16x16x32_bf16 v[28:31], v[160:163], v[212:215], v[28:31]
	v_mfma_f32_16x16x32_bf16 v[24:27], v[168:171], v[212:215], v[24:27]
	v_mfma_f32_16x16x32_bf16 v[12:15], v[160:163], v[220:223], v[12:15]
	v_mfma_f32_16x16x32_bf16 v[8:11], v[168:171], v[220:223], v[8:11]
	s_setprio 0
	s_setprio 3
	v_mfma_f32_16x16x32_bf16 v[52:55], v[172:175], v[192:195], 0
	v_mfma_f32_16x16x32_bf16 v[48:51], v[180:183], v[192:195], 0
	v_mfma_f32_16x16x32_bf16 v[36:39], v[172:175], v[200:203], 0
	v_mfma_f32_16x16x32_bf16 v[32:35], v[180:183], v[200:203], 0
	v_mfma_f32_16x16x32_bf16 v[20:23], v[172:175], v[208:211], 0
	v_mfma_f32_16x16x32_bf16 v[16:19], v[180:183], v[208:211], 0
	v_mfma_f32_16x16x32_bf16 v[4:7], v[172:175], v[216:219], 0
	v_mfma_f32_16x16x32_bf16 v[0:3], v[180:183], v[216:219], 0
	v_mfma_f32_16x16x32_bf16 v[52:55], v[176:179], v[196:199], v[52:55]
	v_mfma_f32_16x16x32_bf16 v[48:51], v[188:191], v[196:199], v[48:51]
	v_mfma_f32_16x16x32_bf16 v[36:39], v[176:179], v[204:207], v[36:39]
	v_mfma_f32_16x16x32_bf16 v[32:35], v[188:191], v[204:207], v[32:35]
	v_mfma_f32_16x16x32_bf16 v[20:23], v[176:179], v[212:215], v[20:23]
	v_mfma_f32_16x16x32_bf16 v[16:19], v[188:191], v[212:215], v[16:19]
	v_mfma_f32_16x16x32_bf16 v[4:7], v[176:179], v[220:223], v[4:7]
	v_mfma_f32_16x16x32_bf16 v[0:3], v[188:191], v[220:223], v[0:3]
	s_setprio 0
	s_barrier
	s_add_i32 s49, 0, 0x18000
	v_add_u32_e32 v155, s49, v149
	s_add_i32 s51, 0, 0x1c000
	ds_read_b128 v[156:159], v155
	ds_read_b128 v[160:163], v155 offset:1024
	ds_read_b128 v[164:167], v155 offset:2048
	ds_read_b128 v[168:171], v155 offset:3072
	v_add_u32_e32 v155, s51, v149
	ds_read_b128 v[172:175], v155
	ds_read_b128 v[176:179], v155 offset:1024
	ds_read_b128 v[180:183], v155 offset:2048
	ds_read_b128 v[188:191], v155 offset:3072
	s_mov_b32 m0, s3
	v_lshl_add_u64 v[226:227], s[34:35], 0, v[128:129]
	ds_read_b128 v[192:195], v153 offset:32768
	ds_read_b128 v[196:199], v153 offset:33792
	ds_read_b128 v[200:203], v153 offset:34816
	ds_read_b128 v[204:207], v153 offset:35840
	ds_read_b128 v[208:211], v153 offset:36864
	ds_read_b128 v[212:215], v153 offset:37888
	ds_read_b128 v[216:219], v153 offset:38912
	ds_read_b128 v[220:223], v153 offset:39936
	global_load_lds_dwordx4 v[226:227], off
	v_lshl_add_u64 v[226:227], s[34:35], 0, v[132:133]
	s_add_u32 s34, s34, 0x160000
	s_mov_b32 m0, s36
	s_addc_u32 s35, s35, 0
	global_load_lds_dwordx4 v[226:227], off
	v_lshl_add_u64 v[226:227], s[34:35], 0, v[128:129]
	s_mov_b32 m0, s37
	s_nop 0
	global_load_lds_dwordx4 v[226:227], off
	v_lshl_add_u64 v[226:227], s[34:35], 0, v[132:133]
	s_mov_b32 m0, s38
	s_nop 0
	global_load_lds_dwordx4 v[226:227], off
	s_waitcnt vmcnt(8) lgkmcnt(0)
	s_barrier
	s_setprio 3
	v_mfma_f32_16x16x32_bf16 v[124:127], v[156:159], v[192:195], v[124:127]
	v_mfma_f32_16x16x32_bf16 v[120:123], v[164:167], v[192:195], v[120:123]
	v_mfma_f32_16x16x32_bf16 v[108:111], v[156:159], v[200:203], v[108:111]
	v_mfma_f32_16x16x32_bf16 v[104:107], v[164:167], v[200:203], v[104:107]
	v_mfma_f32_16x16x32_bf16 v[92:95], v[156:159], v[208:211], v[92:95]
	v_mfma_f32_16x16x32_bf16 v[88:91], v[164:167], v[208:211], v[88:91]
	v_mfma_f32_16x16x32_bf16 v[76:79], v[156:159], v[216:219], v[76:79]
	v_mfma_f32_16x16x32_bf16 v[72:75], v[164:167], v[216:219], v[72:75]
	v_mfma_f32_16x16x32_bf16 v[124:127], v[160:163], v[196:199], v[124:127]
	v_mfma_f32_16x16x32_bf16 v[120:123], v[168:171], v[196:199], v[120:123]
	v_mfma_f32_16x16x32_bf16 v[108:111], v[160:163], v[204:207], v[108:111]
	v_mfma_f32_16x16x32_bf16 v[104:107], v[168:171], v[204:207], v[104:107]
	v_mfma_f32_16x16x32_bf16 v[92:95], v[160:163], v[212:215], v[92:95]
	v_mfma_f32_16x16x32_bf16 v[88:91], v[168:171], v[212:215], v[88:91]
	v_mfma_f32_16x16x32_bf16 v[76:79], v[160:163], v[220:223], v[76:79]
	v_mfma_f32_16x16x32_bf16 v[72:75], v[168:171], v[220:223], v[72:75]
	s_setprio 0
	s_setprio 3
	v_mfma_f32_16x16x32_bf16 v[116:119], v[172:175], v[192:195], v[116:119]
	v_mfma_f32_16x16x32_bf16 v[112:115], v[180:183], v[192:195], v[112:115]
	v_mfma_f32_16x16x32_bf16 v[100:103], v[172:175], v[200:203], v[100:103]
	v_mfma_f32_16x16x32_bf16 v[96:99], v[180:183], v[200:203], v[96:99]
	v_mfma_f32_16x16x32_bf16 v[84:87], v[172:175], v[208:211], v[84:87]
	v_mfma_f32_16x16x32_bf16 v[80:83], v[180:183], v[208:211], v[80:83]
	v_mfma_f32_16x16x32_bf16 v[68:71], v[172:175], v[216:219], v[68:71]
	v_mfma_f32_16x16x32_bf16 v[64:67], v[180:183], v[216:219], v[64:67]
	v_mfma_f32_16x16x32_bf16 v[116:119], v[176:179], v[196:199], v[116:119]
	v_mfma_f32_16x16x32_bf16 v[112:115], v[188:191], v[196:199], v[112:115]
	v_mfma_f32_16x16x32_bf16 v[100:103], v[176:179], v[204:207], v[100:103]
	v_mfma_f32_16x16x32_bf16 v[96:99], v[188:191], v[204:207], v[96:99]
	v_mfma_f32_16x16x32_bf16 v[84:87], v[176:179], v[212:215], v[84:87]
	v_mfma_f32_16x16x32_bf16 v[80:83], v[188:191], v[212:215], v[80:83]
	v_mfma_f32_16x16x32_bf16 v[68:71], v[176:179], v[220:223], v[68:71]
	v_mfma_f32_16x16x32_bf16 v[64:67], v[188:191], v[220:223], v[64:67]
	s_setprio 0
	s_barrier
; #define PG8_STAGE(bufoff, gbase, voff) do { _Pragma("unroll") for (int _i = 0; _i < 2; ++_i) \
;         __builtin_amdgcn_global_load_lds((const unsigned*)((const char*)(gbase) + (voff)[_i]), (LAS unsigned*)(lds + (bufoff) + ldsw + _i * 8192), 16, 0, 0); } while (0)
; #define PG8_LDA(dst, b, h) do { _Pragma("unroll") for (int m = 0; m < 4; ++m) _Pragma("unroll") for (int k = 0; k < 2; ++k) dst[m][k] = *(const LAS bf16x8*)(lds + PG8_SA(b, h) + aoff + m * 2048 + k * 1024); } while (0)
; #define PG8_LDB(dst, b, h) do { _Pragma("unroll") for (int n = 0; n < 2; ++n) _Pragma("unroll") for (int k = 0; k < 2; ++k) dst[n][k] = *(const LAS bf16x8*)(lds + PG8_SB(b, h) + boff + n * 2048 + k * 1024); } while (0)
; #define PG8_WAIT_V(n) asm volatile("s_waitcnt vmcnt(" #n ")" ::: "memory")
; #define PG8_BAR __builtin_amdgcn_s_barrier()
; template <class Epi, class Sched>
; __device__ __forceinline__ void gemm_phase(LAS unsigned char* lds, const Gemm g, const Sched& S, const Epi& E, int tid_in) {
;     ...
;         for (int t = 0; t < nt; t += 2) {
;             const bool last = (t == nt - 2);
;             const char* a1 = cA + (size_t)(t + 1) * kstep;
;             const char* a2 = last ? nA : cA + (size_t)(t + 2) * kstep; const char* b2 = last ? nB : cB + (size_t)(t + 2) * kstep;
;             const char* a3 = a2 + kstep; const char* b3 = b2 + kstep;
;             PG8_LDB(B0, 0, 0); PG8_LDB(B1, 0, 1); PG8_SCHED; PG8_LDA(At, 0, 0); PG8_STAGE(PG8_SA(1, 0), a1, voffA); PG8_STAGE(PG8_SA(1, 1), a1 + hstep, voffA);
;             PG8_WAIT_V(8); PG8_WAIT_L(0); PG8_BAR; PG8_MMA(0, 0, At, B0); PG8_MMA(0, 1, At, B1); PG8_BAR; PG8_SCHED;
;             PG8_LDA(At, 0, 1); PG8_STAGE(PG8_SB(0, 0), b2, voffB); PG8_STAGE(PG8_SB(0, 1), b2 + hstep, voffB);
;             PG8_WAIT_V(6); PG8_WAIT_L(0); PG8_BAR; PG8_MMA(1, 0, At, B0); PG8_MMA(1, 1, At, B1); PG8_BAR; PG8_SCHED;
;             PG8_LDB(B0, 1, 0); PG8_LDB(B1, 1, 1); PG8_SCHED; PG8_LDA(At, 1, 0); PG8_STAGE(PG8_SA(0, 0), a2, voffA); PG8_STAGE(PG8_SA(0, 1), a2 + hstep, voffA);
;             PG8_WAIT_V(8); PG8_WAIT_L(0); PG8_BAR; PG8_MMA(0, 0, At, B0); PG8_MMA(0, 1, At, B1); PG8_BAR; PG8_SCHED;
;             PG8_LDA(At, 1, 1); PG8_STAGE(PG8_SB(1, 0), b3, voffB); PG8_STAGE(PG8_SB(1, 1), b3 + hstep, voffB);
;             PG8_WAIT_V(6); PG8_WAIT_L(0); PG8_BAR; PG8_MMA(1, 0, At, B0); PG8_MMA(1, 1, At, B1); PG8_BAR; PG8_SCHED;
	s_add_i32 s34, s49, s2
	v_lshl_add_u64 v[184:185], v[184:185], 0, s[18:19]
	s_mov_b32 m0, s34
	ds_read_b128 v[192:195], v153 offset:49152
	ds_read_b128 v[196:199], v153 offset:50176
	ds_read_b128 v[200:203], v153 offset:51200
	ds_read_b128 v[204:207], v153 offset:52224
	ds_read_b128 v[208:211], v153 offset:53248
	ds_read_b128 v[212:215], v153 offset:54272
	ds_read_b128 v[216:219], v153 offset:55296
	ds_read_b128 v[220:223], v153 offset:56320
	global_load_lds_dwordx4 v[184:185], off
	s_add_i32 m0, s34, 0x2000
	s_add_u32 s30, s30, 0x160080
	v_lshl_add_u64 v[184:185], v[224:225], 0, s[18:19]
	s_addc_u32 s31, s31, 0
	s_add_i32 s34, s51, s2
	global_load_lds_dwordx4 v[184:185], off
	v_lshl_add_u64 v[184:185], s[30:31], 0, v[130:131]
	s_mov_b32 m0, s34
	s_nop 0
	global_load_lds_dwordx4 v[184:185], off
	v_lshl_add_u64 v[184:185], s[30:31], 0, v[134:135]
	s_add_i32 m0, s34, 0x2000
	s_nop 0
	global_load_lds_dwordx4 v[184:185], off
	s_waitcnt vmcnt(6) lgkmcnt(0)
	s_barrier
	s_setprio 3
	v_mfma_f32_16x16x32_bf16 v[60:63], v[156:159], v[192:195], v[60:63]
	v_mfma_f32_16x16x32_bf16 v[56:59], v[164:167], v[192:195], v[56:59]
	v_mfma_f32_16x16x32_bf16 v[44:47], v[156:159], v[200:203], v[44:47]
	v_mfma_f32_16x16x32_bf16 v[40:43], v[164:167], v[200:203], v[40:43]
	v_mfma_f32_16x16x32_bf16 v[28:31], v[156:159], v[208:211], v[28:31]
	v_mfma_f32_16x16x32_bf16 v[24:27], v[164:167], v[208:211], v[24:27]
	v_mfma_f32_16x16x32_bf16 v[12:15], v[156:159], v[216:219], v[12:15]
	v_mfma_f32_16x16x32_bf16 v[8:11], v[164:167], v[216:219], v[8:11]
	v_mfma_f32_16x16x32_bf16 v[60:63], v[160:163], v[196:199], v[60:63]
	v_mfma_f32_16x16x32_bf16 v[56:59], v[168:171], v[196:199], v[56:59]
	v_mfma_f32_16x16x32_bf16 v[44:47], v[160:163], v[204:207], v[44:47]
	v_mfma_f32_16x16x32_bf16 v[40:43], v[168:171], v[204:207], v[40:43]
	v_mfma_f32_16x16x32_bf16 v[28:31], v[160:163], v[212:215], v[28:31]
	v_mfma_f32_16x16x32_bf16 v[24:27], v[168:171], v[212:215], v[24:27]
	v_mfma_f32_16x16x32_bf16 v[12:15], v[160:163], v[220:223], v[12:15]
	v_mfma_f32_16x16x32_bf16 v[8:11], v[168:171], v[220:223], v[8:11]
	s_setprio 0
	s_setprio 3
	v_mfma_f32_16x16x32_bf16 v[52:55], v[172:175], v[192:195], v[52:55]
	v_mfma_f32_16x16x32_bf16 v[48:51], v[180:183], v[192:195], v[48:51]
	v_mfma_f32_16x16x32_bf16 v[36:39], v[172:175], v[200:203], v[36:39]
	v_mfma_f32_16x16x32_bf16 v[32:35], v[180:183], v[200:203], v[32:35]
	v_mfma_f32_16x16x32_bf16 v[20:23], v[172:175], v[208:211], v[20:23]
	v_mfma_f32_16x16x32_bf16 v[16:19], v[180:183], v[208:211], v[16:19]
	v_mfma_f32_16x16x32_bf16 v[4:7], v[172:175], v[216:219], v[4:7]
	v_mfma_f32_16x16x32_bf16 v[0:3], v[180:183], v[216:219], v[0:3]
	v_mfma_f32_16x16x32_bf16 v[52:55], v[176:179], v[196:199], v[52:55]
	v_mfma_f32_16x16x32_bf16 v[48:51], v[188:191], v[196:199], v[48:51]
	v_mfma_f32_16x16x32_bf16 v[36:39], v[176:179], v[204:207], v[36:39]
	v_mfma_f32_16x16x32_bf16 v[32:35], v[188:191], v[204:207], v[32:35]
	v_mfma_f32_16x16x32_bf16 v[20:23], v[176:179], v[212:215], v[20:23]
	v_mfma_f32_16x16x32_bf16 v[16:19], v[188:191], v[212:215], v[16:19]
	v_mfma_f32_16x16x32_bf16 v[4:7], v[176:179], v[220:223], v[4:7]
	v_mfma_f32_16x16x32_bf16 v[0:3], v[188:191], v[220:223], v[0:3]
	s_setprio 0
	s_barrier
	s_add_i32 s48, s48, 2
	s_add_u32 s28, s28, 0x100
	s_addc_u32 s29, s29, 0
	s_cmpk_gt_u32 s48, 0x55
	s_cbranch_scc0 .LBB0_842
	s_branch .Lpeel_exit_3
.LBB0_842:
	ds_read_b128 v[156:159], v151
	ds_read_b128 v[160:163], v151 offset:1024
	ds_read_b128 v[164:167], v151 offset:2048
	ds_read_b128 v[168:171], v151 offset:3072
	ds_read_b128 v[172:175], v152
	ds_read_b128 v[176:179], v152 offset:1024
	ds_read_b128 v[180:183], v152 offset:2048
	ds_read_b128 v[188:191], v152 offset:3072
	s_add_u32 s30, s26, s28
	s_addc_u32 s31, s27, s29
	s_add_u32 s34, s30, 0x100
	s_addc_u32 s35, s31, 0
	s_add_u32 s30, s46, s28
	s_addc_u32 s31, s47, s29
	s_cmpk_eq_i32 s28, 0x2b00
	s_cselect_b32 s31, s25, s31
	s_cselect_b32 s30, s24, s30
	s_cselect_b32 s35, s7, s35
	s_cselect_b32 s34, s6, s34
	v_lshl_add_u64 v[184:185], v[144:145], 0, s[28:29]
	v_lshl_add_u64 v[224:225], v[184:185], 0, s[18:19]
	s_add_i32 m0, s3, 0x8000
	ds_read_b128 v[192:195], v153
	ds_read_b128 v[196:199], v153 offset:1024
	ds_read_b128 v[200:203], v153 offset:2048
	ds_read_b128 v[204:207], v153 offset:3072
	ds_read_b128 v[208:211], v153 offset:4096
	ds_read_b128 v[212:215], v153 offset:5120
	ds_read_b128 v[216:219], v153 offset:6144
	ds_read_b128 v[220:223], v153 offset:7168
	global_load_lds_dwordx4 v[224:225], off
	v_lshl_add_u64 v[224:225], v[146:147], 0, s[28:29]
	v_lshl_add_u64 v[226:227], v[224:225], 0, s[18:19]
	s_add_i32 m0, s3, 0xa000
	v_lshl_add_u64 v[184:185], v[184:185], 0, s[20:21]
	global_load_lds_dwordx4 v[226:227], off
	s_add_i32 m0, s3, 0xc000
	s_nop 0
	global_load_lds_dwordx4 v[184:185], off
	v_lshl_add_u64 v[184:185], v[224:225], 0, s[20:21]
	s_add_i32 m0, s3, 0xe000
	s_nop 0
	global_load_lds_dwordx4 v[184:185], off
	s_waitcnt vmcnt(8) lgkmcnt(0)
	s_barrier
; #define PG8_STAGE(bufoff, gbase, voff) do { _Pragma("unroll") for (int _i = 0; _i < 2; ++_i) \
;         __builtin_amdgcn_global_load_lds((const unsigned*)((const char*)(gbase) + (voff)[_i]), (LAS unsigned*)(lds + (bufoff) + ldsw + _i * 8192), 16, 0, 0); } while (0)
; #define PG8_LDA(dst, b, h) do { _Pragma("unroll") for (int m = 0; m < 4; ++m) _Pragma("unroll") for (int k = 0; k < 2; ++k) dst[m][k] = *(const LAS bf16x8*)(lds + PG8_SA(b, h) + aoff + m * 2048 + k * 1024); } while (0)
; #define PG8_MMA(ai, bj, At, Bt) do { __builtin_amdgcn_s_setprio(3); _Pragma("unroll") for (int m = 0; m < 4; ++m) _Pragma("unroll") for (int n = 0; n < 2; ++n) _Pragma("unroll") for (int k = 0; k < 2; ++k) \
;         acc[ai][bj][m][n] = __builtin_amdgcn_mfma_f32_16x16x32_bf16(Bt[n][k], At[m][k], acc[ai][bj][m][n], 0, 0, 0); __builtin_amdgcn_s_setprio(0); } while (0)
; #define PG8_WAIT_V(n) asm volatile("s_waitcnt vmcnt(" #n ")" ::: "memory")
; #define PG8_WAIT_L(n) asm volatile("s_waitcnt lgkmcnt(" #n ")" ::: "memory")
; #define PG8_BAR __builtin_amdgcn_s_barrier()
; #define PG8_SCHED __builtin_amdgcn_sched_barrier(0)
; template <class Epi, class Sched>
; __device__ __forceinline__ void gemm_phase(LAS unsigned char* lds, const Gemm g, const Sched& S, const Epi& E, int tid_in) {
;     ...
;             PG8_WAIT_V(8); PG8_WAIT_L(0); PG8_BAR; PG8_MMA(0, 0, At, B0); PG8_MMA(0, 1, At, B1); PG8_BAR; PG8_SCHED;
;             PG8_LDA(At, 0, 1); PG8_STAGE(PG8_SB(0, 0), b2, voffB); PG8_STAGE(PG8_SB(0, 1), b2 + hstep, voffB);
;             PG8_WAIT_V(6); PG8_WAIT_L(0); PG8_BAR; PG8_MMA(1, 0, At, B0); PG8_MMA(1, 1, At, B1); PG8_BAR; PG8_SCHED;
	s_setprio 3
	v_mfma_f32_16x16x32_bf16 v[124:127], v[156:159], v[192:195], v[124:127]
	v_mfma_f32_16x16x32_bf16 v[120:123], v[164:167], v[192:195], v[120:123]
	v_mfma_f32_16x16x32_bf16 v[108:111], v[156:159], v[200:203], v[108:111]
	v_mfma_f32_16x16x32_bf16 v[104:107], v[164:167], v[200:203], v[104:107]
	v_mfma_f32_16x16x32_bf16 v[92:95], v[156:159], v[208:211], v[92:95]
	v_mfma_f32_16x16x32_bf16 v[88:91], v[164:167], v[208:211], v[88:91]
	v_mfma_f32_16x16x32_bf16 v[76:79], v[156:159], v[216:219], v[76:79]
	v_mfma_f32_16x16x32_bf16 v[72:75], v[164:167], v[216:219], v[72:75]
	v_mfma_f32_16x16x32_bf16 v[124:127], v[160:163], v[196:199], v[124:127]
	v_mfma_f32_16x16x32_bf16 v[120:123], v[168:171], v[196:199], v[120:123]
	v_mfma_f32_16x16x32_bf16 v[108:111], v[160:163], v[204:207], v[108:111]
	v_mfma_f32_16x16x32_bf16 v[104:107], v[168:171], v[204:207], v[104:107]
	v_mfma_f32_16x16x32_bf16 v[92:95], v[160:163], v[212:215], v[92:95]
	v_mfma_f32_16x16x32_bf16 v[88:91], v[168:171], v[212:215], v[88:91]
	v_mfma_f32_16x16x32_bf16 v[76:79], v[160:163], v[220:223], v[76:79]
	v_mfma_f32_16x16x32_bf16 v[72:75], v[168:171], v[220:223], v[72:75]
	s_setprio 0
	s_setprio 3
	v_mfma_f32_16x16x32_bf16 v[116:119], v[172:175], v[192:195], v[116:119]
	v_mfma_f32_16x16x32_bf16 v[112:115], v[180:183], v[192:195], v[112:115]
	v_mfma_f32_16x16x32_bf16 v[100:103], v[172:175], v[200:203], v[100:103]
	v_mfma_f32_16x16x32_bf16 v[96:99], v[180:183], v[200:203], v[96:99]
	v_mfma_f32_16x16x32_bf16 v[84:87], v[172:175], v[208:211], v[84:87]
	v_mfma_f32_16x16x32_bf16 v[80:83], v[180:183], v[208:211], v[80:83]
	v_mfma_f32_16x16x32_bf16 v[68:71], v[172:175], v[216:219], v[68:71]
	v_mfma_f32_16x16x32_bf16 v[64:67], v[180:183], v[216:219], v[64:67]
	v_mfma_f32_16x16x32_bf16 v[116:119], v[176:179], v[196:199], v[116:119]
	v_mfma_f32_16x16x32_bf16 v[112:115], v[188:191], v[196:199], v[112:115]
	v_mfma_f32_16x16x32_bf16 v[100:103], v[176:179], v[204:207], v[100:103]
	v_mfma_f32_16x16x32_bf16 v[96:99], v[188:191], v[204:207], v[96:99]
	v_mfma_f32_16x16x32_bf16 v[84:87], v[176:179], v[212:215], v[84:87]
	v_mfma_f32_16x16x32_bf16 v[80:83], v[188:191], v[212:215], v[80:83]
	v_mfma_f32_16x16x32_bf16 v[68:71], v[176:179], v[220:223], v[68:71]
	v_mfma_f32_16x16x32_bf16 v[64:67], v[188:191], v[220:223], v[64:67]
	s_setprio 0
	s_barrier
	s_add_i32 s49, s40, s2
	v_lshl_add_u64 v[184:185], s[30:31], 0, v[130:131]
	s_mov_b32 m0, s49
	ds_read_b128 v[192:195], v153 offset:16384
	ds_read_b128 v[196:199], v153 offset:17408
	ds_read_b128 v[200:203], v153 offset:18432
	ds_read_b128 v[204:207], v153 offset:19456
	ds_read_b128 v[208:211], v153 offset:20480
	ds_read_b128 v[212:215], v153 offset:21504
	ds_read_b128 v[216:219], v153 offset:22528
	ds_read_b128 v[220:223], v153 offset:23552
	global_load_lds_dwordx4 v[184:185], off
	s_add_i32 m0, s49, 0x2000
	s_add_u32 s68, s30, 0x160000
	v_lshl_add_u64 v[224:225], s[30:31], 0, v[134:135]
	s_addc_u32 s69, s31, 0
	s_add_i32 s49, s41, s2
	global_load_lds_dwordx4 v[224:225], off
	v_lshl_add_u64 v[226:227], s[68:69], 0, v[130:131]
	s_mov_b32 m0, s49
	s_nop 0
	global_load_lds_dwordx4 v[226:227], off
	v_lshl_add_u64 v[226:227], s[68:69], 0, v[134:135]
	s_add_i32 m0, s49, 0x2000
	s_nop 0
	global_load_lds_dwordx4 v[226:227], off
	s_waitcnt vmcnt(6) lgkmcnt(0)
	s_barrier
	s_setprio 3
	v_mfma_f32_16x16x32_bf16 v[60:63], v[156:159], v[192:195], v[60:63]
	v_mfma_f32_16x16x32_bf16 v[56:59], v[164:167], v[192:195], v[56:59]
	v_mfma_f32_16x16x32_bf16 v[44:47], v[156:159], v[200:203], v[44:47]
	v_mfma_f32_16x16x32_bf16 v[40:43], v[164:167], v[200:203], v[40:43]
	v_mfma_f32_16x16x32_bf16 v[28:31], v[156:159], v[208:211], v[28:31]
	v_mfma_f32_16x16x32_bf16 v[24:27], v[164:167], v[208:211], v[24:27]
	v_mfma_f32_16x16x32_bf16 v[12:15], v[156:159], v[216:219], v[12:15]
	v_mfma_f32_16x16x32_bf16 v[8:11], v[164:167], v[216:219], v[8:11]
	v_mfma_f32_16x16x32_bf16 v[60:63], v[160:163], v[196:199], v[60:63]
	v_mfma_f32_16x16x32_bf16 v[56:59], v[168:171], v[196:199], v[56:59]
	v_mfma_f32_16x16x32_bf16 v[44:47], v[160:163], v[204:207], v[44:47]
	v_mfma_f32_16x16x32_bf16 v[40:43], v[168:171], v[204:207], v[40:43]
	v_mfma_f32_16x16x32_bf16 v[28:31], v[160:163], v[212:215], v[28:31]
	v_mfma_f32_16x16x32_bf16 v[24:27], v[168:171], v[212:215], v[24:27]
	v_mfma_f32_16x16x32_bf16 v[12:15], v[160:163], v[220:223], v[12:15]
	v_mfma_f32_16x16x32_bf16 v[8:11], v[168:171], v[220:223], v[8:11]
	s_setprio 0
	s_setprio 3
	v_mfma_f32_16x16x32_bf16 v[52:55], v[172:175], v[192:195], v[52:55]
	v_mfma_f32_16x16x32_bf16 v[48:51], v[180:183], v[192:195], v[48:51]
	v_mfma_f32_16x16x32_bf16 v[36:39], v[172:175], v[200:203], v[36:39]
	v_mfma_f32_16x16x32_bf16 v[32:35], v[180:183], v[200:203], v[32:35]
	v_mfma_f32_16x16x32_bf16 v[20:23], v[172:175], v[208:211], v[20:23]
	v_mfma_f32_16x16x32_bf16 v[16:19], v[180:183], v[208:211], v[16:19]
	v_mfma_f32_16x16x32_bf16 v[4:7], v[172:175], v[216:219], v[4:7]
	v_mfma_f32_16x16x32_bf16 v[0:3], v[180:183], v[216:219], v[0:3]
	v_mfma_f32_16x16x32_bf16 v[52:55], v[176:179], v[196:199], v[52:55]
	v_mfma_f32_16x16x32_bf16 v[48:51], v[188:191], v[196:199], v[48:51]
	v_mfma_f32_16x16x32_bf16 v[36:39], v[176:179], v[204:207], v[36:39]
	v_mfma_f32_16x16x32_bf16 v[32:35], v[188:191], v[204:207], v[32:35]
	v_mfma_f32_16x16x32_bf16 v[20:23], v[176:179], v[212:215], v[20:23]
	v_mfma_f32_16x16x32_bf16 v[16:19], v[188:191], v[212:215], v[16:19]
	v_mfma_f32_16x16x32_bf16 v[4:7], v[176:179], v[220:223], v[4:7]
	v_mfma_f32_16x16x32_bf16 v[0:3], v[188:191], v[220:223], v[0:3]
	s_setprio 0
	s_barrier
; #define PG8_STAGE(bufoff, gbase, voff) do { _Pragma("unroll") for (int _i = 0; _i < 2; ++_i) \
;         __builtin_amdgcn_global_load_lds((const unsigned*)((const char*)(gbase) + (voff)[_i]), (LAS unsigned*)(lds + (bufoff) + ldsw + _i * 8192), 16, 0, 0); } while (0)
; #define PG8_LDA(dst, b, h) do { _Pragma("unroll") for (int m = 0; m < 4; ++m) _Pragma("unroll") for (int k = 0; k < 2; ++k) dst[m][k] = *(const LAS bf16x8*)(lds + PG8_SA(b, h) + aoff + m * 2048 + k * 1024); } while (0)
; #define PG8_LDB(dst, b, h) do { _Pragma("unroll") for (int n = 0; n < 2; ++n) _Pragma("unroll") for (int k = 0; k < 2; ++k) dst[n][k] = *(const LAS bf16x8*)(lds + PG8_SB(b, h) + boff + n * 2048 + k * 1024); } while (0)
; #define PG8_MMA(ai, bj, At, Bt) do { __builtin_amdgcn_s_setprio(3); _Pragma("unroll") for (int m = 0; m < 4; ++m) _Pragma("unroll") for (int n = 0; n < 2; ++n) _Pragma("unroll") for (int k = 0; k < 2; ++k) \
;         acc[ai][bj][m][n] = __builtin_amdgcn_mfma_f32_16x16x32_bf16(Bt[n][k], At[m][k], acc[ai][bj][m][n], 0, 0, 0); __builtin_amdgcn_s_setprio(0); } while (0)
; #define PG8_WAIT_V(n) asm volatile("s_waitcnt vmcnt(" #n ")" ::: "memory")
; #define PG8_WAIT_L(n) asm volatile("s_waitcnt lgkmcnt(" #n ")" ::: "memory")
; #define PG8_BAR __builtin_amdgcn_s_barrier()
; #define PG8_SCHED __builtin_amdgcn_sched_barrier(0)
; template <class Epi, class Sched>
; __device__ __forceinline__ void gemm_phase(LAS unsigned char* lds, const Gemm g, const Sched& S, const Epi& E, int tid_in) {
;     ...
;             PG8_LDB(B0, 1, 0); PG8_LDB(B1, 1, 1); PG8_SCHED; PG8_LDA(At, 1, 0); PG8_STAGE(PG8_SA(0, 0), a2, voffA); PG8_STAGE(PG8_SA(0, 1), a2 + hstep, voffA);
;             PG8_WAIT_V(8); PG8_WAIT_L(0); PG8_BAR; PG8_MMA(0, 0, At, B0); PG8_MMA(0, 1, At, B1); PG8_BAR; PG8_SCHED;
;             PG8_LDA(At, 1, 1); PG8_STAGE(PG8_SB(1, 0), b3, voffB); PG8_STAGE(PG8_SB(1, 1), b3 + hstep, voffB);
;             PG8_WAIT_V(6); PG8_WAIT_L(0); PG8_BAR; PG8_MMA(1, 0, At, B0); PG8_MMA(1, 1, At, B1); PG8_BAR; PG8_SCHED;
;         }
	s_add_i32 s49, 0, 0x18000
	v_add_u32_e32 v155, s49, v149
	s_add_i32 s51, 0, 0x1c000
	ds_read_b128 v[156:159], v155
	ds_read_b128 v[160:163], v155 offset:1024
	ds_read_b128 v[164:167], v155 offset:2048
	ds_read_b128 v[168:171], v155 offset:3072
	v_add_u32_e32 v155, s51, v149
	ds_read_b128 v[172:175], v155
	ds_read_b128 v[176:179], v155 offset:1024
	ds_read_b128 v[180:183], v155 offset:2048
	ds_read_b128 v[188:191], v155 offset:3072
	s_mov_b32 m0, s3
	v_lshl_add_u64 v[226:227], s[34:35], 0, v[128:129]
	ds_read_b128 v[192:195], v153 offset:32768
	ds_read_b128 v[196:199], v153 offset:33792
	ds_read_b128 v[200:203], v153 offset:34816
	ds_read_b128 v[204:207], v153 offset:35840
	ds_read_b128 v[208:211], v153 offset:36864
	ds_read_b128 v[212:215], v153 offset:37888
	ds_read_b128 v[216:219], v153 offset:38912
	ds_read_b128 v[220:223], v153 offset:39936
	global_load_lds_dwordx4 v[226:227], off
	v_lshl_add_u64 v[226:227], s[34:35], 0, v[132:133]
	s_add_u32 s34, s34, 0x160000
	s_mov_b32 m0, s36
	s_addc_u32 s35, s35, 0
	global_load_lds_dwordx4 v[226:227], off
	v_lshl_add_u64 v[226:227], s[34:35], 0, v[128:129]
	s_mov_b32 m0, s37
	s_nop 0
	global_load_lds_dwordx4 v[226:227], off
	v_lshl_add_u64 v[226:227], s[34:35], 0, v[132:133]
	s_mov_b32 m0, s38
	s_nop 0
	global_load_lds_dwordx4 v[226:227], off
	s_waitcnt vmcnt(8) lgkmcnt(0)
	s_barrier
	s_setprio 3
	v_mfma_f32_16x16x32_bf16 v[124:127], v[156:159], v[192:195], v[124:127]
	v_mfma_f32_16x16x32_bf16 v[120:123], v[164:167], v[192:195], v[120:123]
	v_mfma_f32_16x16x32_bf16 v[108:111], v[156:159], v[200:203], v[108:111]
	v_mfma_f32_16x16x32_bf16 v[104:107], v[164:167], v[200:203], v[104:107]
	v_mfma_f32_16x16x32_bf16 v[92:95], v[156:159], v[208:211], v[92:95]
	v_mfma_f32_16x16x32_bf16 v[88:91], v[164:167], v[208:211], v[88:91]
	v_mfma_f32_16x16x32_bf16 v[76:79], v[156:159], v[216:219], v[76:79]
	v_mfma_f32_16x16x32_bf16 v[72:75], v[164:167], v[216:219], v[72:75]
	v_mfma_f32_16x16x32_bf16 v[124:127], v[160:163], v[196:199], v[124:127]
	v_mfma_f32_16x16x32_bf16 v[120:123], v[168:171], v[196:199], v[120:123]
	v_mfma_f32_16x16x32_bf16 v[108:111], v[160:163], v[204:207], v[108:111]
	v_mfma_f32_16x16x32_bf16 v[104:107], v[168:171], v[204:207], v[104:107]
	v_mfma_f32_16x16x32_bf16 v[92:95], v[160:163], v[212:215], v[92:95]
	v_mfma_f32_16x16x32_bf16 v[88:91], v[168:171], v[212:215], v[88:91]
	v_mfma_f32_16x16x32_bf16 v[76:79], v[160:163], v[220:223], v[76:79]
	v_mfma_f32_16x16x32_bf16 v[72:75], v[168:171], v[220:223], v[72:75]
	s_setprio 0
	s_setprio 3
	v_mfma_f32_16x16x32_bf16 v[116:119], v[172:175], v[192:195], v[116:119]
	v_mfma_f32_16x16x32_bf16 v[112:115], v[180:183], v[192:195], v[112:115]
	v_mfma_f32_16x16x32_bf16 v[100:103], v[172:175], v[200:203], v[100:103]
	v_mfma_f32_16x16x32_bf16 v[96:99], v[180:183], v[200:203], v[96:99]
	v_mfma_f32_16x16x32_bf16 v[84:87], v[172:175], v[208:211], v[84:87]
	v_mfma_f32_16x16x32_bf16 v[80:83], v[180:183], v[208:211], v[80:83]
	v_mfma_f32_16x16x32_bf16 v[68:71], v[172:175], v[216:219], v[68:71]
	v_mfma_f32_16x16x32_bf16 v[64:67], v[180:183], v[216:219], v[64:67]
	v_mfma_f32_16x16x32_bf16 v[116:119], v[176:179], v[196:199], v[116:119]
	v_mfma_f32_16x16x32_bf16 v[112:115], v[188:191], v[196:199], v[112:115]
	v_mfma_f32_16x16x32_bf16 v[100:103], v[176:179], v[204:207], v[100:103]
	v_mfma_f32_16x16x32_bf16 v[96:99], v[188:191], v[204:207], v[96:99]
	v_mfma_f32_16x16x32_bf16 v[84:87], v[176:179], v[212:215], v[84:87]
	v_mfma_f32_16x16x32_bf16 v[80:83], v[188:191], v[212:215], v[80:83]
	v_mfma_f32_16x16x32_bf16 v[68:71], v[176:179], v[220:223], v[68:71]
	v_mfma_f32_16x16x32_bf16 v[64:67], v[188:191], v[220:223], v[64:67]
	s_setprio 0
	s_barrier
	s_add_i32 s34, s49, s2
	v_lshl_add_u64 v[184:185], v[184:185], 0, s[18:19]
	s_mov_b32 m0, s34
	ds_read_b128 v[192:195], v153 offset:49152
	ds_read_b128 v[196:199], v153 offset:50176
	ds_read_b128 v[200:203], v153 offset:51200
	ds_read_b128 v[204:207], v153 offset:52224
	ds_read_b128 v[208:211], v153 offset:53248
	ds_read_b128 v[212:215], v153 offset:54272
	ds_read_b128 v[216:219], v153 offset:55296
	ds_read_b128 v[220:223], v153 offset:56320
	global_load_lds_dwordx4 v[184:185], off
	s_add_i32 m0, s34, 0x2000
	s_add_u32 s30, s30, 0x160080
	v_lshl_add_u64 v[184:185], v[224:225], 0, s[18:19]
	s_addc_u32 s31, s31, 0
	s_add_i32 s34, s51, s2
	global_load_lds_dwordx4 v[184:185], off
	v_lshl_add_u64 v[184:185], s[30:31], 0, v[130:131]
	s_mov_b32 m0, s34
	s_nop 0
	global_load_lds_dwordx4 v[184:185], off
	v_lshl_add_u64 v[184:185], s[30:31], 0, v[134:135]
	s_add_i32 m0, s34, 0x2000
	s_nop 0
	global_load_lds_dwordx4 v[184:185], off
	s_waitcnt vmcnt(6) lgkmcnt(0)
	s_barrier
	s_setprio 3
	v_mfma_f32_16x16x32_bf16 v[60:63], v[156:159], v[192:195], v[60:63]
	v_mfma_f32_16x16x32_bf16 v[56:59], v[164:167], v[192:195], v[56:59]
	v_mfma_f32_16x16x32_bf16 v[44:47], v[156:159], v[200:203], v[44:47]
	v_mfma_f32_16x16x32_bf16 v[40:43], v[164:167], v[200:203], v[40:43]
	v_mfma_f32_16x16x32_bf16 v[28:31], v[156:159], v[208:211], v[28:31]
	v_mfma_f32_16x16x32_bf16 v[24:27], v[164:167], v[208:211], v[24:27]
	v_mfma_f32_16x16x32_bf16 v[12:15], v[156:159], v[216:219], v[12:15]
	v_mfma_f32_16x16x32_bf16 v[8:11], v[164:167], v[216:219], v[8:11]
	v_mfma_f32_16x16x32_bf16 v[60:63], v[160:163], v[196:199], v[60:63]
	v_mfma_f32_16x16x32_bf16 v[56:59], v[168:171], v[196:199], v[56:59]
	v_mfma_f32_16x16x32_bf16 v[44:47], v[160:163], v[204:207], v[44:47]
	v_mfma_f32_16x16x32_bf16 v[40:43], v[168:171], v[204:207], v[40:43]
	v_mfma_f32_16x16x32_bf16 v[28:31], v[160:163], v[212:215], v[28:31]
	v_mfma_f32_16x16x32_bf16 v[24:27], v[168:171], v[212:215], v[24:27]
	v_mfma_f32_16x16x32_bf16 v[12:15], v[160:163], v[220:223], v[12:15]
	v_mfma_f32_16x16x32_bf16 v[8:11], v[168:171], v[220:223], v[8:11]
	s_setprio 0
	s_setprio 3
	v_mfma_f32_16x16x32_bf16 v[52:55], v[172:175], v[192:195], v[52:55]
	v_mfma_f32_16x16x32_bf16 v[48:51], v[180:183], v[192:195], v[48:51]
	v_mfma_f32_16x16x32_bf16 v[36:39], v[172:175], v[200:203], v[36:39]
	v_mfma_f32_16x16x32_bf16 v[32:35], v[180:183], v[200:203], v[32:35]
	v_mfma_f32_16x16x32_bf16 v[20:23], v[172:175], v[208:211], v[20:23]
	v_mfma_f32_16x16x32_bf16 v[16:19], v[180:183], v[208:211], v[16:19]
	v_mfma_f32_16x16x32_bf16 v[4:7], v[172:175], v[216:219], v[4:7]
	v_mfma_f32_16x16x32_bf16 v[0:3], v[180:183], v[216:219], v[0:3]
	v_mfma_f32_16x16x32_bf16 v[52:55], v[176:179], v[196:199], v[52:55]
	v_mfma_f32_16x16x32_bf16 v[48:51], v[188:191], v[196:199], v[48:51]
	v_mfma_f32_16x16x32_bf16 v[36:39], v[176:179], v[204:207], v[36:39]
	v_mfma_f32_16x16x32_bf16 v[32:35], v[188:191], v[204:207], v[32:35]
	v_mfma_f32_16x16x32_bf16 v[20:23], v[176:179], v[212:215], v[20:23]
	v_mfma_f32_16x16x32_bf16 v[16:19], v[188:191], v[212:215], v[16:19]
	v_mfma_f32_16x16x32_bf16 v[4:7], v[176:179], v[220:223], v[4:7]
	v_mfma_f32_16x16x32_bf16 v[0:3], v[188:191], v[220:223], v[0:3]
	s_setprio 0
	s_barrier
	s_add_i32 s48, s48, 2
	s_add_u32 s28, s28, 0x100
	s_addc_u32 s29, s29, 0
	s_cmpk_gt_u32 s48, 0x55
	s_cbranch_scc0 .LBB0_842

;     __device__ bool next(int i, Unit& u) const { if (!b.next(i >> 1, u)) return false; u.half = i & 1; u.koff = (i & 1) * kbytes; return true; }
; #define PG8_STAGE(bufoff, gbase, voff) do { _Pragma("unroll") for (int _i = 0; _i < 2; ++_i) \
;         __builtin_amdgcn_global_load_lds((const unsigned*)((const char*)(gbase) + (voff)[_i]), (LAS unsigned*)(lds + (bufoff) + ldsw + _i * 8192), 16, 0, 0); } while (0)
; #define PG8_LDA(dst, b, h) do { _Pragma("unroll") for (int m = 0; m < 4; ++m) _Pragma("unroll") for (int k = 0; k < 2; ++k) dst[m][k] = *(const LAS bf16x8*)(lds + PG8_SA(b, h) + aoff + m * 2048 + k * 1024); } while (0)
; #define PG8_LDB(dst, b, h) do { _Pragma("unroll") for (int n = 0; n < 2; ++n) _Pragma("unroll") for (int k = 0; k < 2; ++k) dst[n][k] = *(const LAS bf16x8*)(lds + PG8_SB(b, h) + boff + n * 2048 + k * 1024); } while (0)
; #define PG8_MMA(ai, bj, At, Bt) do { __builtin_amdgcn_s_setprio(3); _Pragma("unroll") for (int m = 0; m < 4; ++m) _Pragma("unroll") for (int n = 0; n < 2; ++n) _Pragma("unroll") for (int k = 0; k < 2; ++k) \
;         acc[ai][bj][m][n] = __builtin_amdgcn_mfma_f32_16x16x32_bf16(Bt[n][k], At[m][k], acc[ai][bj][m][n], 0, 0, 0); __builtin_amdgcn_s_setprio(0); } while (0)
; template <class Epi, class Sched>
; __device__ __forceinline__ void gemm_phase(LAS unsigned char* lds, const Gemm g, const Sched& S, const Epi& E, int tid_in) {
;     ...
;         const bool has_next = S.next(ui + 1, nxt);
;         const char* nA = has_next ? (const char*)g.A + (size_t)nxt.pm * tstep + nxt.koff : cA; const char* nB = has_next ? (const char*)g.Bt + (size_t)nxt.pn * tstep + nxt.koff : cB;
;         for (int t = 0; t < nt; t += 2) {
;             const bool last = (t == nt - 2);
;             const char* a1 = cA + (size_t)(t + 1) * kstep;
;             const char* a2 = last ? nA : cA + (size_t)(t + 2) * kstep; const char* b2 = last ? nB : cB + (size_t)(t + 2) * kstep;
;             const char* a3 = a2 + kstep; const char* b3 = b2 + kstep;
;             PG8_LDB(B0, 0, 0); PG8_LDB(B1, 0, 1); PG8_SCHED; PG8_LDA(At, 0, 0); PG8_STAGE(PG8_SA(1, 0), a1, voffA); PG8_STAGE(PG8_SA(1, 1), a1 + hstep, voffA);
;             PG8_WAIT_V(8); PG8_WAIT_L(0); PG8_BAR; PG8_MMA(0, 0, At, B0); PG8_MMA(0, 1, At, B1); PG8_BAR; PG8_SCHED;
;             PG8_LDA(At, 0, 1); PG8_STAGE(PG8_SB(0, 0), b2, voffB); PG8_STAGE(PG8_SB(0, 1), b2 + hstep, voffB);
.LBB0_988:
	ds_read_b128 v[4:7], v143
	ds_read_b128 v[8:11], v143 offset:1024
	ds_read_b128 v[12:15], v143 offset:2048
	ds_read_b128 v[16:19], v143 offset:3072
	ds_read_b128 v[20:23], v144
	ds_read_b128 v[24:27], v144 offset:1024
	ds_read_b128 v[28:31], v144 offset:2048
	ds_read_b128 v[32:35], v144 offset:3072
	s_ashr_i32 s35, s34, 31
	s_lshl_b64 s[36:37], s[34:35], 17
	s_add_u32 s36, s3, s36
	s_addc_u32 s37, s51, s37
	s_and_b64 s[38:39], s[4:5], exec
	s_cselect_b32 s49, s37, s43
	s_cselect_b32 s48, s36, s42
	s_ashr_i32 s31, s30, 31
	s_lshl_b64 s[38:39], s[30:31], 17
	s_add_u32 s38, s62, s38
	s_addc_u32 s39, s63, s39
	s_and_b64 s[46:47], s[4:5], exec
	s_cselect_b32 s47, s39, s45
	s_cselect_b32 s46, s38, s44
	v_lshl_add_u64 v[0:1], s[42:43], 0, v[134:135]
	s_mov_b32 m0, s71
	v_lshl_add_u64 v[2:3], v[0:1], 0, s[8:9]
	ds_read_b128 v[36:39], v145
	ds_read_b128 v[40:43], v145 offset:1024
	ds_read_b128 v[44:47], v145 offset:2048
	ds_read_b128 v[48:51], v145 offset:3072
	ds_read_b128 v[52:55], v145 offset:4096
	ds_read_b128 v[56:59], v145 offset:5120
	ds_read_b128 v[60:63], v145 offset:6144
	ds_read_b128 v[64:67], v145 offset:7168
	global_load_lds_dwordx4 v[2:3], off
	v_lshl_add_u64 v[2:3], s[42:43], 0, v[130:131]
	s_add_u32 s80, s42, 0x10080
	v_lshl_add_u64 v[68:69], v[2:3], 0, s[8:9]
	s_mov_b32 m0, s72
	s_addc_u32 s81, s43, 0
	global_load_lds_dwordx4 v[68:69], off
	v_lshl_add_u64 v[68:69], s[80:81], 0, v[134:135]
	s_mov_b32 m0, s73
	s_nop 0
	global_load_lds_dwordx4 v[68:69], off
	v_lshl_add_u64 v[68:69], s[80:81], 0, v[130:131]
	s_mov_b32 m0, s74
	s_nop 0
	global_load_lds_dwordx4 v[68:69], off
	s_waitcnt vmcnt(8) lgkmcnt(0)
	s_barrier
	s_setprio 3
	v_mfma_f32_16x16x32_bf16 v[68:71], v[4:7], v[36:39], 0
	v_mfma_f32_16x16x32_bf16 v[72:75], v[12:15], v[36:39], 0
	v_mfma_f32_16x16x32_bf16 v[76:79], v[4:7], v[44:47], 0
	v_mfma_f32_16x16x32_bf16 v[80:83], v[12:15], v[44:47], 0
	v_mfma_f32_16x16x32_bf16 v[84:87], v[4:7], v[52:55], 0
	v_mfma_f32_16x16x32_bf16 v[88:91], v[12:15], v[52:55], 0
	v_mfma_f32_16x16x32_bf16 v[92:95], v[4:7], v[60:63], 0
	v_mfma_f32_16x16x32_bf16 v[96:99], v[12:15], v[60:63], 0
	v_mfma_f32_16x16x32_bf16 v[68:71], v[8:11], v[40:43], v[68:71]
	v_mfma_f32_16x16x32_bf16 v[72:75], v[16:19], v[40:43], v[72:75]
	v_mfma_f32_16x16x32_bf16 v[76:79], v[8:11], v[48:51], v[76:79]
	v_mfma_f32_16x16x32_bf16 v[80:83], v[16:19], v[48:51], v[80:83]
	v_mfma_f32_16x16x32_bf16 v[84:87], v[8:11], v[56:59], v[84:87]
	v_mfma_f32_16x16x32_bf16 v[88:91], v[16:19], v[56:59], v[88:91]
	v_mfma_f32_16x16x32_bf16 v[92:95], v[8:11], v[64:67], v[92:95]
	v_mfma_f32_16x16x32_bf16 v[96:99], v[16:19], v[64:67], v[96:99]
	s_setprio 0
	s_setprio 3
	v_mfma_f32_16x16x32_bf16 v[100:103], v[20:23], v[36:39], 0
	v_mfma_f32_16x16x32_bf16 v[36:39], v[28:31], v[36:39], 0
	v_mfma_f32_16x16x32_bf16 v[100:103], v[24:27], v[40:43], v[100:103]
	v_mfma_f32_16x16x32_bf16 v[36:39], v[32:35], v[40:43], v[36:39]
	v_mfma_f32_16x16x32_bf16 v[40:43], v[20:23], v[44:47], 0
	v_mfma_f32_16x16x32_bf16 v[44:47], v[28:31], v[44:47], 0
	v_mfma_f32_16x16x32_bf16 v[40:43], v[24:27], v[48:51], v[40:43]
	v_mfma_f32_16x16x32_bf16 v[44:47], v[32:35], v[48:51], v[44:47]
	v_mfma_f32_16x16x32_bf16 v[48:51], v[20:23], v[52:55], 0
	v_mfma_f32_16x16x32_bf16 v[52:55], v[28:31], v[52:55], 0
	v_mfma_f32_16x16x32_bf16 v[48:51], v[24:27], v[56:59], v[48:51]
	v_mfma_f32_16x16x32_bf16 v[52:55], v[32:35], v[56:59], v[52:55]
	v_mfma_f32_16x16x32_bf16 v[56:59], v[20:23], v[60:63], 0
	v_mfma_f32_16x16x32_bf16 v[60:63], v[28:31], v[60:63], 0
	v_mfma_f32_16x16x32_bf16 v[56:59], v[24:27], v[64:67], v[56:59]
	v_mfma_f32_16x16x32_bf16 v[60:63], v[32:35], v[64:67], v[60:63]
	s_setprio 0
	s_barrier
	s_add_i32 s82, s69, s2
	v_lshl_add_u64 v[216:217], s[44:45], 0, v[132:133]
	s_add_i32 s31, s82, 0x2000
	v_lshl_add_u64 v[150:151], v[216:217], 0, s[18:19]
	s_mov_b32 m0, s82
	v_lshl_add_u64 v[218:219], s[44:45], 0, v[128:129]
	s_add_u32 s80, s44, 0x10100
	ds_read_b128 v[64:67], v145 offset:16384
	ds_read_b128 v[104:107], v145 offset:17408
	ds_read_b128 v[108:111], v145 offset:18432
	ds_read_b128 v[112:115], v145 offset:19456
	ds_read_b128 v[116:119], v145 offset:20480
	ds_read_b128 v[120:123], v145 offset:21504
	ds_read_b128 v[124:127], v145 offset:22528
	ds_read_b128 v[146:149], v145 offset:23552
	global_load_lds_dwordx4 v[150:151], off
	v_lshl_add_u64 v[150:151], v[218:219], 0, s[18:19]
	s_mov_b32 m0, s31
	s_addc_u32 s81, s45, 0
	s_add_i32 s35, s70, s2
	global_load_lds_dwordx4 v[150:151], off
	v_lshl_add_u64 v[150:151], s[80:81], 0, v[132:133]
	s_mov_b32 m0, s35
	s_nop 0
	global_load_lds_dwordx4 v[150:151], off
	v_lshl_add_u64 v[150:151], s[80:81], 0, v[128:129]
	s_add_i32 s80, s35, 0x2000
	s_mov_b32 m0, s80
	s_nop 0
	global_load_lds_dwordx4 v[150:151], off
	s_waitcnt vmcnt(6) lgkmcnt(0)
	s_barrier
; #define PG8_STAGE(bufoff, gbase, voff) do { _Pragma("unroll") for (int _i = 0; _i < 2; ++_i) \
;         __builtin_amdgcn_global_load_lds((const unsigned*)((const char*)(gbase) + (voff)[_i]), (LAS unsigned*)(lds + (bufoff) + ldsw + _i * 8192), 16, 0, 0); } while (0)
; #define PG8_LDA(dst, b, h) do { _Pragma("unroll") for (int m = 0; m < 4; ++m) _Pragma("unroll") for (int k = 0; k < 2; ++k) dst[m][k] = *(const LAS bf16x8*)(lds + PG8_SA(b, h) + aoff + m * 2048 + k * 1024); } while (0)
; #define PG8_LDB(dst, b, h) do { _Pragma("unroll") for (int n = 0; n < 2; ++n) _Pragma("unroll") for (int k = 0; k < 2; ++k) dst[n][k] = *(const LAS bf16x8*)(lds + PG8_SB(b, h) + boff + n * 2048 + k * 1024); } while (0)
; #define PG8_MMA(ai, bj, At, Bt) do { __builtin_amdgcn_s_setprio(3); _Pragma("unroll") for (int m = 0; m < 4; ++m) _Pragma("unroll") for (int n = 0; n < 2; ++n) _Pragma("unroll") for (int k = 0; k < 2; ++k) \
;         acc[ai][bj][m][n] = __builtin_amdgcn_mfma_f32_16x16x32_bf16(Bt[n][k], At[m][k], acc[ai][bj][m][n], 0, 0, 0); __builtin_amdgcn_s_setprio(0); } while (0)
; #define PG8_WAIT_V(n) asm volatile("s_waitcnt vmcnt(" #n ")" ::: "memory")
; #define PG8_WAIT_L(n) asm volatile("s_waitcnt lgkmcnt(" #n ")" ::: "memory")
; #define PG8_BAR __builtin_amdgcn_s_barrier()
; #define PG8_SCHED __builtin_amdgcn_sched_barrier(0)
; template <class Epi, class Sched>
; __device__ __forceinline__ void gemm_phase(LAS unsigned char* lds, const Gemm g, const Sched& S, const Epi& E, int tid_in) {
;     ...
;             PG8_WAIT_V(6); PG8_WAIT_L(0); PG8_BAR; PG8_MMA(1, 0, At, B0); PG8_MMA(1, 1, At, B1); PG8_BAR; PG8_SCHED;
;             PG8_LDB(B0, 1, 0); PG8_LDB(B1, 1, 1); PG8_SCHED; PG8_LDA(At, 1, 0); PG8_STAGE(PG8_SA(0, 0), a2, voffA); PG8_STAGE(PG8_SA(0, 1), a2 + hstep, voffA);
;             PG8_WAIT_V(8); PG8_WAIT_L(0); PG8_BAR; PG8_MMA(0, 0, At, B0); PG8_MMA(0, 1, At, B1); PG8_BAR; PG8_SCHED;
	s_setprio 3
	v_mfma_f32_16x16x32_bf16 v[150:153], v[4:7], v[64:67], 0
	v_mfma_f32_16x16x32_bf16 v[158:161], v[4:7], v[108:111], 0
	v_mfma_f32_16x16x32_bf16 v[166:169], v[4:7], v[116:119], 0
	v_mfma_f32_16x16x32_bf16 v[4:7], v[4:7], v[124:127], 0
	v_mfma_f32_16x16x32_bf16 v[150:153], v[8:11], v[104:107], v[150:153]
	v_mfma_f32_16x16x32_bf16 v[158:161], v[8:11], v[112:115], v[158:161]
	v_mfma_f32_16x16x32_bf16 v[166:169], v[8:11], v[120:123], v[166:169]
	v_mfma_f32_16x16x32_bf16 v[4:7], v[8:11], v[146:149], v[4:7]
	v_mfma_f32_16x16x32_bf16 v[8:11], v[12:15], v[124:127], 0
	v_mfma_f32_16x16x32_bf16 v[154:157], v[12:15], v[64:67], 0
	v_mfma_f32_16x16x32_bf16 v[162:165], v[12:15], v[108:111], 0
	v_mfma_f32_16x16x32_bf16 v[170:173], v[12:15], v[116:119], 0
	v_mfma_f32_16x16x32_bf16 v[8:11], v[16:19], v[146:149], v[8:11]
	v_mfma_f32_16x16x32_bf16 v[154:157], v[16:19], v[104:107], v[154:157]
	v_mfma_f32_16x16x32_bf16 v[162:165], v[16:19], v[112:115], v[162:165]
	v_mfma_f32_16x16x32_bf16 v[170:173], v[16:19], v[120:123], v[170:173]
	s_setprio 0
	s_setprio 3
	v_mfma_f32_16x16x32_bf16 v[12:15], v[20:23], v[64:67], 0
	v_mfma_f32_16x16x32_bf16 v[16:19], v[28:31], v[64:67], 0
	v_mfma_f32_16x16x32_bf16 v[12:15], v[24:27], v[104:107], v[12:15]
	v_mfma_f32_16x16x32_bf16 v[16:19], v[32:35], v[104:107], v[16:19]
	v_mfma_f32_16x16x32_bf16 v[64:67], v[20:23], v[108:111], 0
	v_mfma_f32_16x16x32_bf16 v[104:107], v[28:31], v[108:111], 0
	v_mfma_f32_16x16x32_bf16 v[108:111], v[20:23], v[116:119], 0
	v_mfma_f32_16x16x32_bf16 v[20:23], v[20:23], v[124:127], 0
	v_mfma_f32_16x16x32_bf16 v[64:67], v[24:27], v[112:115], v[64:67]
	v_mfma_f32_16x16x32_bf16 v[104:107], v[32:35], v[112:115], v[104:107]
	v_mfma_f32_16x16x32_bf16 v[108:111], v[24:27], v[120:123], v[108:111]
	v_mfma_f32_16x16x32_bf16 v[112:115], v[28:31], v[116:119], 0
	v_mfma_f32_16x16x32_bf16 v[20:23], v[24:27], v[146:149], v[20:23]
	v_mfma_f32_16x16x32_bf16 v[24:27], v[28:31], v[124:127], 0
	v_mfma_f32_16x16x32_bf16 v[112:115], v[32:35], v[120:123], v[112:115]
	v_mfma_f32_16x16x32_bf16 v[24:27], v[32:35], v[146:149], v[24:27]
	s_setprio 0
	s_barrier
	s_add_i32 s83, 0, 0x18000
	s_add_i32 s87, 0, 0x1c000
	v_add_u32_e32 v224, s83, v141
	v_add_u32_e32 v225, s87, v141
	ds_read_b128 v[28:31], v224
	ds_read_b128 v[32:35], v224 offset:1024
	ds_read_b128 v[116:119], v224 offset:2048
	ds_read_b128 v[120:123], v224 offset:3072
	ds_read_b128 v[124:127], v225
	ds_read_b128 v[146:149], v225 offset:1024
	ds_read_b128 v[174:177], v225 offset:2048
	ds_read_b128 v[178:181], v225 offset:3072
	s_mov_b32 m0, s41
	v_lshl_add_u64 v[220:221], v[0:1], 0, s[18:19]
	s_add_u32 s88, s42, 0x10100
	ds_read_b128 v[182:185], v145 offset:32768
	ds_read_b128 v[188:191], v145 offset:33792
	ds_read_b128 v[192:195], v145 offset:34816
	ds_read_b128 v[196:199], v145 offset:35840
	ds_read_b128 v[200:203], v145 offset:36864
	ds_read_b128 v[204:207], v145 offset:37888
	ds_read_b128 v[208:211], v145 offset:38912
	ds_read_b128 v[212:215], v145 offset:39936
	global_load_lds_dwordx4 v[220:221], off
	v_lshl_add_u64 v[220:221], v[2:3], 0, s[18:19]
	s_mov_b32 m0, s66
	s_addc_u32 s89, s43, 0
	global_load_lds_dwordx4 v[220:221], off
	v_lshl_add_u64 v[220:221], s[88:89], 0, v[134:135]
	s_mov_b32 m0, s67
	s_nop 0
	global_load_lds_dwordx4 v[220:221], off
	v_lshl_add_u64 v[220:221], s[88:89], 0, v[130:131]
	s_mov_b32 m0, s68
	s_nop 0
	global_load_lds_dwordx4 v[220:221], off
	s_waitcnt vmcnt(8) lgkmcnt(0)
	s_barrier
	s_setprio 3
	v_mfma_f32_16x16x32_bf16 v[68:71], v[28:31], v[182:185], v[68:71]
	v_mfma_f32_16x16x32_bf16 v[72:75], v[116:119], v[182:185], v[72:75]
	v_mfma_f32_16x16x32_bf16 v[76:79], v[28:31], v[192:195], v[76:79]
	v_mfma_f32_16x16x32_bf16 v[80:83], v[116:119], v[192:195], v[80:83]
	v_mfma_f32_16x16x32_bf16 v[84:87], v[28:31], v[200:203], v[84:87]
	v_mfma_f32_16x16x32_bf16 v[88:91], v[116:119], v[200:203], v[88:91]
	v_mfma_f32_16x16x32_bf16 v[92:95], v[28:31], v[208:211], v[92:95]
	v_mfma_f32_16x16x32_bf16 v[96:99], v[116:119], v[208:211], v[96:99]
	v_mfma_f32_16x16x32_bf16 v[68:71], v[32:35], v[188:191], v[68:71]
	v_mfma_f32_16x16x32_bf16 v[72:75], v[120:123], v[188:191], v[72:75]
	v_mfma_f32_16x16x32_bf16 v[76:79], v[32:35], v[196:199], v[76:79]
	v_mfma_f32_16x16x32_bf16 v[80:83], v[120:123], v[196:199], v[80:83]
	v_mfma_f32_16x16x32_bf16 v[84:87], v[32:35], v[204:207], v[84:87]
	v_mfma_f32_16x16x32_bf16 v[88:91], v[120:123], v[204:207], v[88:91]
	v_mfma_f32_16x16x32_bf16 v[92:95], v[32:35], v[212:215], v[92:95]
	v_mfma_f32_16x16x32_bf16 v[96:99], v[120:123], v[212:215], v[96:99]
	s_setprio 0
	s_setprio 3
	v_mfma_f32_16x16x32_bf16 v[100:103], v[124:127], v[182:185], v[100:103]
	v_mfma_f32_16x16x32_bf16 v[36:39], v[174:177], v[182:185], v[36:39]
	v_mfma_f32_16x16x32_bf16 v[40:43], v[124:127], v[192:195], v[40:43]
	v_mfma_f32_16x16x32_bf16 v[44:47], v[174:177], v[192:195], v[44:47]
	v_mfma_f32_16x16x32_bf16 v[48:51], v[124:127], v[200:203], v[48:51]
	v_mfma_f32_16x16x32_bf16 v[52:55], v[174:177], v[200:203], v[52:55]
	v_mfma_f32_16x16x32_bf16 v[56:59], v[124:127], v[208:211], v[56:59]
	v_mfma_f32_16x16x32_bf16 v[60:63], v[174:177], v[208:211], v[60:63]
	v_mfma_f32_16x16x32_bf16 v[100:103], v[146:149], v[188:191], v[100:103]
	v_mfma_f32_16x16x32_bf16 v[36:39], v[178:181], v[188:191], v[36:39]
	v_mfma_f32_16x16x32_bf16 v[40:43], v[146:149], v[196:199], v[40:43]
	v_mfma_f32_16x16x32_bf16 v[44:47], v[178:181], v[196:199], v[44:47]
	v_mfma_f32_16x16x32_bf16 v[48:51], v[146:149], v[204:207], v[48:51]
	v_mfma_f32_16x16x32_bf16 v[52:55], v[178:181], v[204:207], v[52:55]
	v_mfma_f32_16x16x32_bf16 v[56:59], v[146:149], v[212:215], v[56:59]
	v_mfma_f32_16x16x32_bf16 v[60:63], v[178:181], v[212:215], v[60:63]
	s_setprio 0
	s_barrier
; #define PG8_STAGE(bufoff, gbase, voff) do { _Pragma("unroll") for (int _i = 0; _i < 2; ++_i) \
;         __builtin_amdgcn_global_load_lds((const unsigned*)((const char*)(gbase) + (voff)[_i]), (LAS unsigned*)(lds + (bufoff) + ldsw + _i * 8192), 16, 0, 0); } while (0)
; #define PG8_LDA(dst, b, h) do { _Pragma("unroll") for (int m = 0; m < 4; ++m) _Pragma("unroll") for (int k = 0; k < 2; ++k) dst[m][k] = *(const LAS bf16x8*)(lds + PG8_SA(b, h) + aoff + m * 2048 + k * 1024); } while (0)
; #define PG8_LDB(dst, b, h) do { _Pragma("unroll") for (int n = 0; n < 2; ++n) _Pragma("unroll") for (int k = 0; k < 2; ++k) dst[n][k] = *(const LAS bf16x8*)(lds + PG8_SB(b, h) + boff + n * 2048 + k * 1024); } while (0)
; #define PG8_MMA(ai, bj, At, Bt) do { __builtin_amdgcn_s_setprio(3); _Pragma("unroll") for (int m = 0; m < 4; ++m) _Pragma("unroll") for (int n = 0; n < 2; ++n) _Pragma("unroll") for (int k = 0; k < 2; ++k) \
;         acc[ai][bj][m][n] = __builtin_amdgcn_mfma_f32_16x16x32_bf16(Bt[n][k], At[m][k], acc[ai][bj][m][n], 0, 0, 0); __builtin_amdgcn_s_setprio(0); } while (0)
; #define PG8_WAIT_V(n) asm volatile("s_waitcnt vmcnt(" #n ")" ::: "memory")
; #define PG8_BAR __builtin_amdgcn_s_barrier()
; template <class Epi, class Sched>
; __device__ __forceinline__ void gemm_phase(LAS unsigned char* lds, const Gemm g, const Sched& S, const Epi& E, int tid_in) {
;     ...
;             PG8_LDB(B0, 0, 0); PG8_LDB(B1, 0, 1); PG8_SCHED; PG8_LDA(At, 0, 0); PG8_STAGE(PG8_SA(1, 0), a1, voffA); PG8_STAGE(PG8_SA(1, 1), a1 + hstep, voffA);
;             PG8_WAIT_V(8); PG8_WAIT_L(0); PG8_BAR; PG8_MMA(0, 0, At, B0); PG8_MMA(0, 1, At, B1); PG8_BAR; PG8_SCHED;
;             PG8_LDA(At, 0, 1); PG8_STAGE(PG8_SB(0, 0), b2, voffB); PG8_STAGE(PG8_SB(0, 1), b2 + hstep, voffB);
;             PG8_WAIT_V(6); PG8_WAIT_L(0); PG8_BAR; PG8_MMA(1, 0, At, B0); PG8_MMA(1, 1, At, B1); PG8_BAR; PG8_SCHED;
;             PG8_LDB(B0, 1, 0); PG8_LDB(B1, 1, 1); PG8_SCHED; PG8_LDA(At, 1, 0); PG8_STAGE(PG8_SA(0, 0), a2, voffA); PG8_STAGE(PG8_SA(0, 1), a2 + hstep, voffA);
;             PG8_WAIT_V(8); PG8_WAIT_L(0); PG8_BAR; PG8_MMA(0, 0, At, B0); PG8_MMA(0, 1, At, B1); PG8_BAR; PG8_SCHED;
;             PG8_LDA(At, 1, 1); PG8_STAGE(PG8_SB(1, 0), b3, voffB); PG8_STAGE(PG8_SB(1, 1), b3 + hstep, voffB);
;             PG8_WAIT_V(6); PG8_WAIT_L(0); PG8_BAR; PG8_MMA(1, 0, At, B0); PG8_MMA(1, 1, At, B1); PG8_BAR; PG8_SCHED;
	s_add_i32 s83, s83, s2
	s_add_i32 s81, s83, 0x2000
	v_lshl_add_u64 v[216:217], v[216:217], 0, s[20:21]
	s_mov_b32 m0, s83
	s_add_u32 s88, s44, 0x10180
	ds_read_b128 v[182:185], v145 offset:49152
	ds_read_b128 v[188:191], v145 offset:50176
	ds_read_b128 v[192:195], v145 offset:51200
	ds_read_b128 v[196:199], v145 offset:52224
	ds_read_b128 v[200:203], v145 offset:53248
	ds_read_b128 v[204:207], v145 offset:54272
	ds_read_b128 v[208:211], v145 offset:55296
	ds_read_b128 v[212:215], v145 offset:56320
	global_load_lds_dwordx4 v[216:217], off
	v_lshl_add_u64 v[216:217], v[218:219], 0, s[20:21]
	s_mov_b32 m0, s81
	s_addc_u32 s89, s45, 0
	s_add_i32 s44, s87, s2
	global_load_lds_dwordx4 v[216:217], off
	v_lshl_add_u64 v[216:217], s[88:89], 0, v[132:133]
	s_mov_b32 m0, s44
	s_add_i32 s45, s44, 0x2000
	global_load_lds_dwordx4 v[216:217], off
	v_lshl_add_u64 v[216:217], s[88:89], 0, v[128:129]
	s_mov_b32 m0, s45
	s_nop 0
	global_load_lds_dwordx4 v[216:217], off
	s_waitcnt vmcnt(6) lgkmcnt(0)
	s_barrier
	s_setprio 3
	v_mfma_f32_16x16x32_bf16 v[4:7], v[28:31], v[208:211], v[4:7]
	v_mfma_f32_16x16x32_bf16 v[8:11], v[116:119], v[208:211], v[8:11]
	v_mfma_f32_16x16x32_bf16 v[150:153], v[28:31], v[182:185], v[150:153]
	v_mfma_f32_16x16x32_bf16 v[154:157], v[116:119], v[182:185], v[154:157]
	v_mfma_f32_16x16x32_bf16 v[158:161], v[28:31], v[192:195], v[158:161]
	v_mfma_f32_16x16x32_bf16 v[162:165], v[116:119], v[192:195], v[162:165]
	v_mfma_f32_16x16x32_bf16 v[166:169], v[28:31], v[200:203], v[166:169]
	v_mfma_f32_16x16x32_bf16 v[170:173], v[116:119], v[200:203], v[170:173]
	v_mfma_f32_16x16x32_bf16 v[4:7], v[32:35], v[212:215], v[4:7]
	v_mfma_f32_16x16x32_bf16 v[8:11], v[120:123], v[212:215], v[8:11]
	v_mfma_f32_16x16x32_bf16 v[150:153], v[32:35], v[188:191], v[150:153]
	v_mfma_f32_16x16x32_bf16 v[154:157], v[120:123], v[188:191], v[154:157]
	v_mfma_f32_16x16x32_bf16 v[158:161], v[32:35], v[196:199], v[158:161]
	v_mfma_f32_16x16x32_bf16 v[162:165], v[120:123], v[196:199], v[162:165]
	v_mfma_f32_16x16x32_bf16 v[166:169], v[32:35], v[204:207], v[166:169]
	v_mfma_f32_16x16x32_bf16 v[170:173], v[120:123], v[204:207], v[170:173]
	s_setprio 0
	s_setprio 3
	v_mfma_f32_16x16x32_bf16 v[12:15], v[124:127], v[182:185], v[12:15]
	v_mfma_f32_16x16x32_bf16 v[16:19], v[174:177], v[182:185], v[16:19]
	v_mfma_f32_16x16x32_bf16 v[28:31], v[124:127], v[192:195], v[64:67]
	v_mfma_f32_16x16x32_bf16 v[32:35], v[174:177], v[192:195], v[104:107]
	v_mfma_f32_16x16x32_bf16 v[64:67], v[124:127], v[200:203], v[108:111]
	v_mfma_f32_16x16x32_bf16 v[104:107], v[174:177], v[200:203], v[112:115]
	v_mfma_f32_16x16x32_bf16 v[20:23], v[124:127], v[208:211], v[20:23]
	v_mfma_f32_16x16x32_bf16 v[24:27], v[174:177], v[208:211], v[24:27]
	v_mfma_f32_16x16x32_bf16 v[12:15], v[146:149], v[188:191], v[12:15]
	v_mfma_f32_16x16x32_bf16 v[16:19], v[178:181], v[188:191], v[16:19]
	v_mfma_f32_16x16x32_bf16 v[28:31], v[146:149], v[196:199], v[28:31]
	v_mfma_f32_16x16x32_bf16 v[32:35], v[178:181], v[196:199], v[32:35]
	v_mfma_f32_16x16x32_bf16 v[64:67], v[146:149], v[204:207], v[64:67]
	v_mfma_f32_16x16x32_bf16 v[104:107], v[178:181], v[204:207], v[104:107]
	v_mfma_f32_16x16x32_bf16 v[20:23], v[146:149], v[212:215], v[20:23]
	v_mfma_f32_16x16x32_bf16 v[24:27], v[178:181], v[212:215], v[24:27]
	s_setprio 0
	s_barrier
	ds_read_b128 v[108:111], v143
	ds_read_b128 v[112:115], v143 offset:1024
	ds_read_b128 v[116:119], v143 offset:2048
	ds_read_b128 v[120:123], v143 offset:3072
	ds_read_b128 v[124:127], v144
	ds_read_b128 v[146:149], v144 offset:1024
	ds_read_b128 v[174:177], v144 offset:2048
	ds_read_b128 v[178:181], v144 offset:3072
	s_mov_b32 m0, s71
	v_lshl_add_u64 v[0:1], v[0:1], 0, s[20:21]
	s_add_u32 s42, s42, 0x10180
	ds_read_b128 v[182:185], v145
	ds_read_b128 v[188:191], v145 offset:1024
	ds_read_b128 v[192:195], v145 offset:2048
	ds_read_b128 v[196:199], v145 offset:3072
	ds_read_b128 v[200:203], v145 offset:4096
	ds_read_b128 v[204:207], v145 offset:5120
	ds_read_b128 v[208:211], v145 offset:6144
	ds_read_b128 v[212:215], v145 offset:7168
	global_load_lds_dwordx4 v[0:1], off
	v_lshl_add_u64 v[0:1], v[2:3], 0, s[20:21]
	s_mov_b32 m0, s72
	s_addc_u32 s43, s43, 0
	global_load_lds_dwordx4 v[0:1], off
	v_lshl_add_u64 v[0:1], s[42:43], 0, v[134:135]
	s_mov_b32 m0, s73
	s_nop 0
	global_load_lds_dwordx4 v[0:1], off
	v_lshl_add_u64 v[0:1], s[42:43], 0, v[130:131]
	s_mov_b32 m0, s74
	s_nop 0
	global_load_lds_dwordx4 v[0:1], off
	s_waitcnt vmcnt(8) lgkmcnt(0)
	s_barrier
	s_setprio 3
	v_mfma_f32_16x16x32_bf16 v[0:3], v[108:111], v[182:185], v[68:71]
	v_mfma_f32_16x16x32_bf16 v[68:71], v[116:119], v[182:185], v[72:75]
	v_mfma_f32_16x16x32_bf16 v[72:75], v[108:111], v[192:195], v[76:79]
	v_mfma_f32_16x16x32_bf16 v[76:79], v[116:119], v[192:195], v[80:83]
	v_mfma_f32_16x16x32_bf16 v[80:83], v[108:111], v[200:203], v[84:87]
	v_mfma_f32_16x16x32_bf16 v[84:87], v[116:119], v[200:203], v[88:91]
	v_mfma_f32_16x16x32_bf16 v[88:91], v[108:111], v[208:211], v[92:95]
	v_mfma_f32_16x16x32_bf16 v[92:95], v[116:119], v[208:211], v[96:99]
	v_mfma_f32_16x16x32_bf16 v[0:3], v[112:115], v[188:191], v[0:3]
	v_mfma_f32_16x16x32_bf16 v[68:71], v[120:123], v[188:191], v[68:71]
	v_mfma_f32_16x16x32_bf16 v[72:75], v[112:115], v[196:199], v[72:75]
	v_mfma_f32_16x16x32_bf16 v[76:79], v[120:123], v[196:199], v[76:79]
	v_mfma_f32_16x16x32_bf16 v[80:83], v[112:115], v[204:207], v[80:83]
	v_mfma_f32_16x16x32_bf16 v[84:87], v[120:123], v[204:207], v[84:87]
	v_mfma_f32_16x16x32_bf16 v[88:91], v[112:115], v[212:215], v[88:91]
	v_mfma_f32_16x16x32_bf16 v[96:99], v[120:123], v[212:215], v[92:95]
	s_setprio 0
	s_setprio 3
	v_mfma_f32_16x16x32_bf16 v[52:55], v[174:177], v[200:203], v[52:55]
	v_mfma_f32_16x16x32_bf16 v[92:95], v[124:127], v[182:185], v[100:103]
	v_mfma_f32_16x16x32_bf16 v[36:39], v[174:177], v[182:185], v[36:39]
	v_mfma_f32_16x16x32_bf16 v[40:43], v[124:127], v[192:195], v[40:43]
	v_mfma_f32_16x16x32_bf16 v[44:47], v[174:177], v[192:195], v[44:47]
	v_mfma_f32_16x16x32_bf16 v[48:51], v[124:127], v[200:203], v[48:51]
	v_mfma_f32_16x16x32_bf16 v[182:185], v[178:181], v[204:207], v[52:55]
	v_mfma_f32_16x16x32_bf16 v[52:55], v[124:127], v[208:211], v[56:59]
	v_mfma_f32_16x16x32_bf16 v[36:39], v[178:181], v[188:191], v[36:39]
	v_mfma_f32_16x16x32_bf16 v[40:43], v[146:149], v[196:199], v[40:43]
	v_mfma_f32_16x16x32_bf16 v[44:47], v[178:181], v[196:199], v[44:47]
	v_mfma_f32_16x16x32_bf16 v[48:51], v[146:149], v[204:207], v[48:51]
	v_mfma_f32_16x16x32_bf16 v[56:59], v[146:149], v[212:215], v[52:55]
	v_mfma_f32_16x16x32_bf16 v[52:55], v[174:177], v[208:211], v[60:63]
	v_mfma_f32_16x16x32_bf16 v[216:219], v[146:149], v[188:191], v[92:95]
	v_mfma_f32_16x16x32_bf16 v[188:191], v[178:181], v[212:215], v[52:55]
	s_setprio 0
	s_barrier
; #define PG8_STAGE(bufoff, gbase, voff) do { _Pragma("unroll") for (int _i = 0; _i < 2; ++_i) \
;         __builtin_amdgcn_global_load_lds((const unsigned*)((const char*)(gbase) + (voff)[_i]), (LAS unsigned*)(lds + (bufoff) + ldsw + _i * 8192), 16, 0, 0); } while (0)
; #define PG8_LDA(dst, b, h) do { _Pragma("unroll") for (int m = 0; m < 4; ++m) _Pragma("unroll") for (int k = 0; k < 2; ++k) dst[m][k] = *(const LAS bf16x8*)(lds + PG8_SA(b, h) + aoff + m * 2048 + k * 1024); } while (0)
; #define PG8_LDB(dst, b, h) do { _Pragma("unroll") for (int n = 0; n < 2; ++n) _Pragma("unroll") for (int k = 0; k < 2; ++k) dst[n][k] = *(const LAS bf16x8*)(lds + PG8_SB(b, h) + boff + n * 2048 + k * 1024); } while (0)
; #define PG8_MMA(ai, bj, At, Bt) do { __builtin_amdgcn_s_setprio(3); _Pragma("unroll") for (int m = 0; m < 4; ++m) _Pragma("unroll") for (int n = 0; n < 2; ++n) _Pragma("unroll") for (int k = 0; k < 2; ++k) \
;         acc[ai][bj][m][n] = __builtin_amdgcn_mfma_f32_16x16x32_bf16(Bt[n][k], At[m][k], acc[ai][bj][m][n], 0, 0, 0); __builtin_amdgcn_s_setprio(0); } while (0)
; #define PG8_WAIT_V(n) asm volatile("s_waitcnt vmcnt(" #n ")" ::: "memory")
; #define PG8_WAIT_L(n) asm volatile("s_waitcnt lgkmcnt(" #n ")" ::: "memory")
; #define PG8_BAR __builtin_amdgcn_s_barrier()
; #define PG8_SCHED __builtin_amdgcn_sched_barrier(0)
; template <class Epi, class Sched>
; __device__ __forceinline__ void gemm_phase(LAS unsigned char* lds, const Gemm g, const Sched& S, const Epi& E, int tid_in) {
;     ...
;             PG8_LDA(At, 0, 1); PG8_STAGE(PG8_SB(0, 0), b2, voffB); PG8_STAGE(PG8_SB(0, 1), b2 + hstep, voffB);
;             PG8_WAIT_V(6); PG8_WAIT_L(0); PG8_BAR; PG8_MMA(1, 0, At, B0); PG8_MMA(1, 1, At, B1); PG8_BAR; PG8_SCHED;
;             PG8_LDB(B0, 1, 0); PG8_LDB(B1, 1, 1); PG8_SCHED; PG8_LDA(At, 1, 0); PG8_STAGE(PG8_SA(0, 0), a2, voffA); PG8_STAGE(PG8_SA(0, 1), a2 + hstep, voffA);
;             PG8_WAIT_V(8); PG8_WAIT_L(0); PG8_BAR; PG8_MMA(0, 0, At, B0); PG8_MMA(0, 1, At, B1); PG8_BAR; PG8_SCHED;
	s_mov_b32 m0, s82
	v_lshl_add_u64 v[252:253], s[46:47], 0, v[132:133]
	s_add_u32 s42, s46, 0x10000
	s_nop 0
	ds_read_b128 v[52:55], v145 offset:16384
	ds_read_b128 v[60:63], v145 offset:17408
	ds_read_b128 v[92:95], v145 offset:18432
	ds_read_b128 v[100:103], v145 offset:19456
	ds_read_b128 v[192:195], v145 offset:20480
	ds_read_b128 v[196:199], v145 offset:21504
	ds_read_b128 v[200:203], v145 offset:22528
	ds_read_b128 v[204:207], v145 offset:23552
	global_load_lds_dwordx4 v[252:253], off
	v_lshl_add_u64 v[186:187], s[46:47], 0, v[128:129]
	s_mov_b32 m0, s31
	s_addc_u32 s43, s47, 0
	global_load_lds_dwordx4 v[186:187], off
	v_lshl_add_u64 v[208:209], s[42:43], 0, v[132:133]
	s_mov_b32 m0, s35
	s_nop 0
	global_load_lds_dwordx4 v[208:209], off
	v_lshl_add_u64 v[208:209], s[42:43], 0, v[128:129]
	s_mov_b32 m0, s80
	s_nop 0
	global_load_lds_dwordx4 v[208:209], off
	s_waitcnt vmcnt(6) lgkmcnt(0)
	s_barrier
	s_setprio 3
	v_mfma_f32_16x16x32_bf16 v[4:7], v[108:111], v[200:203], v[4:7]
	v_mfma_f32_16x16x32_bf16 v[8:11], v[116:119], v[200:203], v[8:11]
	v_mfma_f32_16x16x32_bf16 v[150:153], v[108:111], v[52:55], v[150:153]
	v_mfma_f32_16x16x32_bf16 v[154:157], v[116:119], v[52:55], v[154:157]
	v_mfma_f32_16x16x32_bf16 v[158:161], v[108:111], v[92:95], v[158:161]
	v_mfma_f32_16x16x32_bf16 v[162:165], v[116:119], v[92:95], v[162:165]
	v_mfma_f32_16x16x32_bf16 v[166:169], v[108:111], v[192:195], v[166:169]
	v_mfma_f32_16x16x32_bf16 v[170:173], v[116:119], v[192:195], v[170:173]
	v_mfma_f32_16x16x32_bf16 v[4:7], v[112:115], v[204:207], v[4:7]
	v_mfma_f32_16x16x32_bf16 v[8:11], v[120:123], v[204:207], v[8:11]
	v_mfma_f32_16x16x32_bf16 v[150:153], v[112:115], v[60:63], v[150:153]
	v_mfma_f32_16x16x32_bf16 v[154:157], v[120:123], v[60:63], v[154:157]
	v_mfma_f32_16x16x32_bf16 v[158:161], v[112:115], v[100:103], v[158:161]
	v_mfma_f32_16x16x32_bf16 v[162:165], v[120:123], v[100:103], v[162:165]
	v_mfma_f32_16x16x32_bf16 v[166:169], v[112:115], v[196:199], v[166:169]
	v_mfma_f32_16x16x32_bf16 v[170:173], v[120:123], v[196:199], v[170:173]
	s_setprio 0
	s_setprio 3
	v_mfma_f32_16x16x32_bf16 v[12:15], v[124:127], v[52:55], v[12:15]
	v_mfma_f32_16x16x32_bf16 v[208:211], v[146:149], v[60:63], v[12:15]
	v_mfma_f32_16x16x32_bf16 v[12:15], v[174:177], v[52:55], v[16:19]
	v_mfma_f32_16x16x32_bf16 v[16:19], v[178:181], v[60:63], v[12:15]
	v_mfma_f32_16x16x32_bf16 v[12:15], v[124:127], v[92:95], v[28:31]
	v_mfma_f32_16x16x32_bf16 v[212:215], v[146:149], v[100:103], v[12:15]
	v_mfma_f32_16x16x32_bf16 v[12:15], v[174:177], v[92:95], v[32:35]
	v_mfma_f32_16x16x32_bf16 v[32:35], v[178:181], v[100:103], v[12:15]
	v_mfma_f32_16x16x32_bf16 v[12:15], v[124:127], v[192:195], v[64:67]
	v_mfma_f32_16x16x32_bf16 v[220:223], v[146:149], v[196:199], v[12:15]
	v_mfma_f32_16x16x32_bf16 v[12:15], v[174:177], v[192:195], v[104:107]
	v_mfma_f32_16x16x32_bf16 v[192:195], v[178:181], v[196:199], v[12:15]
	v_mfma_f32_16x16x32_bf16 v[12:15], v[124:127], v[200:203], v[20:23]
	v_mfma_f32_16x16x32_bf16 v[146:149], v[146:149], v[204:207], v[12:15]
	v_mfma_f32_16x16x32_bf16 v[12:15], v[174:177], v[200:203], v[24:27]
	v_mfma_f32_16x16x32_bf16 v[174:177], v[178:181], v[204:207], v[12:15]
	s_setprio 0
	s_barrier
	s_nop 4
	ds_read_b128 v[12:15], v224
	ds_read_b128 v[24:27], v224 offset:1024
	ds_read_b128 v[64:67], v224 offset:2048
	ds_read_b128 v[178:181], v224 offset:3072
	ds_read_b128 v[196:199], v225
	ds_read_b128 v[200:203], v225 offset:1024
	ds_read_b128 v[204:207], v225 offset:2048
	ds_read_b128 v[224:227], v225 offset:3072
	s_mov_b32 m0, s41
	v_lshl_add_u64 v[52:53], s[48:49], 0, v[134:135]
	s_add_u32 s42, s48, 0x10000
	ds_read_b128 v[20:23], v145 offset:32768
	ds_read_b128 v[28:31], v145 offset:33792
	ds_read_b128 v[228:231], v145 offset:34816
	ds_read_b128 v[232:235], v145 offset:35840
	ds_read_b128 v[236:239], v145 offset:36864
	ds_read_b128 v[240:243], v145 offset:37888
	ds_read_b128 v[244:247], v145 offset:38912
	ds_read_b128 v[248:251], v145 offset:39936
	global_load_lds_dwordx4 v[52:53], off
	v_lshl_add_u64 v[52:53], s[48:49], 0, v[130:131]
	s_mov_b32 m0, s66
	s_addc_u32 s43, s49, 0
	global_load_lds_dwordx4 v[52:53], off
	v_lshl_add_u64 v[52:53], s[42:43], 0, v[134:135]
	s_mov_b32 m0, s67
	s_nop 0
	global_load_lds_dwordx4 v[52:53], off
	v_lshl_add_u64 v[52:53], s[42:43], 0, v[130:131]
	s_mov_b32 m0, s68
	s_nop 0
	global_load_lds_dwordx4 v[52:53], off
	s_waitcnt vmcnt(8) lgkmcnt(0)
	s_barrier
; #define PG8_STAGE(bufoff, gbase, voff) do { _Pragma("unroll") for (int _i = 0; _i < 2; ++_i) \
;         __builtin_amdgcn_global_load_lds((const unsigned*)((const char*)(gbase) + (voff)[_i]), (LAS unsigned*)(lds + (bufoff) + ldsw + _i * 8192), 16, 0, 0); } while (0)
; #define PG8_LDA(dst, b, h) do { _Pragma("unroll") for (int m = 0; m < 4; ++m) _Pragma("unroll") for (int k = 0; k < 2; ++k) dst[m][k] = *(const LAS bf16x8*)(lds + PG8_SA(b, h) + aoff + m * 2048 + k * 1024); } while (0)
; #define PG8_MMA(ai, bj, At, Bt) do { __builtin_amdgcn_s_setprio(3); _Pragma("unroll") for (int m = 0; m < 4; ++m) _Pragma("unroll") for (int n = 0; n < 2; ++n) _Pragma("unroll") for (int k = 0; k < 2; ++k) \
;         acc[ai][bj][m][n] = __builtin_amdgcn_mfma_f32_16x16x32_bf16(Bt[n][k], At[m][k], acc[ai][bj][m][n], 0, 0, 0); __builtin_amdgcn_s_setprio(0); } while (0)
; #define PG8_WAIT_V(n) asm volatile("s_waitcnt vmcnt(" #n ")" ::: "memory")
; #define PG8_WAIT_L(n) asm volatile("s_waitcnt lgkmcnt(" #n ")" ::: "memory")
; #define PG8_BAR __builtin_amdgcn_s_barrier()
; #define PG8_SCHED __builtin_amdgcn_sched_barrier(0)
; template <class Epi, class Sched>
; __device__ __forceinline__ void gemm_phase(LAS unsigned char* lds, const Gemm g, const Sched& S, const Epi& E, int tid_in) {
;     ...
;             PG8_WAIT_V(8); PG8_WAIT_L(0); PG8_BAR; PG8_MMA(0, 0, At, B0); PG8_MMA(0, 1, At, B1); PG8_BAR; PG8_SCHED;
;             PG8_LDA(At, 1, 1); PG8_STAGE(PG8_SB(1, 0), b3, voffB); PG8_STAGE(PG8_SB(1, 1), b3 + hstep, voffB);
;             PG8_WAIT_V(6); PG8_WAIT_L(0); PG8_BAR; PG8_MMA(1, 0, At, B0); PG8_MMA(1, 1, At, B1); PG8_BAR; PG8_SCHED;
;         }
;         if (wr == 0) PG8_BAR;
	s_setprio 3
	v_mfma_f32_16x16x32_bf16 v[0:3], v[12:15], v[20:23], v[0:3]
	v_mfma_f32_16x16x32_bf16 v[124:127], v[24:27], v[28:31], v[0:3]
	v_mfma_f32_16x16x32_bf16 v[0:3], v[64:67], v[20:23], v[68:71]
	v_mfma_f32_16x16x32_bf16 v[116:119], v[178:181], v[28:31], v[0:3]
	v_mfma_f32_16x16x32_bf16 v[0:3], v[12:15], v[228:231], v[72:75]
	v_mfma_f32_16x16x32_bf16 v[108:111], v[24:27], v[232:235], v[0:3]
	v_mfma_f32_16x16x32_bf16 v[0:3], v[64:67], v[228:231], v[76:79]
	v_mfma_f32_16x16x32_bf16 v[100:103], v[178:181], v[232:235], v[0:3]
	v_mfma_f32_16x16x32_bf16 v[0:3], v[12:15], v[236:239], v[80:83]
	v_mfma_f32_16x16x32_bf16 v[92:95], v[24:27], v[240:243], v[0:3]
	v_mfma_f32_16x16x32_bf16 v[0:3], v[64:67], v[236:239], v[84:87]
	v_mfma_f32_16x16x32_bf16 v[84:87], v[178:181], v[240:243], v[0:3]
	v_mfma_f32_16x16x32_bf16 v[0:3], v[12:15], v[244:247], v[88:91]
	v_mfma_f32_16x16x32_bf16 v[60:63], v[24:27], v[248:251], v[0:3]
	v_mfma_f32_16x16x32_bf16 v[0:3], v[64:67], v[244:247], v[96:99]
	v_mfma_f32_16x16x32_bf16 v[52:55], v[178:181], v[248:251], v[0:3]
	s_setprio 0
	s_setprio 3
	v_mfma_f32_16x16x32_bf16 v[0:3], v[196:199], v[20:23], v[216:219]
	v_mfma_f32_16x16x32_bf16 v[120:123], v[200:203], v[28:31], v[0:3]
	v_mfma_f32_16x16x32_bf16 v[0:3], v[204:207], v[20:23], v[36:39]
	v_mfma_f32_16x16x32_bf16 v[112:115], v[224:227], v[28:31], v[0:3]
	v_mfma_f32_16x16x32_bf16 v[0:3], v[196:199], v[228:231], v[40:43]
	v_mfma_f32_16x16x32_bf16 v[104:107], v[200:203], v[232:235], v[0:3]
	v_mfma_f32_16x16x32_bf16 v[0:3], v[204:207], v[228:231], v[44:47]
	v_mfma_f32_16x16x32_bf16 v[96:99], v[224:227], v[232:235], v[0:3]
	v_mfma_f32_16x16x32_bf16 v[0:3], v[196:199], v[236:239], v[48:51]
	v_mfma_f32_16x16x32_bf16 v[88:91], v[200:203], v[240:243], v[0:3]
	v_mfma_f32_16x16x32_bf16 v[0:3], v[204:207], v[236:239], v[182:185]
	v_mfma_f32_16x16x32_bf16 v[80:83], v[224:227], v[240:243], v[0:3]
	v_mfma_f32_16x16x32_bf16 v[0:3], v[196:199], v[244:247], v[56:59]
	v_mfma_f32_16x16x32_bf16 v[56:59], v[200:203], v[248:251], v[0:3]
	v_mfma_f32_16x16x32_bf16 v[0:3], v[204:207], v[244:247], v[188:191]
	v_mfma_f32_16x16x32_bf16 v[48:51], v[224:227], v[248:251], v[0:3]
	s_setprio 0
	s_barrier
	s_mov_b32 m0, s83
	v_lshl_add_u64 v[20:21], v[252:253], 0, s[8:9]
	s_add_u32 s42, s46, 0x10080
	s_nop 1
	ds_read_b128 v[0:3], v145 offset:49152
	ds_read_b128 v[40:43], v145 offset:50176
	ds_read_b128 v[182:185], v145 offset:51200
	ds_read_b128 v[188:191], v145 offset:52224
	ds_read_b128 v[216:219], v145 offset:53248
	ds_read_b128 v[228:231], v145 offset:54272
	ds_read_b128 v[232:235], v145 offset:55296
	ds_read_b128 v[236:239], v145 offset:56320
	global_load_lds_dwordx4 v[20:21], off
	v_lshl_add_u64 v[20:21], v[186:187], 0, s[8:9]
	s_mov_b32 m0, s81
	s_addc_u32 s43, s47, 0
	global_load_lds_dwordx4 v[20:21], off
	v_lshl_add_u64 v[20:21], s[42:43], 0, v[132:133]
	s_mov_b32 m0, s44
	s_nop 0
	global_load_lds_dwordx4 v[20:21], off
	v_lshl_add_u64 v[20:21], s[42:43], 0, v[128:129]
	s_mov_b32 m0, s45
	s_nop 0
	global_load_lds_dwordx4 v[20:21], off
	s_waitcnt vmcnt(6) lgkmcnt(0)
	s_barrier
	s_setprio 3
	v_mfma_f32_16x16x32_bf16 v[20:23], v[12:15], v[0:3], v[150:153]
	v_mfma_f32_16x16x32_bf16 v[76:79], v[24:27], v[40:43], v[20:23]
	v_mfma_f32_16x16x32_bf16 v[20:23], v[64:67], v[0:3], v[154:157]
	v_mfma_f32_16x16x32_bf16 v[68:71], v[178:181], v[40:43], v[20:23]
	v_mfma_f32_16x16x32_bf16 v[20:23], v[12:15], v[182:185], v[158:161]
	v_mfma_f32_16x16x32_bf16 v[44:47], v[24:27], v[188:191], v[20:23]
	v_mfma_f32_16x16x32_bf16 v[20:23], v[64:67], v[182:185], v[162:165]
	v_mfma_f32_16x16x32_bf16 v[36:39], v[178:181], v[188:191], v[20:23]
	v_mfma_f32_16x16x32_bf16 v[20:23], v[12:15], v[216:219], v[166:169]
	v_mfma_f32_16x16x32_bf16 v[4:7], v[12:15], v[232:235], v[4:7]
	v_mfma_f32_16x16x32_bf16 v[28:31], v[24:27], v[228:231], v[20:23]
	v_mfma_f32_16x16x32_bf16 v[20:23], v[64:67], v[216:219], v[170:173]
	v_mfma_f32_16x16x32_bf16 v[12:15], v[24:27], v[236:239], v[4:7]
	v_mfma_f32_16x16x32_bf16 v[4:7], v[64:67], v[232:235], v[8:11]
	v_mfma_f32_16x16x32_bf16 v[20:23], v[178:181], v[228:231], v[20:23]
	v_mfma_f32_16x16x32_bf16 v[4:7], v[178:181], v[236:239], v[4:7]
	s_setprio 0
	s_setprio 3
	v_mfma_f32_16x16x32_bf16 v[8:11], v[196:199], v[0:3], v[208:211]
	v_mfma_f32_16x16x32_bf16 v[0:3], v[204:207], v[0:3], v[16:19]
	v_mfma_f32_16x16x32_bf16 v[64:67], v[224:227], v[40:43], v[0:3]
	v_mfma_f32_16x16x32_bf16 v[0:3], v[196:199], v[182:185], v[212:215]
	v_mfma_f32_16x16x32_bf16 v[72:75], v[200:203], v[40:43], v[8:11]
	v_mfma_f32_16x16x32_bf16 v[40:43], v[200:203], v[188:191], v[0:3]
	v_mfma_f32_16x16x32_bf16 v[0:3], v[204:207], v[182:185], v[32:35]
	v_mfma_f32_16x16x32_bf16 v[32:35], v[224:227], v[188:191], v[0:3]
	v_mfma_f32_16x16x32_bf16 v[0:3], v[196:199], v[216:219], v[220:223]
	v_mfma_f32_16x16x32_bf16 v[24:27], v[200:203], v[228:231], v[0:3]
	v_mfma_f32_16x16x32_bf16 v[0:3], v[204:207], v[216:219], v[192:195]
	v_mfma_f32_16x16x32_bf16 v[16:19], v[224:227], v[228:231], v[0:3]
	v_mfma_f32_16x16x32_bf16 v[0:3], v[196:199], v[232:235], v[146:149]
	v_mfma_f32_16x16x32_bf16 v[8:11], v[200:203], v[236:239], v[0:3]
	v_mfma_f32_16x16x32_bf16 v[0:3], v[204:207], v[232:235], v[174:177]
	v_mfma_f32_16x16x32_bf16 v[0:3], v[224:227], v[236:239], v[0:3]
	s_setprio 0
	s_barrier
	s_andn2_b64 vcc, exec, s[14:15]
	s_cbranch_vccnz .LBB0_990
	s_barrier

;     __device__ bool next(int i, Unit& u) const { if (!b.next(i >> 1, u)) return false; u.half = i & 1; u.koff = (i & 1) * kbytes; return true; }
; #define PG8_STAGE(bufoff, gbase, voff) do { _Pragma("unroll") for (int _i = 0; _i < 2; ++_i) \
;         __builtin_amdgcn_global_load_lds((const unsigned*)((const char*)(gbase) + (voff)[_i]), (LAS unsigned*)(lds + (bufoff) + ldsw + _i * 8192), 16, 0, 0); } while (0)
; #define PG8_LDA(dst, b, h) do { _Pragma("unroll") for (int m = 0; m < 4; ++m) _Pragma("unroll") for (int k = 0; k < 2; ++k) dst[m][k] = *(const LAS bf16x8*)(lds + PG8_SA(b, h) + aoff + m * 2048 + k * 1024); } while (0)
; #define PG8_LDB(dst, b, h) do { _Pragma("unroll") for (int n = 0; n < 2; ++n) _Pragma("unroll") for (int k = 0; k < 2; ++k) dst[n][k] = *(const LAS bf16x8*)(lds + PG8_SB(b, h) + boff + n * 2048 + k * 1024); } while (0)
; #define PG8_MMA(ai, bj, At, Bt) do { __builtin_amdgcn_s_setprio(3); _Pragma("unroll") for (int m = 0; m < 4; ++m) _Pragma("unroll") for (int n = 0; n < 2; ++n) _Pragma("unroll") for (int k = 0; k < 2; ++k) \
;         acc[ai][bj][m][n] = __builtin_amdgcn_mfma_f32_16x16x32_bf16(Bt[n][k], At[m][k], acc[ai][bj][m][n], 0, 0, 0); __builtin_amdgcn_s_setprio(0); } while (0)
; template <class Epi, class Sched>
; __device__ __forceinline__ void gemm_phase(LAS unsigned char* lds, const Gemm g, const Sched& S, const Epi& E, int tid_in) {
;     ...
;         const bool has_next = S.next(ui + 1, nxt);
;         const char* nA = has_next ? (const char*)g.A + (size_t)nxt.pm * tstep + nxt.koff : cA; const char* nB = has_next ? (const char*)g.Bt + (size_t)nxt.pn * tstep + nxt.koff : cB;
;         for (int t = 0; t < nt; t += 2) {
;             const bool last = (t == nt - 2);
;             const char* a1 = cA + (size_t)(t + 1) * kstep;
;             const char* a2 = last ? nA : cA + (size_t)(t + 2) * kstep; const char* b2 = last ? nB : cB + (size_t)(t + 2) * kstep;
;             const char* a3 = a2 + kstep; const char* b3 = b2 + kstep;
;             PG8_LDB(B0, 0, 0); PG8_LDB(B1, 0, 1); PG8_SCHED; PG8_LDA(At, 0, 0); PG8_STAGE(PG8_SA(1, 0), a1, voffA); PG8_STAGE(PG8_SA(1, 1), a1 + hstep, voffA);
;             PG8_WAIT_V(8); PG8_WAIT_L(0); PG8_BAR; PG8_MMA(0, 0, At, B0); PG8_MMA(0, 1, At, B1); PG8_BAR; PG8_SCHED;
;             PG8_LDA(At, 0, 1); PG8_STAGE(PG8_SB(0, 0), b2, voffB); PG8_STAGE(PG8_SB(0, 1), b2 + hstep, voffB);
.LBB0_1008:
	s_ashr_i32 s23, s22, 31
	s_lshl_b64 s[24:25], s[22:23], 20
	s_add_u32 s24, s58, s24
	s_addc_u32 s25, s59, s25
	s_and_b64 s[26:27], s[4:5], exec
	s_cselect_b32 s23, s25, s31
	s_cselect_b32 s29, s24, s30
	s_ashr_i32 s21, s20, 31
	s_lshl_b64 s[26:27], s[20:21], 20
	s_add_u32 s26, s60, s26
	s_addc_u32 s27, s61, s27
	s_and_b64 s[36:37], s[4:5], exec
	s_cselect_b32 s21, s27, s35
	s_cselect_b32 s47, s26, s34
	s_add_u32 s48, s34, 0x100
	v_lshl_add_u64 v[144:145], s[30:31], 0, v[136:137]
	v_lshl_add_u64 v[146:147], s[30:31], 0, v[138:139]
	s_addc_u32 s49, s35, 0
	s_mov_b32 s51, -2
	s_mov_b64 s[34:35], 0
	s_waitcnt lgkmcnt(0)
	ds_read_b128 v[158:161], v153
	ds_read_b128 v[162:165], v153 offset:1024
	ds_read_b128 v[166:169], v153 offset:2048
	ds_read_b128 v[170:173], v153 offset:3072
	ds_read_b128 v[174:177], v154
	ds_read_b128 v[178:181], v154 offset:1024
	ds_read_b128 v[182:185], v154 offset:2048
	ds_read_b128 v[188:191], v154 offset:3072
	s_add_u32 s36, s30, s34
	s_addc_u32 s37, s31, s35
	s_add_u32 s38, s36, 0x100
	s_addc_u32 s39, s37, 0
	s_add_u32 s36, s48, s34
	s_addc_u32 s37, s49, s35
	s_cmpk_eq_i32 s34, 0xf00
	s_cselect_b32 s37, s21, s37
	s_cselect_b32 s36, s47, s36
	s_cselect_b32 s39, s23, s39
	s_cselect_b32 s38, s29, s38
	v_lshl_add_u64 v[148:149], v[146:147], 0, s[34:35]
	v_lshl_add_u64 v[186:187], v[148:149], 0, s[14:15]
	s_add_i32 m0, s3, 0x8000
	ds_read_b128 v[192:195], v155
	ds_read_b128 v[196:199], v155 offset:1024
	ds_read_b128 v[200:203], v155 offset:2048
	ds_read_b128 v[204:207], v155 offset:3072
	ds_read_b128 v[208:211], v155 offset:4096
	ds_read_b128 v[212:215], v155 offset:5120
	ds_read_b128 v[216:219], v155 offset:6144
	ds_read_b128 v[220:223], v155 offset:7168
	global_load_lds_dwordx4 v[186:187], off
	v_lshl_add_u64 v[186:187], v[144:145], 0, s[34:35]
	v_lshl_add_u64 v[224:225], v[186:187], 0, s[14:15]
	s_add_i32 m0, s3, 0xa000
	v_lshl_add_u64 v[148:149], v[148:149], 0, s[16:17]
	global_load_lds_dwordx4 v[224:225], off
	s_add_i32 m0, s3, 0xc000
	s_nop 0
	global_load_lds_dwordx4 v[148:149], off
	v_lshl_add_u64 v[148:149], v[186:187], 0, s[16:17]
	s_add_i32 m0, s3, 0xe000
	s_nop 0
	global_load_lds_dwordx4 v[148:149], off
	s_waitcnt vmcnt(8) lgkmcnt(0)
	s_barrier
	s_setprio 3
	v_mfma_f32_16x16x32_bf16 v[124:127], v[158:161], v[192:195], 0
	v_mfma_f32_16x16x32_bf16 v[120:123], v[166:169], v[192:195], 0
	v_mfma_f32_16x16x32_bf16 v[108:111], v[158:161], v[200:203], 0
	v_mfma_f32_16x16x32_bf16 v[104:107], v[166:169], v[200:203], 0
	v_mfma_f32_16x16x32_bf16 v[92:95], v[158:161], v[208:211], 0
	v_mfma_f32_16x16x32_bf16 v[88:91], v[166:169], v[208:211], 0
	v_mfma_f32_16x16x32_bf16 v[76:79], v[158:161], v[216:219], 0
	v_mfma_f32_16x16x32_bf16 v[72:75], v[166:169], v[216:219], 0
	v_mfma_f32_16x16x32_bf16 v[124:127], v[162:165], v[196:199], v[124:127]
	v_mfma_f32_16x16x32_bf16 v[120:123], v[170:173], v[196:199], v[120:123]
	v_mfma_f32_16x16x32_bf16 v[108:111], v[162:165], v[204:207], v[108:111]
	v_mfma_f32_16x16x32_bf16 v[104:107], v[170:173], v[204:207], v[104:107]
	v_mfma_f32_16x16x32_bf16 v[92:95], v[162:165], v[212:215], v[92:95]
	v_mfma_f32_16x16x32_bf16 v[88:91], v[170:173], v[212:215], v[88:91]
	v_mfma_f32_16x16x32_bf16 v[76:79], v[162:165], v[220:223], v[76:79]
	v_mfma_f32_16x16x32_bf16 v[72:75], v[170:173], v[220:223], v[72:75]
	s_setprio 0
	s_setprio 3
	v_mfma_f32_16x16x32_bf16 v[116:119], v[174:177], v[192:195], 0
	v_mfma_f32_16x16x32_bf16 v[112:115], v[182:185], v[192:195], 0
	v_mfma_f32_16x16x32_bf16 v[100:103], v[174:177], v[200:203], 0
	v_mfma_f32_16x16x32_bf16 v[96:99], v[182:185], v[200:203], 0
	v_mfma_f32_16x16x32_bf16 v[84:87], v[174:177], v[208:211], 0
	v_mfma_f32_16x16x32_bf16 v[80:83], v[182:185], v[208:211], 0
	v_mfma_f32_16x16x32_bf16 v[68:71], v[174:177], v[216:219], 0
	v_mfma_f32_16x16x32_bf16 v[64:67], v[182:185], v[216:219], 0
	v_mfma_f32_16x16x32_bf16 v[116:119], v[178:181], v[196:199], v[116:119]
	v_mfma_f32_16x16x32_bf16 v[112:115], v[188:191], v[196:199], v[112:115]
	v_mfma_f32_16x16x32_bf16 v[100:103], v[178:181], v[204:207], v[100:103]
	v_mfma_f32_16x16x32_bf16 v[96:99], v[188:191], v[204:207], v[96:99]
	v_mfma_f32_16x16x32_bf16 v[84:87], v[178:181], v[212:215], v[84:87]
	v_mfma_f32_16x16x32_bf16 v[80:83], v[188:191], v[212:215], v[80:83]
	v_mfma_f32_16x16x32_bf16 v[68:71], v[178:181], v[220:223], v[68:71]
	v_mfma_f32_16x16x32_bf16 v[64:67], v[188:191], v[220:223], v[64:67]
	s_setprio 0
	s_barrier
	s_add_i32 s62, s44, s2
	v_lshl_add_u64 v[148:149], s[36:37], 0, v[130:131]
	s_mov_b32 m0, s62
	ds_read_b128 v[192:195], v155 offset:16384
	ds_read_b128 v[196:199], v155 offset:17408
	ds_read_b128 v[200:203], v155 offset:18432
	ds_read_b128 v[204:207], v155 offset:19456
	ds_read_b128 v[208:211], v155 offset:20480
	ds_read_b128 v[212:215], v155 offset:21504
	ds_read_b128 v[216:219], v155 offset:22528
	ds_read_b128 v[220:223], v155 offset:23552
	global_load_lds_dwordx4 v[148:149], off
	s_add_i32 m0, s62, 0x2000
	s_add_u32 s62, s36, 0x80000
	v_lshl_add_u64 v[186:187], s[36:37], 0, v[134:135]
	s_addc_u32 s63, s37, 0
	s_add_i32 s64, s45, s2
	global_load_lds_dwordx4 v[186:187], off
	v_lshl_add_u64 v[224:225], s[62:63], 0, v[130:131]
	s_mov_b32 m0, s64
	s_nop 0
	global_load_lds_dwordx4 v[224:225], off
	v_lshl_add_u64 v[224:225], s[62:63], 0, v[134:135]
	s_add_i32 m0, s64, 0x2000
	s_nop 0
	global_load_lds_dwordx4 v[224:225], off
	s_waitcnt vmcnt(6) lgkmcnt(0)
	s_barrier
; #define PG8_STAGE(bufoff, gbase, voff) do { _Pragma("unroll") for (int _i = 0; _i < 2; ++_i) \
;         __builtin_amdgcn_global_load_lds((const unsigned*)((const char*)(gbase) + (voff)[_i]), (LAS unsigned*)(lds + (bufoff) + ldsw + _i * 8192), 16, 0, 0); } while (0)
; #define PG8_LDA(dst, b, h) do { _Pragma("unroll") for (int m = 0; m < 4; ++m) _Pragma("unroll") for (int k = 0; k < 2; ++k) dst[m][k] = *(const LAS bf16x8*)(lds + PG8_SA(b, h) + aoff + m * 2048 + k * 1024); } while (0)
; #define PG8_LDB(dst, b, h) do { _Pragma("unroll") for (int n = 0; n < 2; ++n) _Pragma("unroll") for (int k = 0; k < 2; ++k) dst[n][k] = *(const LAS bf16x8*)(lds + PG8_SB(b, h) + boff + n * 2048 + k * 1024); } while (0)
; #define PG8_MMA(ai, bj, At, Bt) do { __builtin_amdgcn_s_setprio(3); _Pragma("unroll") for (int m = 0; m < 4; ++m) _Pragma("unroll") for (int n = 0; n < 2; ++n) _Pragma("unroll") for (int k = 0; k < 2; ++k) \
;         acc[ai][bj][m][n] = __builtin_amdgcn_mfma_f32_16x16x32_bf16(Bt[n][k], At[m][k], acc[ai][bj][m][n], 0, 0, 0); __builtin_amdgcn_s_setprio(0); } while (0)
; #define PG8_WAIT_V(n) asm volatile("s_waitcnt vmcnt(" #n ")" ::: "memory")
; #define PG8_WAIT_L(n) asm volatile("s_waitcnt lgkmcnt(" #n ")" ::: "memory")
; #define PG8_BAR __builtin_amdgcn_s_barrier()
; #define PG8_SCHED __builtin_amdgcn_sched_barrier(0)
; template <class Epi, class Sched>
; __device__ __forceinline__ void gemm_phase(LAS unsigned char* lds, const Gemm g, const Sched& S, const Epi& E, int tid_in) {
;     ...
;             PG8_WAIT_V(6); PG8_WAIT_L(0); PG8_BAR; PG8_MMA(1, 0, At, B0); PG8_MMA(1, 1, At, B1); PG8_BAR; PG8_SCHED;
;             PG8_LDB(B0, 1, 0); PG8_LDB(B1, 1, 1); PG8_SCHED; PG8_LDA(At, 1, 0); PG8_STAGE(PG8_SA(0, 0), a2, voffA); PG8_STAGE(PG8_SA(0, 1), a2 + hstep, voffA);
;             PG8_WAIT_V(8); PG8_WAIT_L(0); PG8_BAR; PG8_MMA(0, 0, At, B0); PG8_MMA(0, 1, At, B1); PG8_BAR; PG8_SCHED;
	s_setprio 3
	v_mfma_f32_16x16x32_bf16 v[60:63], v[158:161], v[192:195], 0
	v_mfma_f32_16x16x32_bf16 v[56:59], v[166:169], v[192:195], 0
	v_mfma_f32_16x16x32_bf16 v[44:47], v[158:161], v[200:203], 0
	v_mfma_f32_16x16x32_bf16 v[40:43], v[166:169], v[200:203], 0
	v_mfma_f32_16x16x32_bf16 v[28:31], v[158:161], v[208:211], 0
	v_mfma_f32_16x16x32_bf16 v[24:27], v[166:169], v[208:211], 0
	v_mfma_f32_16x16x32_bf16 v[12:15], v[158:161], v[216:219], 0
	v_mfma_f32_16x16x32_bf16 v[8:11], v[166:169], v[216:219], 0
	v_mfma_f32_16x16x32_bf16 v[60:63], v[162:165], v[196:199], v[60:63]
	v_mfma_f32_16x16x32_bf16 v[56:59], v[170:173], v[196:199], v[56:59]
	v_mfma_f32_16x16x32_bf16 v[44:47], v[162:165], v[204:207], v[44:47]
	v_mfma_f32_16x16x32_bf16 v[40:43], v[170:173], v[204:207], v[40:43]
	v_mfma_f32_16x16x32_bf16 v[28:31], v[162:165], v[212:215], v[28:31]
	v_mfma_f32_16x16x32_bf16 v[24:27], v[170:173], v[212:215], v[24:27]
	v_mfma_f32_16x16x32_bf16 v[12:15], v[162:165], v[220:223], v[12:15]
	v_mfma_f32_16x16x32_bf16 v[8:11], v[170:173], v[220:223], v[8:11]
	s_setprio 0
	s_setprio 3
	v_mfma_f32_16x16x32_bf16 v[52:55], v[174:177], v[192:195], 0
	v_mfma_f32_16x16x32_bf16 v[48:51], v[182:185], v[192:195], 0
	v_mfma_f32_16x16x32_bf16 v[36:39], v[174:177], v[200:203], 0
	v_mfma_f32_16x16x32_bf16 v[32:35], v[182:185], v[200:203], 0
	v_mfma_f32_16x16x32_bf16 v[20:23], v[174:177], v[208:211], 0
	v_mfma_f32_16x16x32_bf16 v[16:19], v[182:185], v[208:211], 0
	v_mfma_f32_16x16x32_bf16 v[4:7], v[174:177], v[216:219], 0
	v_mfma_f32_16x16x32_bf16 v[0:3], v[182:185], v[216:219], 0
	v_mfma_f32_16x16x32_bf16 v[52:55], v[178:181], v[196:199], v[52:55]
	v_mfma_f32_16x16x32_bf16 v[48:51], v[188:191], v[196:199], v[48:51]
	v_mfma_f32_16x16x32_bf16 v[36:39], v[178:181], v[204:207], v[36:39]
	v_mfma_f32_16x16x32_bf16 v[32:35], v[188:191], v[204:207], v[32:35]
	v_mfma_f32_16x16x32_bf16 v[20:23], v[178:181], v[212:215], v[20:23]
	v_mfma_f32_16x16x32_bf16 v[16:19], v[188:191], v[212:215], v[16:19]
	v_mfma_f32_16x16x32_bf16 v[4:7], v[178:181], v[220:223], v[4:7]
	v_mfma_f32_16x16x32_bf16 v[0:3], v[188:191], v[220:223], v[0:3]
	s_setprio 0
	s_barrier
	s_add_i32 s62, 0, 0x18000
	v_add_u32_e32 v157, s62, v151
	s_add_i32 s63, 0, 0x1c000
	ds_read_b128 v[158:161], v157
	ds_read_b128 v[162:165], v157 offset:1024
	ds_read_b128 v[166:169], v157 offset:2048
	ds_read_b128 v[170:173], v157 offset:3072
	v_add_u32_e32 v157, s63, v151
	ds_read_b128 v[174:177], v157
	ds_read_b128 v[178:181], v157 offset:1024
	ds_read_b128 v[182:185], v157 offset:2048
	ds_read_b128 v[188:191], v157 offset:3072
	s_mov_b32 m0, s3
	v_lshl_add_u64 v[224:225], s[38:39], 0, v[128:129]
	ds_read_b128 v[192:195], v155 offset:32768
	ds_read_b128 v[196:199], v155 offset:33792
	ds_read_b128 v[200:203], v155 offset:34816
	ds_read_b128 v[204:207], v155 offset:35840
	ds_read_b128 v[208:211], v155 offset:36864
	ds_read_b128 v[212:215], v155 offset:37888
	ds_read_b128 v[216:219], v155 offset:38912
	ds_read_b128 v[220:223], v155 offset:39936
	global_load_lds_dwordx4 v[224:225], off
	v_lshl_add_u64 v[224:225], s[38:39], 0, v[132:133]
	s_add_u32 s38, s38, 0x80000
	s_mov_b32 m0, s40
	s_addc_u32 s39, s39, 0
	global_load_lds_dwordx4 v[224:225], off
	v_lshl_add_u64 v[224:225], s[38:39], 0, v[128:129]
	s_mov_b32 m0, s41
	s_nop 0
	global_load_lds_dwordx4 v[224:225], off
	v_lshl_add_u64 v[224:225], s[38:39], 0, v[132:133]
	s_mov_b32 m0, s42
	s_nop 0
	global_load_lds_dwordx4 v[224:225], off
	s_waitcnt vmcnt(8) lgkmcnt(0)
	s_barrier
	s_setprio 3
	v_mfma_f32_16x16x32_bf16 v[124:127], v[158:161], v[192:195], v[124:127]
	v_mfma_f32_16x16x32_bf16 v[120:123], v[166:169], v[192:195], v[120:123]
	v_mfma_f32_16x16x32_bf16 v[108:111], v[158:161], v[200:203], v[108:111]
	v_mfma_f32_16x16x32_bf16 v[104:107], v[166:169], v[200:203], v[104:107]
	v_mfma_f32_16x16x32_bf16 v[92:95], v[158:161], v[208:211], v[92:95]
	v_mfma_f32_16x16x32_bf16 v[88:91], v[166:169], v[208:211], v[88:91]
	v_mfma_f32_16x16x32_bf16 v[76:79], v[158:161], v[216:219], v[76:79]
	v_mfma_f32_16x16x32_bf16 v[72:75], v[166:169], v[216:219], v[72:75]
	v_mfma_f32_16x16x32_bf16 v[124:127], v[162:165], v[196:199], v[124:127]
	v_mfma_f32_16x16x32_bf16 v[120:123], v[170:173], v[196:199], v[120:123]
	v_mfma_f32_16x16x32_bf16 v[108:111], v[162:165], v[204:207], v[108:111]
	v_mfma_f32_16x16x32_bf16 v[104:107], v[170:173], v[204:207], v[104:107]
	v_mfma_f32_16x16x32_bf16 v[92:95], v[162:165], v[212:215], v[92:95]
	v_mfma_f32_16x16x32_bf16 v[88:91], v[170:173], v[212:215], v[88:91]
	v_mfma_f32_16x16x32_bf16 v[76:79], v[162:165], v[220:223], v[76:79]
	v_mfma_f32_16x16x32_bf16 v[72:75], v[170:173], v[220:223], v[72:75]
	s_setprio 0
	s_setprio 3
	v_mfma_f32_16x16x32_bf16 v[116:119], v[174:177], v[192:195], v[116:119]
	v_mfma_f32_16x16x32_bf16 v[112:115], v[182:185], v[192:195], v[112:115]
	v_mfma_f32_16x16x32_bf16 v[100:103], v[174:177], v[200:203], v[100:103]
	v_mfma_f32_16x16x32_bf16 v[96:99], v[182:185], v[200:203], v[96:99]
	v_mfma_f32_16x16x32_bf16 v[84:87], v[174:177], v[208:211], v[84:87]
	v_mfma_f32_16x16x32_bf16 v[80:83], v[182:185], v[208:211], v[80:83]
	v_mfma_f32_16x16x32_bf16 v[68:71], v[174:177], v[216:219], v[68:71]
	v_mfma_f32_16x16x32_bf16 v[64:67], v[182:185], v[216:219], v[64:67]
	v_mfma_f32_16x16x32_bf16 v[116:119], v[178:181], v[196:199], v[116:119]
	v_mfma_f32_16x16x32_bf16 v[112:115], v[188:191], v[196:199], v[112:115]
	v_mfma_f32_16x16x32_bf16 v[100:103], v[178:181], v[204:207], v[100:103]
	v_mfma_f32_16x16x32_bf16 v[96:99], v[188:191], v[204:207], v[96:99]
	v_mfma_f32_16x16x32_bf16 v[84:87], v[178:181], v[212:215], v[84:87]
	v_mfma_f32_16x16x32_bf16 v[80:83], v[188:191], v[212:215], v[80:83]
	v_mfma_f32_16x16x32_bf16 v[68:71], v[178:181], v[220:223], v[68:71]
	v_mfma_f32_16x16x32_bf16 v[64:67], v[188:191], v[220:223], v[64:67]
	s_setprio 0
	s_barrier
; #define PG8_STAGE(bufoff, gbase, voff) do { _Pragma("unroll") for (int _i = 0; _i < 2; ++_i) \
;         __builtin_amdgcn_global_load_lds((const unsigned*)((const char*)(gbase) + (voff)[_i]), (LAS unsigned*)(lds + (bufoff) + ldsw + _i * 8192), 16, 0, 0); } while (0)
; #define PG8_LDA(dst, b, h) do { _Pragma("unroll") for (int m = 0; m < 4; ++m) _Pragma("unroll") for (int k = 0; k < 2; ++k) dst[m][k] = *(const LAS bf16x8*)(lds + PG8_SA(b, h) + aoff + m * 2048 + k * 1024); } while (0)
; #define PG8_LDB(dst, b, h) do { _Pragma("unroll") for (int n = 0; n < 2; ++n) _Pragma("unroll") for (int k = 0; k < 2; ++k) dst[n][k] = *(const LAS bf16x8*)(lds + PG8_SB(b, h) + boff + n * 2048 + k * 1024); } while (0)
; #define PG8_WAIT_V(n) asm volatile("s_waitcnt vmcnt(" #n ")" ::: "memory")
; #define PG8_BAR __builtin_amdgcn_s_barrier()
; template <class Epi, class Sched>
; __device__ __forceinline__ void gemm_phase(LAS unsigned char* lds, const Gemm g, const Sched& S, const Epi& E, int tid_in) {
;     ...
;         for (int t = 0; t < nt; t += 2) {
;             const bool last = (t == nt - 2);
;             const char* a1 = cA + (size_t)(t + 1) * kstep;
;             const char* a2 = last ? nA : cA + (size_t)(t + 2) * kstep; const char* b2 = last ? nB : cB + (size_t)(t + 2) * kstep;
;             const char* a3 = a2 + kstep; const char* b3 = b2 + kstep;
;             PG8_LDB(B0, 0, 0); PG8_LDB(B1, 0, 1); PG8_SCHED; PG8_LDA(At, 0, 0); PG8_STAGE(PG8_SA(1, 0), a1, voffA); PG8_STAGE(PG8_SA(1, 1), a1 + hstep, voffA);
;             PG8_WAIT_V(8); PG8_WAIT_L(0); PG8_BAR; PG8_MMA(0, 0, At, B0); PG8_MMA(0, 1, At, B1); PG8_BAR; PG8_SCHED;
;             PG8_LDA(At, 0, 1); PG8_STAGE(PG8_SB(0, 0), b2, voffB); PG8_STAGE(PG8_SB(0, 1), b2 + hstep, voffB);
;             PG8_WAIT_V(6); PG8_WAIT_L(0); PG8_BAR; PG8_MMA(1, 0, At, B0); PG8_MMA(1, 1, At, B1); PG8_BAR; PG8_SCHED;
;             PG8_LDB(B0, 1, 0); PG8_LDB(B1, 1, 1); PG8_SCHED; PG8_LDA(At, 1, 0); PG8_STAGE(PG8_SA(0, 0), a2, voffA); PG8_STAGE(PG8_SA(0, 1), a2 + hstep, voffA);
;             PG8_WAIT_V(8); PG8_WAIT_L(0); PG8_BAR; PG8_MMA(0, 0, At, B0); PG8_MMA(0, 1, At, B1); PG8_BAR; PG8_SCHED;
;             PG8_LDA(At, 1, 1); PG8_STAGE(PG8_SB(1, 0), b3, voffB); PG8_STAGE(PG8_SB(1, 1), b3 + hstep, voffB);
;             PG8_WAIT_V(6); PG8_WAIT_L(0); PG8_BAR; PG8_MMA(1, 0, At, B0); PG8_MMA(1, 1, At, B1); PG8_BAR; PG8_SCHED;
	s_add_i32 s38, s62, s2
	v_lshl_add_u64 v[148:149], v[148:149], 0, s[14:15]
	s_mov_b32 m0, s38
	ds_read_b128 v[192:195], v155 offset:49152
	ds_read_b128 v[196:199], v155 offset:50176
	ds_read_b128 v[200:203], v155 offset:51200
	ds_read_b128 v[204:207], v155 offset:52224
	ds_read_b128 v[208:211], v155 offset:53248
	ds_read_b128 v[212:215], v155 offset:54272
	ds_read_b128 v[216:219], v155 offset:55296
	ds_read_b128 v[220:223], v155 offset:56320
	global_load_lds_dwordx4 v[148:149], off
	s_add_i32 m0, s38, 0x2000
	s_add_u32 s36, s36, 0x80080
	v_lshl_add_u64 v[148:149], v[186:187], 0, s[14:15]
	s_addc_u32 s37, s37, 0
	s_add_i32 s38, s63, s2
	global_load_lds_dwordx4 v[148:149], off
	v_lshl_add_u64 v[148:149], s[36:37], 0, v[130:131]
	s_mov_b32 m0, s38
	s_nop 0
	global_load_lds_dwordx4 v[148:149], off
	v_lshl_add_u64 v[148:149], s[36:37], 0, v[134:135]
	s_add_i32 m0, s38, 0x2000
	s_nop 0
	global_load_lds_dwordx4 v[148:149], off
	s_waitcnt vmcnt(6) lgkmcnt(0)
	s_barrier
	s_setprio 3
	v_mfma_f32_16x16x32_bf16 v[60:63], v[158:161], v[192:195], v[60:63]
	v_mfma_f32_16x16x32_bf16 v[56:59], v[166:169], v[192:195], v[56:59]
	v_mfma_f32_16x16x32_bf16 v[44:47], v[158:161], v[200:203], v[44:47]
	v_mfma_f32_16x16x32_bf16 v[40:43], v[166:169], v[200:203], v[40:43]
	v_mfma_f32_16x16x32_bf16 v[28:31], v[158:161], v[208:211], v[28:31]
	v_mfma_f32_16x16x32_bf16 v[24:27], v[166:169], v[208:211], v[24:27]
	v_mfma_f32_16x16x32_bf16 v[12:15], v[158:161], v[216:219], v[12:15]
	v_mfma_f32_16x16x32_bf16 v[8:11], v[166:169], v[216:219], v[8:11]
	v_mfma_f32_16x16x32_bf16 v[60:63], v[162:165], v[196:199], v[60:63]
	v_mfma_f32_16x16x32_bf16 v[56:59], v[170:173], v[196:199], v[56:59]
	v_mfma_f32_16x16x32_bf16 v[44:47], v[162:165], v[204:207], v[44:47]
	v_mfma_f32_16x16x32_bf16 v[40:43], v[170:173], v[204:207], v[40:43]
	v_mfma_f32_16x16x32_bf16 v[28:31], v[162:165], v[212:215], v[28:31]
	v_mfma_f32_16x16x32_bf16 v[24:27], v[170:173], v[212:215], v[24:27]
	v_mfma_f32_16x16x32_bf16 v[12:15], v[162:165], v[220:223], v[12:15]
	v_mfma_f32_16x16x32_bf16 v[8:11], v[170:173], v[220:223], v[8:11]
	s_setprio 0
	s_setprio 3
	v_mfma_f32_16x16x32_bf16 v[52:55], v[174:177], v[192:195], v[52:55]
	v_mfma_f32_16x16x32_bf16 v[48:51], v[182:185], v[192:195], v[48:51]
	v_mfma_f32_16x16x32_bf16 v[36:39], v[174:177], v[200:203], v[36:39]
	v_mfma_f32_16x16x32_bf16 v[32:35], v[182:185], v[200:203], v[32:35]
	v_mfma_f32_16x16x32_bf16 v[20:23], v[174:177], v[208:211], v[20:23]
	v_mfma_f32_16x16x32_bf16 v[16:19], v[182:185], v[208:211], v[16:19]
	v_mfma_f32_16x16x32_bf16 v[4:7], v[174:177], v[216:219], v[4:7]
	v_mfma_f32_16x16x32_bf16 v[0:3], v[182:185], v[216:219], v[0:3]
	v_mfma_f32_16x16x32_bf16 v[52:55], v[178:181], v[196:199], v[52:55]
	v_mfma_f32_16x16x32_bf16 v[48:51], v[188:191], v[196:199], v[48:51]
	v_mfma_f32_16x16x32_bf16 v[36:39], v[178:181], v[204:207], v[36:39]
	v_mfma_f32_16x16x32_bf16 v[32:35], v[188:191], v[204:207], v[32:35]
	v_mfma_f32_16x16x32_bf16 v[20:23], v[178:181], v[212:215], v[20:23]
	v_mfma_f32_16x16x32_bf16 v[16:19], v[188:191], v[212:215], v[16:19]
	v_mfma_f32_16x16x32_bf16 v[4:7], v[178:181], v[220:223], v[4:7]
	v_mfma_f32_16x16x32_bf16 v[0:3], v[188:191], v[220:223], v[0:3]
	s_setprio 0
	s_barrier
	s_add_i32 s51, s51, 2
	s_add_u32 s34, s34, 0x100
	s_addc_u32 s35, s35, 0
	s_cmp_gt_u32 s51, 29
	s_cbranch_scc0 .LBB0_1009
	s_branch .Lpeel_exit_4
.LBB0_1009:
	ds_read_b128 v[158:161], v153
	ds_read_b128 v[162:165], v153 offset:1024
	ds_read_b128 v[166:169], v153 offset:2048
	ds_read_b128 v[170:173], v153 offset:3072
	ds_read_b128 v[174:177], v154
	ds_read_b128 v[178:181], v154 offset:1024
	ds_read_b128 v[182:185], v154 offset:2048
	ds_read_b128 v[188:191], v154 offset:3072
	s_add_u32 s36, s30, s34
	s_addc_u32 s37, s31, s35
	s_add_u32 s38, s36, 0x100
	s_addc_u32 s39, s37, 0
	s_add_u32 s36, s48, s34
	s_addc_u32 s37, s49, s35
	s_cmpk_eq_i32 s34, 0xf00
	s_cselect_b32 s37, s21, s37
	s_cselect_b32 s36, s47, s36
	s_cselect_b32 s39, s23, s39
	s_cselect_b32 s38, s29, s38
	v_lshl_add_u64 v[148:149], v[146:147], 0, s[34:35]
	v_lshl_add_u64 v[186:187], v[148:149], 0, s[14:15]
	s_add_i32 m0, s3, 0x8000
	ds_read_b128 v[192:195], v155
	ds_read_b128 v[196:199], v155 offset:1024
	ds_read_b128 v[200:203], v155 offset:2048
	ds_read_b128 v[204:207], v155 offset:3072
	ds_read_b128 v[208:211], v155 offset:4096
	ds_read_b128 v[212:215], v155 offset:5120
	ds_read_b128 v[216:219], v155 offset:6144
	ds_read_b128 v[220:223], v155 offset:7168
	global_load_lds_dwordx4 v[186:187], off
	v_lshl_add_u64 v[186:187], v[144:145], 0, s[34:35]
	v_lshl_add_u64 v[224:225], v[186:187], 0, s[14:15]
	s_add_i32 m0, s3, 0xa000
	v_lshl_add_u64 v[148:149], v[148:149], 0, s[16:17]
	global_load_lds_dwordx4 v[224:225], off
	s_add_i32 m0, s3, 0xc000
	s_nop 0
	global_load_lds_dwordx4 v[148:149], off
	v_lshl_add_u64 v[148:149], v[186:187], 0, s[16:17]
	s_add_i32 m0, s3, 0xe000
	s_nop 0
	global_load_lds_dwordx4 v[148:149], off
	s_waitcnt vmcnt(8) lgkmcnt(0)
	s_barrier
; #define PG8_STAGE(bufoff, gbase, voff) do { _Pragma("unroll") for (int _i = 0; _i < 2; ++_i) \
;         __builtin_amdgcn_global_load_lds((const unsigned*)((const char*)(gbase) + (voff)[_i]), (LAS unsigned*)(lds + (bufoff) + ldsw + _i * 8192), 16, 0, 0); } while (0)
; #define PG8_LDA(dst, b, h) do { _Pragma("unroll") for (int m = 0; m < 4; ++m) _Pragma("unroll") for (int k = 0; k < 2; ++k) dst[m][k] = *(const LAS bf16x8*)(lds + PG8_SA(b, h) + aoff + m * 2048 + k * 1024); } while (0)
; #define PG8_MMA(ai, bj, At, Bt) do { __builtin_amdgcn_s_setprio(3); _Pragma("unroll") for (int m = 0; m < 4; ++m) _Pragma("unroll") for (int n = 0; n < 2; ++n) _Pragma("unroll") for (int k = 0; k < 2; ++k) \
;         acc[ai][bj][m][n] = __builtin_amdgcn_mfma_f32_16x16x32_bf16(Bt[n][k], At[m][k], acc[ai][bj][m][n], 0, 0, 0); __builtin_amdgcn_s_setprio(0); } while (0)
; #define PG8_WAIT_V(n) asm volatile("s_waitcnt vmcnt(" #n ")" ::: "memory")
; #define PG8_WAIT_L(n) asm volatile("s_waitcnt lgkmcnt(" #n ")" ::: "memory")
; #define PG8_BAR __builtin_amdgcn_s_barrier()
; #define PG8_SCHED __builtin_amdgcn_sched_barrier(0)
; template <class Epi, class Sched>
; __device__ __forceinline__ void gemm_phase(LAS unsigned char* lds, const Gemm g, const Sched& S, const Epi& E, int tid_in) {
;     ...
;             PG8_WAIT_V(8); PG8_WAIT_L(0); PG8_BAR; PG8_MMA(0, 0, At, B0); PG8_MMA(0, 1, At, B1); PG8_BAR; PG8_SCHED;
;             PG8_LDA(At, 0, 1); PG8_STAGE(PG8_SB(0, 0), b2, voffB); PG8_STAGE(PG8_SB(0, 1), b2 + hstep, voffB);
;             PG8_WAIT_V(6); PG8_WAIT_L(0); PG8_BAR; PG8_MMA(1, 0, At, B0); PG8_MMA(1, 1, At, B1); PG8_BAR; PG8_SCHED;
	s_setprio 3
	v_mfma_f32_16x16x32_bf16 v[124:127], v[158:161], v[192:195], v[124:127]
	v_mfma_f32_16x16x32_bf16 v[120:123], v[166:169], v[192:195], v[120:123]
	v_mfma_f32_16x16x32_bf16 v[108:111], v[158:161], v[200:203], v[108:111]
	v_mfma_f32_16x16x32_bf16 v[104:107], v[166:169], v[200:203], v[104:107]
	v_mfma_f32_16x16x32_bf16 v[92:95], v[158:161], v[208:211], v[92:95]
	v_mfma_f32_16x16x32_bf16 v[88:91], v[166:169], v[208:211], v[88:91]
	v_mfma_f32_16x16x32_bf16 v[76:79], v[158:161], v[216:219], v[76:79]
	v_mfma_f32_16x16x32_bf16 v[72:75], v[166:169], v[216:219], v[72:75]
	v_mfma_f32_16x16x32_bf16 v[124:127], v[162:165], v[196:199], v[124:127]
	v_mfma_f32_16x16x32_bf16 v[120:123], v[170:173], v[196:199], v[120:123]
	v_mfma_f32_16x16x32_bf16 v[108:111], v[162:165], v[204:207], v[108:111]
	v_mfma_f32_16x16x32_bf16 v[104:107], v[170:173], v[204:207], v[104:107]
	v_mfma_f32_16x16x32_bf16 v[92:95], v[162:165], v[212:215], v[92:95]
	v_mfma_f32_16x16x32_bf16 v[88:91], v[170:173], v[212:215], v[88:91]
	v_mfma_f32_16x16x32_bf16 v[76:79], v[162:165], v[220:223], v[76:79]
	v_mfma_f32_16x16x32_bf16 v[72:75], v[170:173], v[220:223], v[72:75]
	s_setprio 0
	s_setprio 3
	v_mfma_f32_16x16x32_bf16 v[116:119], v[174:177], v[192:195], v[116:119]
	v_mfma_f32_16x16x32_bf16 v[112:115], v[182:185], v[192:195], v[112:115]
	v_mfma_f32_16x16x32_bf16 v[100:103], v[174:177], v[200:203], v[100:103]
	v_mfma_f32_16x16x32_bf16 v[96:99], v[182:185], v[200:203], v[96:99]
	v_mfma_f32_16x16x32_bf16 v[84:87], v[174:177], v[208:211], v[84:87]
	v_mfma_f32_16x16x32_bf16 v[80:83], v[182:185], v[208:211], v[80:83]
	v_mfma_f32_16x16x32_bf16 v[68:71], v[174:177], v[216:219], v[68:71]
	v_mfma_f32_16x16x32_bf16 v[64:67], v[182:185], v[216:219], v[64:67]
	v_mfma_f32_16x16x32_bf16 v[116:119], v[178:181], v[196:199], v[116:119]
	v_mfma_f32_16x16x32_bf16 v[112:115], v[188:191], v[196:199], v[112:115]
	v_mfma_f32_16x16x32_bf16 v[100:103], v[178:181], v[204:207], v[100:103]
	v_mfma_f32_16x16x32_bf16 v[96:99], v[188:191], v[204:207], v[96:99]
	v_mfma_f32_16x16x32_bf16 v[84:87], v[178:181], v[212:215], v[84:87]
	v_mfma_f32_16x16x32_bf16 v[80:83], v[188:191], v[212:215], v[80:83]
	v_mfma_f32_16x16x32_bf16 v[68:71], v[178:181], v[220:223], v[68:71]
	v_mfma_f32_16x16x32_bf16 v[64:67], v[188:191], v[220:223], v[64:67]
	s_setprio 0
	s_barrier
	s_add_i32 s62, s44, s2
	v_lshl_add_u64 v[148:149], s[36:37], 0, v[130:131]
	s_mov_b32 m0, s62
	ds_read_b128 v[192:195], v155 offset:16384
	ds_read_b128 v[196:199], v155 offset:17408
	ds_read_b128 v[200:203], v155 offset:18432
	ds_read_b128 v[204:207], v155 offset:19456
	ds_read_b128 v[208:211], v155 offset:20480
	ds_read_b128 v[212:215], v155 offset:21504
	ds_read_b128 v[216:219], v155 offset:22528
	ds_read_b128 v[220:223], v155 offset:23552
	global_load_lds_dwordx4 v[148:149], off
	s_add_i32 m0, s62, 0x2000
	s_add_u32 s62, s36, 0x80000
	v_lshl_add_u64 v[186:187], s[36:37], 0, v[134:135]
	s_addc_u32 s63, s37, 0
	s_add_i32 s64, s45, s2
	global_load_lds_dwordx4 v[186:187], off
	v_lshl_add_u64 v[224:225], s[62:63], 0, v[130:131]
	s_mov_b32 m0, s64
	s_nop 0
	global_load_lds_dwordx4 v[224:225], off
	v_lshl_add_u64 v[224:225], s[62:63], 0, v[134:135]
	s_add_i32 m0, s64, 0x2000
	s_nop 0
	global_load_lds_dwordx4 v[224:225], off
	s_waitcnt vmcnt(6) lgkmcnt(0)
	s_barrier
	s_setprio 3
	v_mfma_f32_16x16x32_bf16 v[60:63], v[158:161], v[192:195], v[60:63]
	v_mfma_f32_16x16x32_bf16 v[56:59], v[166:169], v[192:195], v[56:59]
	v_mfma_f32_16x16x32_bf16 v[44:47], v[158:161], v[200:203], v[44:47]
	v_mfma_f32_16x16x32_bf16 v[40:43], v[166:169], v[200:203], v[40:43]
	v_mfma_f32_16x16x32_bf16 v[28:31], v[158:161], v[208:211], v[28:31]
	v_mfma_f32_16x16x32_bf16 v[24:27], v[166:169], v[208:211], v[24:27]
	v_mfma_f32_16x16x32_bf16 v[12:15], v[158:161], v[216:219], v[12:15]
	v_mfma_f32_16x16x32_bf16 v[8:11], v[166:169], v[216:219], v[8:11]
	v_mfma_f32_16x16x32_bf16 v[60:63], v[162:165], v[196:199], v[60:63]
	v_mfma_f32_16x16x32_bf16 v[56:59], v[170:173], v[196:199], v[56:59]
	v_mfma_f32_16x16x32_bf16 v[44:47], v[162:165], v[204:207], v[44:47]
	v_mfma_f32_16x16x32_bf16 v[40:43], v[170:173], v[204:207], v[40:43]
	v_mfma_f32_16x16x32_bf16 v[28:31], v[162:165], v[212:215], v[28:31]
	v_mfma_f32_16x16x32_bf16 v[24:27], v[170:173], v[212:215], v[24:27]
	v_mfma_f32_16x16x32_bf16 v[12:15], v[162:165], v[220:223], v[12:15]
	v_mfma_f32_16x16x32_bf16 v[8:11], v[170:173], v[220:223], v[8:11]
	s_setprio 0
	s_setprio 3
	v_mfma_f32_16x16x32_bf16 v[52:55], v[174:177], v[192:195], v[52:55]
	v_mfma_f32_16x16x32_bf16 v[48:51], v[182:185], v[192:195], v[48:51]
	v_mfma_f32_16x16x32_bf16 v[36:39], v[174:177], v[200:203], v[36:39]
	v_mfma_f32_16x16x32_bf16 v[32:35], v[182:185], v[200:203], v[32:35]
	v_mfma_f32_16x16x32_bf16 v[20:23], v[174:177], v[208:211], v[20:23]
	v_mfma_f32_16x16x32_bf16 v[16:19], v[182:185], v[208:211], v[16:19]
	v_mfma_f32_16x16x32_bf16 v[4:7], v[174:177], v[216:219], v[4:7]
	v_mfma_f32_16x16x32_bf16 v[0:3], v[182:185], v[216:219], v[0:3]
	v_mfma_f32_16x16x32_bf16 v[52:55], v[178:181], v[196:199], v[52:55]
	v_mfma_f32_16x16x32_bf16 v[48:51], v[188:191], v[196:199], v[48:51]
	v_mfma_f32_16x16x32_bf16 v[36:39], v[178:181], v[204:207], v[36:39]
	v_mfma_f32_16x16x32_bf16 v[32:35], v[188:191], v[204:207], v[32:35]
	v_mfma_f32_16x16x32_bf16 v[20:23], v[178:181], v[212:215], v[20:23]
	v_mfma_f32_16x16x32_bf16 v[16:19], v[188:191], v[212:215], v[16:19]
	v_mfma_f32_16x16x32_bf16 v[4:7], v[178:181], v[220:223], v[4:7]
	v_mfma_f32_16x16x32_bf16 v[0:3], v[188:191], v[220:223], v[0:3]
	s_setprio 0
	s_barrier
; #define PG8_STAGE(bufoff, gbase, voff) do { _Pragma("unroll") for (int _i = 0; _i < 2; ++_i) \
;         __builtin_amdgcn_global_load_lds((const unsigned*)((const char*)(gbase) + (voff)[_i]), (LAS unsigned*)(lds + (bufoff) + ldsw + _i * 8192), 16, 0, 0); } while (0)
; #define PG8_LDA(dst, b, h) do { _Pragma("unroll") for (int m = 0; m < 4; ++m) _Pragma("unroll") for (int k = 0; k < 2; ++k) dst[m][k] = *(const LAS bf16x8*)(lds + PG8_SA(b, h) + aoff + m * 2048 + k * 1024); } while (0)
; #define PG8_LDB(dst, b, h) do { _Pragma("unroll") for (int n = 0; n < 2; ++n) _Pragma("unroll") for (int k = 0; k < 2; ++k) dst[n][k] = *(const LAS bf16x8*)(lds + PG8_SB(b, h) + boff + n * 2048 + k * 1024); } while (0)
; #define PG8_MMA(ai, bj, At, Bt) do { __builtin_amdgcn_s_setprio(3); _Pragma("unroll") for (int m = 0; m < 4; ++m) _Pragma("unroll") for (int n = 0; n < 2; ++n) _Pragma("unroll") for (int k = 0; k < 2; ++k) \
;         acc[ai][bj][m][n] = __builtin_amdgcn_mfma_f32_16x16x32_bf16(Bt[n][k], At[m][k], acc[ai][bj][m][n], 0, 0, 0); __builtin_amdgcn_s_setprio(0); } while (0)
; #define PG8_WAIT_V(n) asm volatile("s_waitcnt vmcnt(" #n ")" ::: "memory")
; #define PG8_WAIT_L(n) asm volatile("s_waitcnt lgkmcnt(" #n ")" ::: "memory")
; #define PG8_BAR __builtin_amdgcn_s_barrier()
; #define PG8_SCHED __builtin_amdgcn_sched_barrier(0)
; template <class Epi, class Sched>
; __device__ __forceinline__ void gemm_phase(LAS unsigned char* lds, const Gemm g, const Sched& S, const Epi& E, int tid_in) {
;     ...
;             PG8_LDB(B0, 1, 0); PG8_LDB(B1, 1, 1); PG8_SCHED; PG8_LDA(At, 1, 0); PG8_STAGE(PG8_SA(0, 0), a2, voffA); PG8_STAGE(PG8_SA(0, 1), a2 + hstep, voffA);
;             PG8_WAIT_V(8); PG8_WAIT_L(0); PG8_BAR; PG8_MMA(0, 0, At, B0); PG8_MMA(0, 1, At, B1); PG8_BAR; PG8_SCHED;
;             PG8_LDA(At, 1, 1); PG8_STAGE(PG8_SB(1, 0), b3, voffB); PG8_STAGE(PG8_SB(1, 1), b3 + hstep, voffB);
;             PG8_WAIT_V(6); PG8_WAIT_L(0); PG8_BAR; PG8_MMA(1, 0, At, B0); PG8_MMA(1, 1, At, B1); PG8_BAR; PG8_SCHED;
;         }
	s_add_i32 s62, 0, 0x18000
	v_add_u32_e32 v157, s62, v151
	s_add_i32 s63, 0, 0x1c000
	ds_read_b128 v[158:161], v157
	ds_read_b128 v[162:165], v157 offset:1024
	ds_read_b128 v[166:169], v157 offset:2048
	ds_read_b128 v[170:173], v157 offset:3072
	v_add_u32_e32 v157, s63, v151
	ds_read_b128 v[174:177], v157
	ds_read_b128 v[178:181], v157 offset:1024
	ds_read_b128 v[182:185], v157 offset:2048
	ds_read_b128 v[188:191], v157 offset:3072
	s_mov_b32 m0, s3
	v_lshl_add_u64 v[224:225], s[38:39], 0, v[128:129]
	ds_read_b128 v[192:195], v155 offset:32768
	ds_read_b128 v[196:199], v155 offset:33792
	ds_read_b128 v[200:203], v155 offset:34816
	ds_read_b128 v[204:207], v155 offset:35840
	ds_read_b128 v[208:211], v155 offset:36864
	ds_read_b128 v[212:215], v155 offset:37888
	ds_read_b128 v[216:219], v155 offset:38912
	ds_read_b128 v[220:223], v155 offset:39936
	global_load_lds_dwordx4 v[224:225], off
	v_lshl_add_u64 v[224:225], s[38:39], 0, v[132:133]
	s_add_u32 s38, s38, 0x80000
	s_mov_b32 m0, s40
	s_addc_u32 s39, s39, 0
	global_load_lds_dwordx4 v[224:225], off
	v_lshl_add_u64 v[224:225], s[38:39], 0, v[128:129]
	s_mov_b32 m0, s41
	s_nop 0
	global_load_lds_dwordx4 v[224:225], off
	v_lshl_add_u64 v[224:225], s[38:39], 0, v[132:133]
	s_mov_b32 m0, s42
	s_nop 0
	global_load_lds_dwordx4 v[224:225], off
	s_waitcnt vmcnt(8) lgkmcnt(0)
	s_barrier
	s_setprio 3
	v_mfma_f32_16x16x32_bf16 v[124:127], v[158:161], v[192:195], v[124:127]
	v_mfma_f32_16x16x32_bf16 v[120:123], v[166:169], v[192:195], v[120:123]
	v_mfma_f32_16x16x32_bf16 v[108:111], v[158:161], v[200:203], v[108:111]
	v_mfma_f32_16x16x32_bf16 v[104:107], v[166:169], v[200:203], v[104:107]
	v_mfma_f32_16x16x32_bf16 v[92:95], v[158:161], v[208:211], v[92:95]
	v_mfma_f32_16x16x32_bf16 v[88:91], v[166:169], v[208:211], v[88:91]
	v_mfma_f32_16x16x32_bf16 v[76:79], v[158:161], v[216:219], v[76:79]
	v_mfma_f32_16x16x32_bf16 v[72:75], v[166:169], v[216:219], v[72:75]
	v_mfma_f32_16x16x32_bf16 v[124:127], v[162:165], v[196:199], v[124:127]
	v_mfma_f32_16x16x32_bf16 v[120:123], v[170:173], v[196:199], v[120:123]
	v_mfma_f32_16x16x32_bf16 v[108:111], v[162:165], v[204:207], v[108:111]
	v_mfma_f32_16x16x32_bf16 v[104:107], v[170:173], v[204:207], v[104:107]
	v_mfma_f32_16x16x32_bf16 v[92:95], v[162:165], v[212:215], v[92:95]
	v_mfma_f32_16x16x32_bf16 v[88:91], v[170:173], v[212:215], v[88:91]
	v_mfma_f32_16x16x32_bf16 v[76:79], v[162:165], v[220:223], v[76:79]
	v_mfma_f32_16x16x32_bf16 v[72:75], v[170:173], v[220:223], v[72:75]
	s_setprio 0
	s_setprio 3
	v_mfma_f32_16x16x32_bf16 v[116:119], v[174:177], v[192:195], v[116:119]
	v_mfma_f32_16x16x32_bf16 v[112:115], v[182:185], v[192:195], v[112:115]
	v_mfma_f32_16x16x32_bf16 v[100:103], v[174:177], v[200:203], v[100:103]
	v_mfma_f32_16x16x32_bf16 v[96:99], v[182:185], v[200:203], v[96:99]
	v_mfma_f32_16x16x32_bf16 v[84:87], v[174:177], v[208:211], v[84:87]
	v_mfma_f32_16x16x32_bf16 v[80:83], v[182:185], v[208:211], v[80:83]
	v_mfma_f32_16x16x32_bf16 v[68:71], v[174:177], v[216:219], v[68:71]
	v_mfma_f32_16x16x32_bf16 v[64:67], v[182:185], v[216:219], v[64:67]
	v_mfma_f32_16x16x32_bf16 v[116:119], v[178:181], v[196:199], v[116:119]
	v_mfma_f32_16x16x32_bf16 v[112:115], v[188:191], v[196:199], v[112:115]
	v_mfma_f32_16x16x32_bf16 v[100:103], v[178:181], v[204:207], v[100:103]
	v_mfma_f32_16x16x32_bf16 v[96:99], v[188:191], v[204:207], v[96:99]
	v_mfma_f32_16x16x32_bf16 v[84:87], v[178:181], v[212:215], v[84:87]
	v_mfma_f32_16x16x32_bf16 v[80:83], v[188:191], v[212:215], v[80:83]
	v_mfma_f32_16x16x32_bf16 v[68:71], v[178:181], v[220:223], v[68:71]
	v_mfma_f32_16x16x32_bf16 v[64:67], v[188:191], v[220:223], v[64:67]
	s_setprio 0
	s_barrier
	s_add_i32 s38, s62, s2
	v_lshl_add_u64 v[148:149], v[148:149], 0, s[14:15]
	s_mov_b32 m0, s38
	ds_read_b128 v[192:195], v155 offset:49152
	ds_read_b128 v[196:199], v155 offset:50176
	ds_read_b128 v[200:203], v155 offset:51200
	ds_read_b128 v[204:207], v155 offset:52224
	ds_read_b128 v[208:211], v155 offset:53248
	ds_read_b128 v[212:215], v155 offset:54272
	ds_read_b128 v[216:219], v155 offset:55296
	ds_read_b128 v[220:223], v155 offset:56320
	global_load_lds_dwordx4 v[148:149], off
	s_add_i32 m0, s38, 0x2000
	s_add_u32 s36, s36, 0x80080
	v_lshl_add_u64 v[148:149], v[186:187], 0, s[14:15]
	s_addc_u32 s37, s37, 0
	s_add_i32 s38, s63, s2
	global_load_lds_dwordx4 v[148:149], off
	v_lshl_add_u64 v[148:149], s[36:37], 0, v[130:131]
	s_mov_b32 m0, s38
	s_nop 0
	global_load_lds_dwordx4 v[148:149], off
	v_lshl_add_u64 v[148:149], s[36:37], 0, v[134:135]
	s_add_i32 m0, s38, 0x2000
	s_nop 0
	global_load_lds_dwordx4 v[148:149], off
	s_waitcnt vmcnt(6) lgkmcnt(0)
	s_barrier
	s_setprio 3
	v_mfma_f32_16x16x32_bf16 v[60:63], v[158:161], v[192:195], v[60:63]
	v_mfma_f32_16x16x32_bf16 v[56:59], v[166:169], v[192:195], v[56:59]
	v_mfma_f32_16x16x32_bf16 v[44:47], v[158:161], v[200:203], v[44:47]
	v_mfma_f32_16x16x32_bf16 v[40:43], v[166:169], v[200:203], v[40:43]
	v_mfma_f32_16x16x32_bf16 v[28:31], v[158:161], v[208:211], v[28:31]
	v_mfma_f32_16x16x32_bf16 v[24:27], v[166:169], v[208:211], v[24:27]
	v_mfma_f32_16x16x32_bf16 v[12:15], v[158:161], v[216:219], v[12:15]
	v_mfma_f32_16x16x32_bf16 v[8:11], v[166:169], v[216:219], v[8:11]
	v_mfma_f32_16x16x32_bf16 v[60:63], v[162:165], v[196:199], v[60:63]
	v_mfma_f32_16x16x32_bf16 v[56:59], v[170:173], v[196:199], v[56:59]
	v_mfma_f32_16x16x32_bf16 v[44:47], v[162:165], v[204:207], v[44:47]
	v_mfma_f32_16x16x32_bf16 v[40:43], v[170:173], v[204:207], v[40:43]
	v_mfma_f32_16x16x32_bf16 v[28:31], v[162:165], v[212:215], v[28:31]
	v_mfma_f32_16x16x32_bf16 v[24:27], v[170:173], v[212:215], v[24:27]
	v_mfma_f32_16x16x32_bf16 v[12:15], v[162:165], v[220:223], v[12:15]
	v_mfma_f32_16x16x32_bf16 v[8:11], v[170:173], v[220:223], v[8:11]
	s_setprio 0
	s_setprio 3
	v_mfma_f32_16x16x32_bf16 v[52:55], v[174:177], v[192:195], v[52:55]
	v_mfma_f32_16x16x32_bf16 v[48:51], v[182:185], v[192:195], v[48:51]
	v_mfma_f32_16x16x32_bf16 v[36:39], v[174:177], v[200:203], v[36:39]
	v_mfma_f32_16x16x32_bf16 v[32:35], v[182:185], v[200:203], v[32:35]
	v_mfma_f32_16x16x32_bf16 v[20:23], v[174:177], v[208:211], v[20:23]
	v_mfma_f32_16x16x32_bf16 v[16:19], v[182:185], v[208:211], v[16:19]
	v_mfma_f32_16x16x32_bf16 v[4:7], v[174:177], v[216:219], v[4:7]
	v_mfma_f32_16x16x32_bf16 v[0:3], v[182:185], v[216:219], v[0:3]
	v_mfma_f32_16x16x32_bf16 v[52:55], v[178:181], v[196:199], v[52:55]
	v_mfma_f32_16x16x32_bf16 v[48:51], v[188:191], v[196:199], v[48:51]
	v_mfma_f32_16x16x32_bf16 v[36:39], v[178:181], v[204:207], v[36:39]
	v_mfma_f32_16x16x32_bf16 v[32:35], v[188:191], v[204:207], v[32:35]
	v_mfma_f32_16x16x32_bf16 v[20:23], v[178:181], v[212:215], v[20:23]
	v_mfma_f32_16x16x32_bf16 v[16:19], v[188:191], v[212:215], v[16:19]
	v_mfma_f32_16x16x32_bf16 v[4:7], v[178:181], v[220:223], v[4:7]
	v_mfma_f32_16x16x32_bf16 v[0:3], v[188:191], v[220:223], v[0:3]
	s_setprio 0
	s_barrier
	s_add_i32 s51, s51, 2
	s_add_u32 s34, s34, 0x100
	s_addc_u32 s35, s35, 0
	s_cmp_gt_u32 s51, 29
	s_cbranch_scc0 .LBB0_1009
